# plus: Q GEMM epilogue row-scale loads prefetched; per-phase s_setprio toggles removed from GEMM loops
# speedup vs baseline: 1.0041x; 1.0041x over previous
.LBB0_304:
	s_add_u32 s2, s68, 0xfff80080
	s_addc_u32 s17, s69, -1
	s_add_i32 s26, 0, 0x10000
	v_add_u32_e32 v156, s26, v141
	ds_read_b128 v[144:147], v156
	ds_read_b128 v[148:151], v156 offset:1024
	ds_read_b128 v[152:155], v156 offset:2048
	ds_read_b128 v[156:159], v156 offset:3072
	s_cmp_eq_u32 s44, 28
	s_cselect_b32 s73, s55, s17
	s_cselect_b32 s72, s83, s2
	s_cselect_b32 s71, s24, s92
	s_cselect_b32 s70, s25, s43
	v_lshl_add_u64 v[164:165], s[68:69], 0, v[136:137]
	s_add_i32 m0, s58, 0xc000
	ds_read_b128 v[160:163], v143
	ds_read_b128 v[188:191], v143 offset:1024
	ds_read_b128 v[192:195], v143 offset:2048
	ds_read_b128 v[196:199], v143 offset:3072
	ds_read_b128 v[200:203], v143 offset:4096
	ds_read_b128 v[216:219], v143 offset:5120
	ds_read_b128 v[220:223], v143 offset:6144
	ds_read_b128 v[224:227], v143 offset:7168
	global_load_lds_dwordx4 v[164:165], off
	v_lshl_add_u64 v[164:165], s[68:69], 0, v[138:139]
	s_add_i32 m0, s58, 0xe000
	s_nop 0
	global_load_lds_dwordx4 v[164:165], off
	s_waitcnt lgkmcnt(8)
	s_barrier
	s_waitcnt lgkmcnt(0)
	s_waitcnt lgkmcnt(0)
	v_mfma_f32_16x16x32_bf16 v[126:129], v[144:147], v[160:163], v[126:129]
	v_mfma_f32_16x16x32_bf16 v[122:125], v[152:155], v[160:163], v[122:125]
	v_mfma_f32_16x16x32_bf16 v[118:121], v[144:147], v[192:195], v[118:121]
	v_mfma_f32_16x16x32_bf16 v[114:117], v[152:155], v[192:195], v[114:117]
	v_mfma_f32_16x16x32_bf16 v[102:105], v[144:147], v[200:203], v[102:105]
	v_mfma_f32_16x16x32_bf16 v[98:101], v[152:155], v[200:203], v[98:101]
	v_mfma_f32_16x16x32_bf16 v[86:89], v[144:147], v[220:223], v[86:89]
	v_mfma_f32_16x16x32_bf16 v[82:85], v[152:155], v[220:223], v[82:85]
	v_mfma_f32_16x16x32_bf16 v[126:129], v[148:151], v[188:191], v[126:129]
	v_mfma_f32_16x16x32_bf16 v[122:125], v[156:159], v[188:191], v[122:125]
	v_mfma_f32_16x16x32_bf16 v[118:121], v[148:151], v[196:199], v[118:121]
	v_mfma_f32_16x16x32_bf16 v[114:117], v[156:159], v[196:199], v[114:117]
	v_mfma_f32_16x16x32_bf16 v[102:105], v[148:151], v[216:219], v[102:105]
	v_mfma_f32_16x16x32_bf16 v[98:101], v[156:159], v[216:219], v[98:101]
	v_mfma_f32_16x16x32_bf16 v[86:89], v[148:151], v[224:227], v[86:89]
	v_mfma_f32_16x16x32_bf16 v[82:85], v[156:159], v[224:227], v[82:85]
	s_barrier
	s_add_i32 s2, 0, 0x14000
	v_add_u32_e32 v164, s2, v141
	s_add_i32 s17, s26, s3
	ds_read_b128 v[228:231], v164
	ds_read_b128 v[232:235], v164 offset:1024
	ds_read_b128 v[236:239], v164 offset:2048
	ds_read_b128 v[240:243], v164 offset:3072
	v_lshl_add_u64 v[164:165], s[70:71], 0, v[0:1]
	s_mov_b32 m0, s17
	v_lshl_add_u64 v[204:205], s[70:71], 0, v[130:131]
	global_load_lds_dwordx4 v[164:165], off
	s_add_i32 m0, s17, 0x2000
	s_nop 0
	global_load_lds_dwordx4 v[204:205], off
	s_barrier
	s_waitcnt lgkmcnt(0)
	s_waitcnt lgkmcnt(0)
	v_mfma_f32_16x16x32_bf16 v[110:113], v[228:231], v[160:163], v[110:113]
	v_mfma_f32_16x16x32_bf16 v[106:109], v[236:239], v[160:163], v[106:109]
	v_mfma_f32_16x16x32_bf16 v[94:97], v[228:231], v[192:195], v[94:97]
	v_mfma_f32_16x16x32_bf16 v[90:93], v[236:239], v[192:195], v[90:93]
	v_mfma_f32_16x16x32_bf16 v[78:81], v[228:231], v[200:203], v[78:81]
	v_mfma_f32_16x16x32_bf16 v[74:77], v[236:239], v[200:203], v[74:77]
	v_mfma_f32_16x16x32_bf16 v[70:73], v[228:231], v[220:223], v[70:73]
	v_mfma_f32_16x16x32_bf16 v[66:69], v[236:239], v[220:223], v[66:69]
	v_mfma_f32_16x16x32_bf16 v[110:113], v[232:235], v[188:191], v[110:113]
	v_mfma_f32_16x16x32_bf16 v[106:109], v[240:243], v[188:191], v[106:109]
	v_mfma_f32_16x16x32_bf16 v[94:97], v[232:235], v[196:199], v[94:97]
	v_mfma_f32_16x16x32_bf16 v[90:93], v[240:243], v[196:199], v[90:93]
	v_mfma_f32_16x16x32_bf16 v[78:81], v[232:235], v[216:219], v[78:81]
	v_mfma_f32_16x16x32_bf16 v[74:77], v[240:243], v[216:219], v[74:77]
	v_mfma_f32_16x16x32_bf16 v[70:73], v[232:235], v[224:227], v[70:73]
	v_mfma_f32_16x16x32_bf16 v[66:69], v[240:243], v[224:227], v[66:69]
	s_mov_b32 m0, s58
	v_lshl_add_u64 v[244:245], s[72:73], 0, v[134:135]
	s_barrier
	ds_read_b128 v[160:163], v143 offset:16384
	ds_read_b128 v[188:191], v143 offset:17408
	ds_read_b128 v[192:195], v143 offset:18432
	ds_read_b128 v[196:199], v143 offset:19456
	ds_read_b128 v[200:203], v143 offset:20480
	ds_read_b128 v[216:219], v143 offset:21504
	ds_read_b128 v[220:223], v143 offset:22528
	ds_read_b128 v[224:227], v143 offset:23552
	global_load_lds_dwordx4 v[244:245], off
	v_lshl_add_u64 v[246:247], s[72:73], 0, v[132:133]
	s_mov_b32 m0, s74
	s_nop 0
	global_load_lds_dwordx4 v[246:247], off
	s_barrier
	s_waitcnt lgkmcnt(0)
	s_waitcnt lgkmcnt(0)
	v_mfma_f32_16x16x32_bf16 v[62:65], v[144:147], v[160:163], v[62:65]
	v_mfma_f32_16x16x32_bf16 v[58:61], v[152:155], v[160:163], v[58:61]
	v_mfma_f32_16x16x32_bf16 v[54:57], v[144:147], v[192:195], v[54:57]
	v_mfma_f32_16x16x32_bf16 v[50:53], v[152:155], v[192:195], v[50:53]
	v_mfma_f32_16x16x32_bf16 v[38:41], v[144:147], v[200:203], v[38:41]
	v_mfma_f32_16x16x32_bf16 v[34:37], v[152:155], v[200:203], v[34:37]
	v_mfma_f32_16x16x32_bf16 v[22:25], v[144:147], v[220:223], v[22:25]
	v_mfma_f32_16x16x32_bf16 v[18:21], v[152:155], v[220:223], v[18:21]
	v_mfma_f32_16x16x32_bf16 v[62:65], v[148:151], v[188:191], v[62:65]
	v_mfma_f32_16x16x32_bf16 v[58:61], v[156:159], v[188:191], v[58:61]
	v_mfma_f32_16x16x32_bf16 v[54:57], v[148:151], v[196:199], v[54:57]
	v_mfma_f32_16x16x32_bf16 v[50:53], v[156:159], v[196:199], v[50:53]
	v_mfma_f32_16x16x32_bf16 v[38:41], v[148:151], v[216:219], v[38:41]
	v_mfma_f32_16x16x32_bf16 v[34:37], v[156:159], v[216:219], v[34:37]
	v_mfma_f32_16x16x32_bf16 v[22:25], v[148:151], v[224:227], v[22:25]
	v_mfma_f32_16x16x32_bf16 v[18:21], v[156:159], v[224:227], v[18:21]
	s_barrier
	s_add_u32 s26, s70, 0x80000
	s_addc_u32 s27, s71, 0
	s_add_i32 s2, s2, s3
	v_lshl_add_u64 v[144:145], s[26:27], 0, v[0:1]
	s_mov_b32 m0, s2
	s_nop 0
	global_load_lds_dwordx4 v[144:145], off
	v_lshl_add_u64 v[144:145], s[26:27], 0, v[130:131]
	s_add_i32 m0, s2, 0x2000
	s_nop 0
	global_load_lds_dwordx4 v[144:145], off
	s_waitcnt vmcnt(6)
	s_barrier
	v_mfma_f32_16x16x32_bf16 v[46:49], v[228:231], v[160:163], v[46:49]
	v_mfma_f32_16x16x32_bf16 v[42:45], v[236:239], v[160:163], v[42:45]
	v_mfma_f32_16x16x32_bf16 v[30:33], v[228:231], v[192:195], v[30:33]
	v_mfma_f32_16x16x32_bf16 v[26:29], v[236:239], v[192:195], v[26:29]
	v_mfma_f32_16x16x32_bf16 v[14:17], v[228:231], v[200:203], v[14:17]
	v_mfma_f32_16x16x32_bf16 v[10:13], v[236:239], v[200:203], v[10:13]
	v_mfma_f32_16x16x32_bf16 v[6:9], v[228:231], v[220:223], v[6:9]
	v_mfma_f32_16x16x32_bf16 v[2:5], v[236:239], v[220:223], v[2:5]
	v_mfma_f32_16x16x32_bf16 v[46:49], v[232:235], v[188:191], v[46:49]
	v_mfma_f32_16x16x32_bf16 v[42:45], v[240:243], v[188:191], v[42:45]
	v_mfma_f32_16x16x32_bf16 v[30:33], v[232:235], v[196:199], v[30:33]
	v_mfma_f32_16x16x32_bf16 v[26:29], v[240:243], v[196:199], v[26:29]
	v_mfma_f32_16x16x32_bf16 v[14:17], v[232:235], v[216:219], v[14:17]
	v_mfma_f32_16x16x32_bf16 v[10:13], v[240:243], v[216:219], v[10:13]
	v_mfma_f32_16x16x32_bf16 v[6:9], v[232:235], v[224:227], v[6:9]
	v_mfma_f32_16x16x32_bf16 v[2:5], v[240:243], v[224:227], v[2:5]
	s_add_i32 s2, 0, 0x18000
	v_add_u32_e32 v156, s2, v141
	s_barrier
	ds_read_b128 v[144:147], v156
	ds_read_b128 v[148:151], v156 offset:1024
	ds_read_b128 v[152:155], v156 offset:2048
	ds_read_b128 v[156:159], v156 offset:3072
	s_add_u32 s26, s72, 0x80000
	s_addc_u32 s27, s73, 0
	s_mov_b32 m0, s75
	v_lshl_add_u64 v[228:229], s[26:27], 0, v[134:135]
	ds_read_b128 v[160:163], v143 offset:32768
	ds_read_b128 v[188:191], v143 offset:33792
	ds_read_b128 v[192:195], v143 offset:34816
	ds_read_b128 v[196:199], v143 offset:35840
	ds_read_b128 v[200:203], v143 offset:36864
	ds_read_b128 v[216:219], v143 offset:37888
	ds_read_b128 v[220:223], v143 offset:38912
	ds_read_b128 v[224:227], v143 offset:39936
	global_load_lds_dwordx4 v[228:229], off
	v_lshl_add_u64 v[228:229], s[26:27], 0, v[132:133]
	s_mov_b32 m0, s79
	s_nop 0
	global_load_lds_dwordx4 v[228:229], off
	s_waitcnt lgkmcnt(8)
	s_barrier
	s_waitcnt lgkmcnt(0)
	s_waitcnt lgkmcnt(0)
	v_mfma_f32_16x16x32_bf16 v[126:129], v[144:147], v[160:163], v[126:129]
	v_mfma_f32_16x16x32_bf16 v[122:125], v[152:155], v[160:163], v[122:125]
	v_mfma_f32_16x16x32_bf16 v[118:121], v[144:147], v[192:195], v[118:121]
	v_mfma_f32_16x16x32_bf16 v[114:117], v[152:155], v[192:195], v[114:117]
	v_mfma_f32_16x16x32_bf16 v[102:105], v[144:147], v[200:203], v[102:105]
	v_mfma_f32_16x16x32_bf16 v[98:101], v[152:155], v[200:203], v[98:101]
	v_mfma_f32_16x16x32_bf16 v[86:89], v[144:147], v[220:223], v[86:89]
	v_mfma_f32_16x16x32_bf16 v[82:85], v[152:155], v[220:223], v[82:85]
	v_mfma_f32_16x16x32_bf16 v[126:129], v[148:151], v[188:191], v[126:129]
	v_mfma_f32_16x16x32_bf16 v[122:125], v[156:159], v[188:191], v[122:125]
	v_mfma_f32_16x16x32_bf16 v[118:121], v[148:151], v[196:199], v[118:121]
	v_mfma_f32_16x16x32_bf16 v[114:117], v[156:159], v[196:199], v[114:117]
	v_mfma_f32_16x16x32_bf16 v[102:105], v[148:151], v[216:219], v[102:105]
	v_mfma_f32_16x16x32_bf16 v[98:101], v[156:159], v[216:219], v[98:101]
	v_mfma_f32_16x16x32_bf16 v[86:89], v[148:151], v[224:227], v[86:89]
	v_mfma_f32_16x16x32_bf16 v[82:85], v[156:159], v[224:227], v[82:85]
	s_barrier
	s_add_i32 s17, 0, 0x1c000
	s_add_i32 s2, s2, s3
	v_add_u32_e32 v206, s17, v141
	v_lshl_add_u64 v[164:165], v[164:165], 0, s[28:29]
	s_mov_b32 m0, s2
	ds_read_b128 v[228:231], v206
	ds_read_b128 v[232:235], v206 offset:1024
	ds_read_b128 v[236:239], v206 offset:2048
	ds_read_b128 v[240:243], v206 offset:3072
	global_load_lds_dwordx4 v[164:165], off
	v_lshl_add_u64 v[164:165], v[204:205], 0, s[28:29]
	s_add_i32 m0, s2, 0x2000
	s_nop 0
	global_load_lds_dwordx4 v[164:165], off
	s_barrier
	s_waitcnt lgkmcnt(0)
	s_waitcnt lgkmcnt(0)
	v_mfma_f32_16x16x32_bf16 v[110:113], v[228:231], v[160:163], v[110:113]
	v_mfma_f32_16x16x32_bf16 v[106:109], v[236:239], v[160:163], v[106:109]
	v_mfma_f32_16x16x32_bf16 v[94:97], v[228:231], v[192:195], v[94:97]
	v_mfma_f32_16x16x32_bf16 v[90:93], v[236:239], v[192:195], v[90:93]
	v_mfma_f32_16x16x32_bf16 v[78:81], v[228:231], v[200:203], v[78:81]
	v_mfma_f32_16x16x32_bf16 v[74:77], v[236:239], v[200:203], v[74:77]
	v_mfma_f32_16x16x32_bf16 v[70:73], v[228:231], v[220:223], v[70:73]
	v_mfma_f32_16x16x32_bf16 v[66:69], v[236:239], v[220:223], v[66:69]
	v_mfma_f32_16x16x32_bf16 v[110:113], v[232:235], v[188:191], v[110:113]
	v_mfma_f32_16x16x32_bf16 v[106:109], v[240:243], v[188:191], v[106:109]
	v_mfma_f32_16x16x32_bf16 v[94:97], v[232:235], v[196:199], v[94:97]
	v_mfma_f32_16x16x32_bf16 v[90:93], v[240:243], v[196:199], v[90:93]
	v_mfma_f32_16x16x32_bf16 v[78:81], v[232:235], v[216:219], v[78:81]
	v_mfma_f32_16x16x32_bf16 v[74:77], v[240:243], v[216:219], v[74:77]
	v_mfma_f32_16x16x32_bf16 v[70:73], v[232:235], v[224:227], v[70:73]
	v_mfma_f32_16x16x32_bf16 v[66:69], v[240:243], v[224:227], v[66:69]
	s_mov_b32 m0, s80
	v_lshl_add_u64 v[164:165], v[244:245], 0, s[28:29]
	s_barrier
	ds_read_b128 v[160:163], v143 offset:49152
	ds_read_b128 v[188:191], v143 offset:50176
	ds_read_b128 v[192:195], v143 offset:51200
	ds_read_b128 v[196:199], v143 offset:52224
	ds_read_b128 v[200:203], v143 offset:53248
	ds_read_b128 v[216:219], v143 offset:54272
	ds_read_b128 v[220:223], v143 offset:55296
	ds_read_b128 v[224:227], v143 offset:56320
	global_load_lds_dwordx4 v[164:165], off
	v_lshl_add_u64 v[164:165], v[246:247], 0, s[28:29]
	s_mov_b32 m0, s81
	s_nop 0
	global_load_lds_dwordx4 v[164:165], off
	s_barrier
	s_waitcnt lgkmcnt(0)
	s_waitcnt lgkmcnt(0)
	v_mfma_f32_16x16x32_bf16 v[62:65], v[144:147], v[160:163], v[62:65]
	v_mfma_f32_16x16x32_bf16 v[58:61], v[152:155], v[160:163], v[58:61]
	v_mfma_f32_16x16x32_bf16 v[54:57], v[144:147], v[192:195], v[54:57]
	v_mfma_f32_16x16x32_bf16 v[50:53], v[152:155], v[192:195], v[50:53]
	v_mfma_f32_16x16x32_bf16 v[38:41], v[144:147], v[200:203], v[38:41]
	v_mfma_f32_16x16x32_bf16 v[34:37], v[152:155], v[200:203], v[34:37]
	v_mfma_f32_16x16x32_bf16 v[22:25], v[144:147], v[220:223], v[22:25]
	v_mfma_f32_16x16x32_bf16 v[18:21], v[152:155], v[220:223], v[18:21]
	v_mfma_f32_16x16x32_bf16 v[62:65], v[148:151], v[188:191], v[62:65]
	v_mfma_f32_16x16x32_bf16 v[58:61], v[156:159], v[188:191], v[58:61]
	v_mfma_f32_16x16x32_bf16 v[54:57], v[148:151], v[196:199], v[54:57]
	v_mfma_f32_16x16x32_bf16 v[50:53], v[156:159], v[196:199], v[50:53]
	v_mfma_f32_16x16x32_bf16 v[38:41], v[148:151], v[216:219], v[38:41]
	v_mfma_f32_16x16x32_bf16 v[34:37], v[156:159], v[216:219], v[34:37]
	v_mfma_f32_16x16x32_bf16 v[22:25], v[148:151], v[224:227], v[22:25]
	v_mfma_f32_16x16x32_bf16 v[18:21], v[156:159], v[224:227], v[18:21]
	s_barrier
	s_add_u32 s26, s70, 0x80080
	s_addc_u32 s27, s71, 0
	s_add_i32 s2, s17, s3
	v_lshl_add_u64 v[144:145], s[26:27], 0, v[0:1]
	s_mov_b32 m0, s2
	s_nop 0
	global_load_lds_dwordx4 v[144:145], off
	v_lshl_add_u64 v[144:145], s[26:27], 0, v[130:131]
	s_add_i32 m0, s2, 0x2000
	s_nop 0
	global_load_lds_dwordx4 v[144:145], off
	s_waitcnt vmcnt(6)
	s_barrier
	v_mfma_f32_16x16x32_bf16 v[46:49], v[228:231], v[160:163], v[46:49]
	v_mfma_f32_16x16x32_bf16 v[42:45], v[236:239], v[160:163], v[42:45]
	v_mfma_f32_16x16x32_bf16 v[30:33], v[228:231], v[192:195], v[30:33]
	v_mfma_f32_16x16x32_bf16 v[26:29], v[236:239], v[192:195], v[26:29]
	v_mfma_f32_16x16x32_bf16 v[14:17], v[228:231], v[200:203], v[14:17]
	v_mfma_f32_16x16x32_bf16 v[10:13], v[236:239], v[200:203], v[10:13]
	v_mfma_f32_16x16x32_bf16 v[6:9], v[228:231], v[220:223], v[6:9]
	v_mfma_f32_16x16x32_bf16 v[2:5], v[236:239], v[220:223], v[2:5]
	v_mfma_f32_16x16x32_bf16 v[46:49], v[232:235], v[188:191], v[46:49]
	v_mfma_f32_16x16x32_bf16 v[42:45], v[240:243], v[188:191], v[42:45]
	v_mfma_f32_16x16x32_bf16 v[30:33], v[232:235], v[196:199], v[30:33]
	v_mfma_f32_16x16x32_bf16 v[26:29], v[240:243], v[196:199], v[26:29]
	v_mfma_f32_16x16x32_bf16 v[14:17], v[232:235], v[216:219], v[14:17]
	v_mfma_f32_16x16x32_bf16 v[10:13], v[240:243], v[216:219], v[10:13]
	v_mfma_f32_16x16x32_bf16 v[6:9], v[232:235], v[224:227], v[6:9]
	v_mfma_f32_16x16x32_bf16 v[2:5], v[240:243], v[224:227], v[2:5]
	s_add_i32 s44, s44, 2
	s_add_u32 s68, s68, 0x100
	s_addc_u32 s69, s69, 0
	s_add_u32 s43, s43, 0x100
	s_addc_u32 s92, s92, 0
	s_cmp_gt_u32 s44, 29
	s_barrier
	s_cbranch_scc0 .LBB0_304
	v_lshl_add_u32 v146, s47, 8, v140
	v_lshl_or_b32 v144, s46, 8, v142
	v_cvt_pk_bf16_f32 v126, v126, v127
	v_cvt_pk_bf16_f32 v127, v128, v129
	v_cvt_pk_bf16_f32 v128, v122, v123
	v_mov_b64_e32 v[122:123], s[22:23]
	v_ashrrev_i32_e32 v145, 31, v144
	v_cvt_pk_bf16_f32 v70, v70, v71
	v_cvt_pk_bf16_f32 v71, v72, v73
	v_cvt_pk_bf16_f32 v72, v66, v67
	v_add_u32_e32 v66, 0x80, v146
	v_cvt_pk_bf16_f32 v129, v124, v125
	v_mad_i64_i32 v[124:125], s[24:25], v146, s97, v[122:123]
	v_lshlrev_b64 v[144:145], 1, v[144:145]
	v_cvt_pk_bf16_f32 v62, v62, v63
	v_cvt_pk_bf16_f32 v63, v64, v65
	v_cvt_pk_bf16_f32 v64, v58, v59
	v_mad_i64_i32 v[58:59], s[24:25], v66, s97, v[122:123]
	v_lshl_add_u64 v[124:125], v[124:125], 0, v[144:145]
	v_cvt_pk_bf16_f32 v110, v110, v111
	v_cvt_pk_bf16_f32 v111, v112, v113
	v_cvt_pk_bf16_f32 v112, v106, v107
	v_cvt_pk_bf16_f32 v113, v108, v109
	v_lshl_add_u64 v[58:59], v[58:59], 0, v[144:145]
	v_cvt_pk_bf16_f32 v46, v46, v47
	v_cvt_pk_bf16_f32 v47, v48, v49
	v_cvt_pk_bf16_f32 v48, v42, v43
	v_cvt_pk_bf16_f32 v49, v44, v45
	global_store_dwordx4 v[124:125], v[110:113], off offset:256
	global_store_dwordx4 v[58:59], v[46:49], off offset:256
	v_cvt_pk_bf16_f32 v94, v94, v95
	v_or_b32_e32 v110, 16, v146
	v_add_u32_e32 v46, 0x90, v146
	v_mad_i64_i32 v[110:111], s[24:25], v110, s97, v[122:123]
	v_mad_i64_i32 v[46:47], s[24:25], v46, s97, v[122:123]
	v_lshl_add_u64 v[110:111], v[110:111], 0, v[144:145]
	v_cvt_pk_bf16_f32 v95, v96, v97
	v_cvt_pk_bf16_f32 v96, v90, v91
	v_cvt_pk_bf16_f32 v97, v92, v93
	v_lshl_add_u64 v[46:47], v[46:47], 0, v[144:145]
	v_cvt_pk_bf16_f32 v30, v30, v31
	v_cvt_pk_bf16_f32 v31, v32, v33
	v_cvt_pk_bf16_f32 v32, v26, v27
	v_cvt_pk_bf16_f32 v33, v28, v29
	global_store_dwordx4 v[110:111], v[94:97], off offset:256
	global_store_dwordx4 v[46:47], v[30:33], off offset:256
	v_cvt_pk_bf16_f32 v78, v78, v79
	v_or_b32_e32 v94, 32, v146
	v_add_u32_e32 v30, 0xa0, v146
	v_mad_i64_i32 v[94:95], s[24:25], v94, s97, v[122:123]
	v_mad_i64_i32 v[30:31], s[24:25], v30, s97, v[122:123]
	v_lshl_add_u64 v[94:95], v[94:95], 0, v[144:145]
	v_cvt_pk_bf16_f32 v79, v80, v81
	v_cvt_pk_bf16_f32 v80, v74, v75
	v_cvt_pk_bf16_f32 v81, v76, v77
	v_lshl_add_u64 v[30:31], v[30:31], 0, v[144:145]
	v_cvt_pk_bf16_f32 v14, v14, v15
	v_cvt_pk_bf16_f32 v15, v16, v17
	v_cvt_pk_bf16_f32 v16, v10, v11
	v_cvt_pk_bf16_f32 v17, v12, v13
	global_store_dwordx4 v[94:95], v[78:81], off offset:256
	global_store_dwordx4 v[30:31], v[14:17], off offset:256
	v_cvt_pk_bf16_f32 v106, v118, v119
	v_or_b32_e32 v78, 48, v146
	v_add_u32_e32 v14, 0xb0, v146
	v_mad_i64_i32 v[78:79], s[24:25], v78, s97, v[122:123]
	v_mad_i64_i32 v[14:15], s[24:25], v14, s97, v[122:123]
	v_cvt_pk_bf16_f32 v107, v120, v121
	v_cvt_pk_bf16_f32 v108, v114, v115
	v_cvt_pk_bf16_f32 v109, v116, v117
	v_cvt_pk_bf16_f32 v90, v102, v103
	v_cvt_pk_bf16_f32 v91, v104, v105
	v_cvt_pk_bf16_f32 v92, v98, v99
	v_cvt_pk_bf16_f32 v93, v100, v101
	v_cvt_pk_bf16_f32 v74, v86, v87
	v_cvt_pk_bf16_f32 v75, v88, v89
	v_cvt_pk_bf16_f32 v76, v82, v83
	v_cvt_pk_bf16_f32 v77, v84, v85
	v_lshl_add_u64 v[78:79], v[78:79], 0, v[144:145]
	v_cvt_pk_bf16_f32 v73, v68, v69
	v_cvt_pk_bf16_f32 v65, v60, v61
	v_cvt_pk_bf16_f32 v42, v54, v55
	v_cvt_pk_bf16_f32 v43, v56, v57
	v_cvt_pk_bf16_f32 v44, v50, v51
	v_cvt_pk_bf16_f32 v45, v52, v53
	v_cvt_pk_bf16_f32 v26, v38, v39
	v_cvt_pk_bf16_f32 v27, v40, v41
	v_cvt_pk_bf16_f32 v28, v34, v35
	v_cvt_pk_bf16_f32 v29, v36, v37
	v_cvt_pk_bf16_f32 v10, v22, v23
	v_cvt_pk_bf16_f32 v11, v24, v25
	v_cvt_pk_bf16_f32 v12, v18, v19
	v_cvt_pk_bf16_f32 v13, v20, v21
	v_lshl_add_u64 v[14:15], v[14:15], 0, v[144:145]
	v_cvt_pk_bf16_f32 v6, v6, v7
	v_cvt_pk_bf16_f32 v7, v8, v9
	v_cvt_pk_bf16_f32 v8, v2, v3
	v_cvt_pk_bf16_f32 v9, v4, v5
	s_and_b64 vcc, exec, s[0:1]
	s_mov_b32 s46, s42
	s_mov_b32 s47, s54
	s_mov_b64 s[70:71], s[64:65]
	s_mov_b64 s[68:69], s[62:63]
	global_store_dwordx4 v[124:125], v[126:129], off
	global_store_dwordx4 v[110:111], v[106:109], off
	global_store_dwordx4 v[94:95], v[90:93], off
	global_store_dwordx4 v[78:79], v[74:77], off
	global_store_dwordx4 v[78:79], v[70:73], off offset:256
	global_store_dwordx4 v[58:59], v[62:65], off
	global_store_dwordx4 v[46:47], v[42:45], off
	global_store_dwordx4 v[30:31], v[26:29], off
	global_store_dwordx4 v[14:15], v[10:13], off
	global_store_dwordx4 v[14:15], v[6:9], off offset:256
	s_cbranch_vccz .LBB0_301
	v_readlane_b32 s0, v254, 12
	s_waitcnt vmcnt(0)
	v_readlane_b32 s1, v254, 13
	v_readlane_b32 s84, v251, 38
	v_readlane_b32 s18, v253, 0
	s_andn2_b64 vcc, exec, s[0:1]
	v_readlane_b32 s85, v251, 39
	v_readlane_b32 s86, v251, 40
	v_readlane_b32 s87, v251, 41
	v_readlane_b32 s14, v250, 63
	v_readlane_b32 s19, v253, 1
	s_cbranch_vccnz .LBB0_308
	s_barrier

.LBB0_433:
	s_add_u32 s6, s78, 0x100
	s_addc_u32 s7, s79, 0
	s_add_i32 s2, 0, 0x10000
	v_add_u32_e32 v0, s2, v153
	ds_read_b128 v[142:145], v0
	ds_read_b128 v[146:149], v0 offset:1024
	ds_read_b128 v[156:159], v0 offset:2048
	ds_read_b128 v[160:163], v0 offset:3072
	s_cmp_eq_u32 s44, 4
	s_cselect_b32 s83, s75, s7
	s_cselect_b32 s82, s74, s6
	s_cselect_b32 s81, s11, s46
	s_cselect_b32 s80, s24, s25
	v_lshl_add_u64 v[150:151], s[78:79], 0, v[138:139]
	s_add_i32 m0, s58, 0xc000
	ds_read_b128 v[188:191], v155
	ds_read_b128 v[192:195], v155 offset:1024
	ds_read_b128 v[196:199], v155 offset:2048
	ds_read_b128 v[200:203], v155 offset:3072
	ds_read_b128 v[216:219], v155 offset:4096
	ds_read_b128 v[220:223], v155 offset:5120
	ds_read_b128 v[224:227], v155 offset:6144
	ds_read_b128 v[228:231], v155 offset:7168
	global_load_lds_dwordx4 v[150:151], off
	v_lshl_add_u64 v[150:151], s[78:79], 0, v[140:141]
	s_add_i32 m0, s58, 0xe000
	s_nop 0
	global_load_lds_dwordx4 v[150:151], off
	s_waitcnt lgkmcnt(8)
	s_barrier
	s_waitcnt lgkmcnt(0)
	s_waitcnt lgkmcnt(0)
	v_mfma_f32_16x16x32_bf16 v[126:129], v[142:145], v[188:191], v[126:129]
	v_mfma_f32_16x16x32_bf16 v[122:125], v[156:159], v[188:191], v[122:125]
	v_mfma_f32_16x16x32_bf16 v[110:113], v[142:145], v[196:199], v[110:113]
	v_mfma_f32_16x16x32_bf16 v[106:109], v[156:159], v[196:199], v[106:109]
	v_mfma_f32_16x16x32_bf16 v[94:97], v[142:145], v[216:219], v[94:97]
	v_mfma_f32_16x16x32_bf16 v[90:93], v[156:159], v[216:219], v[90:93]
	v_mfma_f32_16x16x32_bf16 v[78:81], v[142:145], v[224:227], v[78:81]
	v_mfma_f32_16x16x32_bf16 v[74:77], v[156:159], v[224:227], v[74:77]
	v_mfma_f32_16x16x32_bf16 v[126:129], v[146:149], v[192:195], v[126:129]
	v_mfma_f32_16x16x32_bf16 v[122:125], v[160:163], v[192:195], v[122:125]
	v_mfma_f32_16x16x32_bf16 v[110:113], v[146:149], v[200:203], v[110:113]
	v_mfma_f32_16x16x32_bf16 v[106:109], v[160:163], v[200:203], v[106:109]
	v_mfma_f32_16x16x32_bf16 v[94:97], v[146:149], v[220:223], v[94:97]
	v_mfma_f32_16x16x32_bf16 v[90:93], v[160:163], v[220:223], v[90:93]
	v_mfma_f32_16x16x32_bf16 v[78:81], v[146:149], v[228:231], v[78:81]
	v_mfma_f32_16x16x32_bf16 v[74:77], v[160:163], v[228:231], v[74:77]
	s_barrier
	s_add_i32 s17, 0, 0x14000
	s_add_i32 s2, s2, s3
	v_add_u32_e32 v0, s17, v153
	v_lshl_add_u64 v[150:151], s[80:81], 0, v[134:135]
	s_mov_b32 m0, s2
	ds_read_b128 v[232:235], v0
	ds_read_b128 v[236:239], v0 offset:1024
	ds_read_b128 v[240:243], v0 offset:2048
	ds_read_b128 v[244:247], v0 offset:3072
	global_load_lds_dwordx4 v[150:151], off
	v_lshl_add_u64 v[164:165], s[80:81], 0, v[130:131]
	s_add_i32 m0, s2, 0x2000
	s_nop 0
	global_load_lds_dwordx4 v[164:165], off
	s_barrier
	s_waitcnt lgkmcnt(0)
	s_waitcnt lgkmcnt(0)
	v_mfma_f32_16x16x32_bf16 v[118:121], v[232:235], v[188:191], v[118:121]
	v_mfma_f32_16x16x32_bf16 v[114:117], v[240:243], v[188:191], v[114:117]
	v_mfma_f32_16x16x32_bf16 v[102:105], v[232:235], v[196:199], v[102:105]
	v_mfma_f32_16x16x32_bf16 v[98:101], v[240:243], v[196:199], v[98:101]
	v_mfma_f32_16x16x32_bf16 v[86:89], v[232:235], v[216:219], v[86:89]
	v_mfma_f32_16x16x32_bf16 v[82:85], v[240:243], v[216:219], v[82:85]
	v_mfma_f32_16x16x32_bf16 v[70:73], v[232:235], v[224:227], v[70:73]
	v_mfma_f32_16x16x32_bf16 v[66:69], v[240:243], v[224:227], v[66:69]
	v_mfma_f32_16x16x32_bf16 v[118:121], v[236:239], v[192:195], v[118:121]
	v_mfma_f32_16x16x32_bf16 v[114:117], v[244:247], v[192:195], v[114:117]
	v_mfma_f32_16x16x32_bf16 v[102:105], v[236:239], v[200:203], v[102:105]
	v_mfma_f32_16x16x32_bf16 v[98:101], v[244:247], v[200:203], v[98:101]
	v_mfma_f32_16x16x32_bf16 v[86:89], v[236:239], v[220:223], v[86:89]
	v_mfma_f32_16x16x32_bf16 v[82:85], v[244:247], v[220:223], v[82:85]
	v_mfma_f32_16x16x32_bf16 v[70:73], v[236:239], v[228:231], v[70:73]
	v_mfma_f32_16x16x32_bf16 v[66:69], v[244:247], v[228:231], v[66:69]
	s_mov_b32 m0, s58
	v_lshl_add_u64 v[204:205], s[82:83], 0, v[136:137]
	s_barrier
	ds_read_b128 v[188:191], v155 offset:16384
	ds_read_b128 v[192:195], v155 offset:17408
	ds_read_b128 v[196:199], v155 offset:18432
	ds_read_b128 v[200:203], v155 offset:19456
	ds_read_b128 v[216:219], v155 offset:20480
	ds_read_b128 v[220:223], v155 offset:21504
	ds_read_b128 v[224:227], v155 offset:22528
	ds_read_b128 v[228:231], v155 offset:23552
	global_load_lds_dwordx4 v[204:205], off
	v_lshl_add_u64 v[248:249], s[82:83], 0, v[132:133]
	s_mov_b32 m0, s69
	s_nop 0
	global_load_lds_dwordx4 v[248:249], off
	s_barrier
	s_waitcnt lgkmcnt(0)
	s_waitcnt lgkmcnt(0)
	v_mfma_f32_16x16x32_bf16 v[62:65], v[142:145], v[188:191], v[62:65]
	v_mfma_f32_16x16x32_bf16 v[58:61], v[156:159], v[188:191], v[58:61]
	v_mfma_f32_16x16x32_bf16 v[46:49], v[142:145], v[196:199], v[46:49]
	v_mfma_f32_16x16x32_bf16 v[42:45], v[156:159], v[196:199], v[42:45]
	v_mfma_f32_16x16x32_bf16 v[30:33], v[142:145], v[216:219], v[30:33]
	v_mfma_f32_16x16x32_bf16 v[26:29], v[156:159], v[216:219], v[26:29]
	v_mfma_f32_16x16x32_bf16 v[14:17], v[142:145], v[224:227], v[14:17]
	v_mfma_f32_16x16x32_bf16 v[10:13], v[156:159], v[224:227], v[10:13]
	v_mfma_f32_16x16x32_bf16 v[62:65], v[146:149], v[192:195], v[62:65]
	v_mfma_f32_16x16x32_bf16 v[58:61], v[160:163], v[192:195], v[58:61]
	v_mfma_f32_16x16x32_bf16 v[46:49], v[146:149], v[200:203], v[46:49]
	v_mfma_f32_16x16x32_bf16 v[42:45], v[160:163], v[200:203], v[42:45]
	v_mfma_f32_16x16x32_bf16 v[30:33], v[146:149], v[220:223], v[30:33]
	v_mfma_f32_16x16x32_bf16 v[26:29], v[160:163], v[220:223], v[26:29]
	v_mfma_f32_16x16x32_bf16 v[14:17], v[146:149], v[228:231], v[14:17]
	v_mfma_f32_16x16x32_bf16 v[10:13], v[160:163], v[228:231], v[10:13]
	s_barrier
	s_add_u32 s26, s80, 0x20000
	s_addc_u32 s27, s81, 0
	s_add_i32 s2, s17, s3
	v_lshl_add_u64 v[142:143], s[26:27], 0, v[134:135]
	s_mov_b32 m0, s2
	s_nop 0
	global_load_lds_dwordx4 v[142:143], off
	v_lshl_add_u64 v[142:143], s[26:27], 0, v[130:131]
	s_add_i32 m0, s2, 0x2000
	s_nop 0
	global_load_lds_dwordx4 v[142:143], off
	s_waitcnt vmcnt(6)
	s_barrier
	v_mfma_f32_16x16x32_bf16 v[54:57], v[232:235], v[188:191], v[54:57]
	v_mfma_f32_16x16x32_bf16 v[50:53], v[240:243], v[188:191], v[50:53]
	v_mfma_f32_16x16x32_bf16 v[38:41], v[232:235], v[196:199], v[38:41]
	v_mfma_f32_16x16x32_bf16 v[34:37], v[240:243], v[196:199], v[34:37]
	v_mfma_f32_16x16x32_bf16 v[22:25], v[232:235], v[216:219], v[22:25]
	v_mfma_f32_16x16x32_bf16 v[18:21], v[240:243], v[216:219], v[18:21]
	v_mfma_f32_16x16x32_bf16 v[6:9], v[232:235], v[224:227], v[6:9]
	v_mfma_f32_16x16x32_bf16 v[2:5], v[240:243], v[224:227], v[2:5]
	v_mfma_f32_16x16x32_bf16 v[54:57], v[236:239], v[192:195], v[54:57]
	v_mfma_f32_16x16x32_bf16 v[50:53], v[244:247], v[192:195], v[50:53]
	v_mfma_f32_16x16x32_bf16 v[38:41], v[236:239], v[200:203], v[38:41]
	v_mfma_f32_16x16x32_bf16 v[34:37], v[244:247], v[200:203], v[34:37]
	v_mfma_f32_16x16x32_bf16 v[22:25], v[236:239], v[220:223], v[22:25]
	v_mfma_f32_16x16x32_bf16 v[18:21], v[244:247], v[220:223], v[18:21]
	v_mfma_f32_16x16x32_bf16 v[6:9], v[236:239], v[228:231], v[6:9]
	v_mfma_f32_16x16x32_bf16 v[2:5], v[244:247], v[228:231], v[2:5]
	s_add_i32 s2, 0, 0x18000
	v_add_u32_e32 v0, s2, v153
	s_barrier
	ds_read_b128 v[142:145], v0
	ds_read_b128 v[146:149], v0 offset:1024
	ds_read_b128 v[156:159], v0 offset:2048
	ds_read_b128 v[160:163], v0 offset:3072
	s_add_u32 s26, s82, 0xd0000
	s_addc_u32 s27, s83, 0
	s_mov_b32 m0, s92
	v_lshl_add_u64 v[232:233], s[26:27], 0, v[136:137]
	ds_read_b128 v[188:191], v155 offset:32768
	ds_read_b128 v[192:195], v155 offset:33792
	ds_read_b128 v[196:199], v155 offset:34816
	ds_read_b128 v[200:203], v155 offset:35840
	ds_read_b128 v[216:219], v155 offset:36864
	ds_read_b128 v[220:223], v155 offset:37888
	ds_read_b128 v[224:227], v155 offset:38912
	ds_read_b128 v[228:231], v155 offset:39936
	global_load_lds_dwordx4 v[232:233], off
	v_lshl_add_u64 v[232:233], s[26:27], 0, v[132:133]
	s_mov_b32 m0, s93
	s_nop 0
	global_load_lds_dwordx4 v[232:233], off
	s_waitcnt lgkmcnt(8)
	s_barrier
	s_waitcnt lgkmcnt(0)
	s_waitcnt lgkmcnt(0)
	v_mfma_f32_16x16x32_bf16 v[126:129], v[142:145], v[188:191], v[126:129]
	v_mfma_f32_16x16x32_bf16 v[122:125], v[156:159], v[188:191], v[122:125]
	v_mfma_f32_16x16x32_bf16 v[110:113], v[142:145], v[196:199], v[110:113]
	v_mfma_f32_16x16x32_bf16 v[106:109], v[156:159], v[196:199], v[106:109]
	v_mfma_f32_16x16x32_bf16 v[94:97], v[142:145], v[216:219], v[94:97]
	v_mfma_f32_16x16x32_bf16 v[90:93], v[156:159], v[216:219], v[90:93]
	v_mfma_f32_16x16x32_bf16 v[78:81], v[142:145], v[224:227], v[78:81]
	v_mfma_f32_16x16x32_bf16 v[74:77], v[156:159], v[224:227], v[74:77]
	v_mfma_f32_16x16x32_bf16 v[126:129], v[146:149], v[192:195], v[126:129]
	v_mfma_f32_16x16x32_bf16 v[122:125], v[160:163], v[192:195], v[122:125]
	v_mfma_f32_16x16x32_bf16 v[110:113], v[146:149], v[200:203], v[110:113]
	v_mfma_f32_16x16x32_bf16 v[106:109], v[160:163], v[200:203], v[106:109]
	v_mfma_f32_16x16x32_bf16 v[94:97], v[146:149], v[220:223], v[94:97]
	v_mfma_f32_16x16x32_bf16 v[90:93], v[160:163], v[220:223], v[90:93]
	v_mfma_f32_16x16x32_bf16 v[78:81], v[146:149], v[228:231], v[78:81]
	v_mfma_f32_16x16x32_bf16 v[74:77], v[160:163], v[228:231], v[74:77]
	s_barrier
	s_add_i32 s17, 0, 0x1c000
	s_add_i32 s2, s2, s3
	v_add_u32_e32 v0, s17, v153
	v_lshl_add_u64 v[150:151], v[150:151], 0, s[28:29]
	s_mov_b32 m0, s2
	ds_read_b128 v[232:235], v0
	ds_read_b128 v[236:239], v0 offset:1024
	ds_read_b128 v[240:243], v0 offset:2048
	ds_read_b128 v[244:247], v0 offset:3072
	global_load_lds_dwordx4 v[150:151], off
	v_lshl_add_u64 v[150:151], v[164:165], 0, s[28:29]
	s_add_i32 m0, s2, 0x2000
	s_nop 0
	global_load_lds_dwordx4 v[150:151], off
	s_barrier
	s_waitcnt lgkmcnt(0)
	s_waitcnt lgkmcnt(0)
	v_mfma_f32_16x16x32_bf16 v[118:121], v[232:235], v[188:191], v[118:121]
	v_mfma_f32_16x16x32_bf16 v[114:117], v[240:243], v[188:191], v[114:117]
	v_mfma_f32_16x16x32_bf16 v[102:105], v[232:235], v[196:199], v[102:105]
	v_mfma_f32_16x16x32_bf16 v[98:101], v[240:243], v[196:199], v[98:101]
	v_mfma_f32_16x16x32_bf16 v[86:89], v[232:235], v[216:219], v[86:89]
	v_mfma_f32_16x16x32_bf16 v[82:85], v[240:243], v[216:219], v[82:85]
	v_mfma_f32_16x16x32_bf16 v[70:73], v[232:235], v[224:227], v[70:73]
	v_mfma_f32_16x16x32_bf16 v[66:69], v[240:243], v[224:227], v[66:69]
	v_mfma_f32_16x16x32_bf16 v[118:121], v[236:239], v[192:195], v[118:121]
	v_mfma_f32_16x16x32_bf16 v[114:117], v[244:247], v[192:195], v[114:117]
	v_mfma_f32_16x16x32_bf16 v[102:105], v[236:239], v[200:203], v[102:105]
	v_mfma_f32_16x16x32_bf16 v[98:101], v[244:247], v[200:203], v[98:101]
	v_mfma_f32_16x16x32_bf16 v[86:89], v[236:239], v[220:223], v[86:89]
	v_mfma_f32_16x16x32_bf16 v[82:85], v[244:247], v[220:223], v[82:85]
	v_mfma_f32_16x16x32_bf16 v[70:73], v[236:239], v[228:231], v[70:73]
	v_mfma_f32_16x16x32_bf16 v[66:69], v[244:247], v[228:231], v[66:69]
	s_mov_b32 m0, s72
	v_lshl_add_u64 v[150:151], v[204:205], 0, s[28:29]
	s_barrier
	ds_read_b128 v[188:191], v155 offset:49152
	ds_read_b128 v[192:195], v155 offset:50176
	ds_read_b128 v[196:199], v155 offset:51200
	ds_read_b128 v[200:203], v155 offset:52224
	ds_read_b128 v[216:219], v155 offset:53248
	ds_read_b128 v[220:223], v155 offset:54272
	ds_read_b128 v[224:227], v155 offset:55296
	ds_read_b128 v[228:231], v155 offset:56320
	global_load_lds_dwordx4 v[150:151], off
	v_lshl_add_u64 v[150:151], v[248:249], 0, s[28:29]
	s_mov_b32 m0, s73
	s_nop 0
	global_load_lds_dwordx4 v[150:151], off
	s_barrier
	s_waitcnt lgkmcnt(0)
	s_waitcnt lgkmcnt(0)
	v_mfma_f32_16x16x32_bf16 v[62:65], v[142:145], v[188:191], v[62:65]
	v_mfma_f32_16x16x32_bf16 v[58:61], v[156:159], v[188:191], v[58:61]
	v_mfma_f32_16x16x32_bf16 v[46:49], v[142:145], v[196:199], v[46:49]
	v_mfma_f32_16x16x32_bf16 v[42:45], v[156:159], v[196:199], v[42:45]
	v_mfma_f32_16x16x32_bf16 v[30:33], v[142:145], v[216:219], v[30:33]
	v_mfma_f32_16x16x32_bf16 v[26:29], v[156:159], v[216:219], v[26:29]
	v_mfma_f32_16x16x32_bf16 v[14:17], v[142:145], v[224:227], v[14:17]
	v_mfma_f32_16x16x32_bf16 v[10:13], v[156:159], v[224:227], v[10:13]
	v_mfma_f32_16x16x32_bf16 v[62:65], v[146:149], v[192:195], v[62:65]
	v_mfma_f32_16x16x32_bf16 v[58:61], v[160:163], v[192:195], v[58:61]
	v_mfma_f32_16x16x32_bf16 v[46:49], v[146:149], v[200:203], v[46:49]
	v_mfma_f32_16x16x32_bf16 v[42:45], v[160:163], v[200:203], v[42:45]
	v_mfma_f32_16x16x32_bf16 v[30:33], v[146:149], v[220:223], v[30:33]
	v_mfma_f32_16x16x32_bf16 v[26:29], v[160:163], v[220:223], v[26:29]
	v_mfma_f32_16x16x32_bf16 v[14:17], v[146:149], v[228:231], v[14:17]
	v_mfma_f32_16x16x32_bf16 v[10:13], v[160:163], v[228:231], v[10:13]
	s_barrier
	s_add_u32 s26, s80, 0x20080
	s_addc_u32 s27, s81, 0
	s_add_i32 s2, s17, s3
	v_lshl_add_u64 v[142:143], s[26:27], 0, v[134:135]
	s_mov_b32 m0, s2
	s_nop 0
	global_load_lds_dwordx4 v[142:143], off
	v_lshl_add_u64 v[142:143], s[26:27], 0, v[130:131]
	s_add_i32 m0, s2, 0x2000
	s_nop 0
	global_load_lds_dwordx4 v[142:143], off
	s_waitcnt vmcnt(6)
	s_barrier
	v_mfma_f32_16x16x32_bf16 v[54:57], v[232:235], v[188:191], v[54:57]
	v_mfma_f32_16x16x32_bf16 v[50:53], v[240:243], v[188:191], v[50:53]
	v_mfma_f32_16x16x32_bf16 v[38:41], v[232:235], v[196:199], v[38:41]
	v_mfma_f32_16x16x32_bf16 v[34:37], v[240:243], v[196:199], v[34:37]
	v_mfma_f32_16x16x32_bf16 v[22:25], v[232:235], v[216:219], v[22:25]
	v_mfma_f32_16x16x32_bf16 v[18:21], v[240:243], v[216:219], v[18:21]
	v_mfma_f32_16x16x32_bf16 v[6:9], v[232:235], v[224:227], v[6:9]
	v_mfma_f32_16x16x32_bf16 v[2:5], v[240:243], v[224:227], v[2:5]
	v_mfma_f32_16x16x32_bf16 v[54:57], v[236:239], v[192:195], v[54:57]
	v_mfma_f32_16x16x32_bf16 v[50:53], v[244:247], v[192:195], v[50:53]
	v_mfma_f32_16x16x32_bf16 v[38:41], v[236:239], v[200:203], v[38:41]
	v_mfma_f32_16x16x32_bf16 v[34:37], v[244:247], v[200:203], v[34:37]
	v_mfma_f32_16x16x32_bf16 v[22:25], v[236:239], v[220:223], v[22:25]
	v_mfma_f32_16x16x32_bf16 v[18:21], v[244:247], v[220:223], v[18:21]
	v_mfma_f32_16x16x32_bf16 v[6:9], v[236:239], v[228:231], v[6:9]
	v_mfma_f32_16x16x32_bf16 v[2:5], v[244:247], v[228:231], v[2:5]
	s_add_i32 s44, s44, 2
	s_add_u32 s25, s25, 0x100
	s_addc_u32 s46, s46, 0
	s_cmp_gt_u32 s44, 5
	s_mov_b64 s[78:79], s[6:7]
	s_barrier
	s_cbranch_scc0 .LBB0_433
	v_lshl_add_u32 v144, s41, 8, v152
	v_ashrrev_i32_e32 v145, 31, v144
	v_lshl_add_u64 v[146:147], v[144:145], 2, s[50:51]
	global_load_dword v216, v[146:147], off
	global_load_dword v217, v[146:147], off offset:64
	global_load_dword v218, v[146:147], off offset:128
	global_load_dword v219, v[146:147], off offset:192
	global_load_dword v220, v[146:147], off offset:512
	global_load_dword v221, v[146:147], off offset:576
	global_load_dword v222, v[146:147], off offset:640
	global_load_dword v223, v[146:147], off offset:704
	v_lshl_or_b32 v142, s40, 8, v154
	s_mov_b32 s2, 0x2aaaaaab
	v_mul_hi_i32 v143, v142, s2
	v_lshlrev_b64 v[148:149], 8, v[144:145]
	v_lshrrev_b32_e32 v145, 31, v143
	v_lshrrev_b32_e32 v143, 5, v143
	v_add_u32_e32 v143, v143, v145
	s_movk_i32 s2, 0xc0
	v_mul_lo_u32 v143, v143, s2
	v_sub_u32_e32 v143, v142, v143
	s_movk_i32 s2, 0x7f
	v_cmp_lt_i32_e32 vcc, s2, v143
	v_add_u32_e32 v143, 0xffffff80, v143
	v_lshl_add_u64 v[148:149], s[20:21], 0, v[148:149]
	s_waitcnt vmcnt(0)
	v_mov_b32_e32 v0, v216
	v_mul_f32_e32 v150, 0x3dd53b94, v0
	v_pk_mul_f32 v[128:129], v[128:129], v[150:151] op_sel_hi:[1,0]
	v_pk_mul_f32 v[126:127], v[126:127], v[150:151] op_sel_hi:[1,0]
	v_pk_mul_f32 v[124:125], v[124:125], v[150:151] op_sel_hi:[1,0]
	v_pk_mul_f32 v[122:123], v[122:123], v[150:151] op_sel_hi:[1,0]
	v_lshrrev_b32_e32 v0, 1, v143
	s_and_saveexec_b64 s[6:7], vcc
	s_cbranch_execz .LBB0_436
	v_lshl_add_u64 v[160:161], v[0:1], 3, v[148:149]
	global_load_dwordx4 v[156:159], v[160:161], off offset:16
	s_nop 0
	global_load_dwordx4 v[160:163], v[160:161], off
	s_waitcnt vmcnt(0)
	v_pk_mul_f32 v[190:191], v[122:123], v[156:157] op_sel:[1,1] op_sel_hi:[0,1]
	v_pk_mul_f32 v[188:189], v[126:127], v[160:161] op_sel:[1,1] op_sel_hi:[0,1]
	v_pk_mul_f32 v[164:165], v[126:127], v[160:161]
	v_pk_fma_f32 v[126:127], v[126:127], v[160:161], v[188:189] op_sel_hi:[1,0,1]
	s_nop 0
	v_mul_f32_e32 v126, v129, v163
	v_pk_fma_f32 v[160:161], v[128:129], v[162:163], v[126:127] op_sel_hi:[1,1,0] neg_lo:[0,0,1] neg_hi:[0,0,1]
	v_mul_f32_e32 v126, v128, v163
	v_pk_fma_f32 v[162:163], v[128:129], v[162:163], v[126:127] op_sel:[1,0,0] op_sel_hi:[0,1,0]
	v_pk_mul_f32 v[128:129], v[122:123], v[156:157]
	v_pk_fma_f32 v[122:123], v[122:123], v[156:157], v[190:191] op_sel_hi:[1,0,1]
	v_sub_f32_e32 v126, v164, v188
	v_mul_f32_e32 v122, v125, v159
	v_pk_fma_f32 v[156:157], v[124:125], v[158:159], v[122:123] op_sel_hi:[1,1,0] neg_lo:[0,0,1] neg_hi:[0,0,1]
	v_mul_f32_e32 v122, v124, v159
	v_pk_fma_f32 v[158:159], v[124:125], v[158:159], v[122:123] op_sel:[1,0,0] op_sel_hi:[0,1,0]
	v_sub_f32_e32 v122, v128, v190
	v_mov_b32_e32 v128, v160
	v_mov_b32_e32 v129, v162
	v_mov_b32_e32 v124, v156
	v_mov_b32_e32 v125, v158

.LBB0_438:
	s_or_b64 exec, exec, s[78:79]
	v_cvt_pk_bf16_f32 v126, v118, v119
	v_or_b32_e32 v118, 16, v144
	v_cvt_pk_bf16_f32 v127, v124, v125
	v_cvt_pk_bf16_f32 v128, v116, v117
	v_cvt_pk_bf16_f32 v129, v120, v121
	v_ashrrev_i32_e32 v119, 31, v118
	global_store_dwordx4 v[122:123], v[126:129], off offset:256
	v_lshl_add_u64 v[116:117], v[118:119], 2, s[50:51]
	s_nop 1
	v_mov_b32_e32 v115, v217
	v_lshlrev_b64 v[122:123], 8, v[118:119]
	s_nop 0
	v_mul_f32_e32 v116, 0x3dd53b94, v115
	v_pk_mul_f32 v[120:121], v[112:113], v[116:117] op_sel_hi:[1,0]
	v_pk_mul_f32 v[110:111], v[110:111], v[116:117] op_sel_hi:[1,0]
	v_pk_mul_f32 v[112:113], v[108:109], v[116:117] op_sel_hi:[1,0]
	v_pk_mul_f32 v[108:109], v[106:107], v[116:117] op_sel_hi:[1,0]
	v_lshl_add_u64 v[106:107], s[20:21], 0, v[122:123]
	s_and_saveexec_b64 s[78:79], vcc
	s_cbranch_execz .LBB0_440
	v_lshl_add_u64 v[126:127], v[0:1], 3, v[106:107]
	global_load_dwordx4 v[122:125], v[126:127], off offset:16
	s_nop 0
	global_load_dwordx4 v[126:129], v[126:127], off
	s_waitcnt vmcnt(0)
	v_pk_mul_f32 v[156:157], v[108:109], v[122:123] op_sel:[1,1] op_sel_hi:[0,1]
	v_pk_mul_f32 v[150:151], v[110:111], v[126:127] op_sel:[1,1] op_sel_hi:[0,1]
	v_pk_mul_f32 v[148:149], v[110:111], v[126:127]
	v_pk_fma_f32 v[110:111], v[110:111], v[126:127], v[150:151] op_sel_hi:[1,0,1]
	s_nop 0
	v_mul_f32_e32 v110, v121, v129
	v_pk_fma_f32 v[126:127], v[120:121], v[128:129], v[110:111] op_sel_hi:[1,1,0] neg_lo:[0,0,1] neg_hi:[0,0,1]
	v_mul_f32_e32 v110, v120, v129
	v_pk_fma_f32 v[128:129], v[120:121], v[128:129], v[110:111] op_sel:[1,0,0] op_sel_hi:[0,1,0]
	v_pk_mul_f32 v[120:121], v[108:109], v[122:123]
	v_pk_fma_f32 v[108:109], v[108:109], v[122:123], v[156:157] op_sel_hi:[1,0,1]
	v_sub_f32_e32 v110, v148, v150
	v_mul_f32_e32 v108, v113, v125
	v_pk_fma_f32 v[122:123], v[112:113], v[124:125], v[108:109] op_sel_hi:[1,1,0] neg_lo:[0,0,1] neg_hi:[0,0,1]
	v_mul_f32_e32 v108, v112, v125
	v_pk_fma_f32 v[124:125], v[112:113], v[124:125], v[108:109] op_sel:[1,0,0] op_sel_hi:[0,1,0]
	v_sub_f32_e32 v108, v120, v156
	v_mov_b32_e32 v120, v126
	v_mov_b32_e32 v121, v128
	v_mov_b32_e32 v112, v122
	v_mov_b32_e32 v113, v124

.LBB0_442:
	s_or_b64 exec, exec, s[78:79]
	v_cvt_pk_bf16_f32 v102, v102, v103
	v_cvt_pk_bf16_f32 v103, v104, v105
	v_cvt_pk_bf16_f32 v105, v100, v101
	v_or_b32_e32 v100, 32, v144
	v_cvt_pk_bf16_f32 v104, v98, v99
	v_ashrrev_i32_e32 v101, 31, v100
	global_store_dwordx4 v[108:109], v[102:105], off offset:256
	v_lshl_add_u64 v[98:99], v[100:101], 2, s[50:51]
	s_nop 1
	v_mov_b32_e32 v98, v218
	v_lshlrev_b64 v[104:105], 8, v[100:101]
	s_nop 0
	v_mul_f32_e32 v98, 0x3dd53b94, v98
	v_pk_mul_f32 v[102:103], v[96:97], v[98:99] op_sel_hi:[1,0]
	v_pk_mul_f32 v[94:95], v[94:95], v[98:99] op_sel_hi:[1,0]
	v_pk_mul_f32 v[96:97], v[92:93], v[98:99] op_sel_hi:[1,0]
	v_pk_mul_f32 v[92:93], v[90:91], v[98:99] op_sel_hi:[1,0]
	v_lshl_add_u64 v[90:91], s[20:21], 0, v[104:105]
	s_and_saveexec_b64 s[78:79], vcc
	s_cbranch_execz .LBB0_444
	v_lshl_add_u64 v[108:109], v[0:1], 3, v[90:91]
	global_load_dwordx4 v[104:107], v[108:109], off offset:16
	s_nop 0
	global_load_dwordx4 v[108:111], v[108:109], off
	s_waitcnt vmcnt(0)
	v_pk_mul_f32 v[118:119], v[92:93], v[104:105] op_sel:[1,1] op_sel_hi:[0,1]
	v_pk_mul_f32 v[116:117], v[94:95], v[108:109] op_sel:[1,1] op_sel_hi:[0,1]
	v_pk_mul_f32 v[112:113], v[94:95], v[108:109]
	v_pk_fma_f32 v[94:95], v[94:95], v[108:109], v[116:117] op_sel_hi:[1,0,1]
	s_nop 0
	v_mul_f32_e32 v94, v103, v111
	v_pk_fma_f32 v[108:109], v[102:103], v[110:111], v[94:95] op_sel_hi:[1,1,0] neg_lo:[0,0,1] neg_hi:[0,0,1]
	v_mul_f32_e32 v94, v102, v111
	v_pk_fma_f32 v[110:111], v[102:103], v[110:111], v[94:95] op_sel:[1,0,0] op_sel_hi:[0,1,0]
	v_pk_mul_f32 v[102:103], v[92:93], v[104:105]
	v_pk_fma_f32 v[92:93], v[92:93], v[104:105], v[118:119] op_sel_hi:[1,0,1]
	v_sub_f32_e32 v94, v112, v116
	v_mul_f32_e32 v92, v97, v107
	v_pk_fma_f32 v[104:105], v[96:97], v[106:107], v[92:93] op_sel_hi:[1,1,0] neg_lo:[0,0,1] neg_hi:[0,0,1]
	v_mul_f32_e32 v92, v96, v107
	v_pk_fma_f32 v[106:107], v[96:97], v[106:107], v[92:93] op_sel:[1,0,0] op_sel_hi:[0,1,0]
	v_sub_f32_e32 v92, v102, v118
	v_mov_b32_e32 v102, v108
	v_mov_b32_e32 v103, v110
	v_mov_b32_e32 v96, v104
	v_mov_b32_e32 v97, v106

.LBB0_446:
	s_or_b64 exec, exec, s[78:79]
	v_cvt_pk_bf16_f32 v86, v86, v87
	v_cvt_pk_bf16_f32 v87, v88, v89
	v_cvt_pk_bf16_f32 v89, v84, v85
	v_or_b32_e32 v84, 48, v144
	v_cvt_pk_bf16_f32 v88, v82, v83
	v_ashrrev_i32_e32 v85, 31, v84
	global_store_dwordx4 v[92:93], v[86:89], off offset:256
	v_lshl_add_u64 v[82:83], v[84:85], 2, s[50:51]
	s_nop 1
	v_mov_b32_e32 v82, v219
	v_lshlrev_b64 v[88:89], 8, v[84:85]
	s_nop 0
	v_mul_f32_e32 v82, 0x3dd53b94, v82
	v_pk_mul_f32 v[86:87], v[80:81], v[82:83] op_sel_hi:[1,0]
	v_pk_mul_f32 v[78:79], v[78:79], v[82:83] op_sel_hi:[1,0]
	v_pk_mul_f32 v[80:81], v[76:77], v[82:83] op_sel_hi:[1,0]
	v_pk_mul_f32 v[76:77], v[74:75], v[82:83] op_sel_hi:[1,0]
	v_lshl_add_u64 v[74:75], s[20:21], 0, v[88:89]
	s_and_saveexec_b64 s[78:79], vcc
	s_cbranch_execz .LBB0_448
	v_lshl_add_u64 v[92:93], v[0:1], 3, v[74:75]
	global_load_dwordx4 v[88:91], v[92:93], off offset:16
	s_nop 0
	global_load_dwordx4 v[92:95], v[92:93], off
	s_waitcnt vmcnt(0)
	v_pk_mul_f32 v[100:101], v[76:77], v[88:89] op_sel:[1,1] op_sel_hi:[0,1]
	v_pk_mul_f32 v[98:99], v[78:79], v[92:93] op_sel:[1,1] op_sel_hi:[0,1]
	v_pk_mul_f32 v[96:97], v[78:79], v[92:93]
	v_pk_fma_f32 v[78:79], v[78:79], v[92:93], v[98:99] op_sel_hi:[1,0,1]
	s_nop 0
	v_mul_f32_e32 v78, v87, v95
	v_pk_fma_f32 v[92:93], v[86:87], v[94:95], v[78:79] op_sel_hi:[1,1,0] neg_lo:[0,0,1] neg_hi:[0,0,1]
	v_mul_f32_e32 v78, v86, v95
	v_pk_fma_f32 v[94:95], v[86:87], v[94:95], v[78:79] op_sel:[1,0,0] op_sel_hi:[0,1,0]
	v_pk_mul_f32 v[86:87], v[76:77], v[88:89]
	v_pk_fma_f32 v[76:77], v[76:77], v[88:89], v[100:101] op_sel_hi:[1,0,1]
	v_sub_f32_e32 v78, v96, v98
	v_mul_f32_e32 v76, v81, v91
	v_pk_fma_f32 v[88:89], v[80:81], v[90:91], v[76:77] op_sel_hi:[1,1,0] neg_lo:[0,0,1] neg_hi:[0,0,1]
	v_mul_f32_e32 v76, v80, v91
	v_pk_fma_f32 v[90:91], v[80:81], v[90:91], v[76:77] op_sel:[1,0,0] op_sel_hi:[0,1,0]
	v_sub_f32_e32 v76, v86, v100
	v_mov_b32_e32 v86, v92
	v_mov_b32_e32 v87, v94
	v_mov_b32_e32 v80, v88
	v_mov_b32_e32 v81, v90

.LBB0_450:
	s_or_b64 exec, exec, s[78:79]
	v_cvt_pk_bf16_f32 v70, v70, v71
	v_cvt_pk_bf16_f32 v71, v72, v73
	v_cvt_pk_bf16_f32 v72, v66, v67
	v_cvt_pk_bf16_f32 v73, v68, v69
	global_store_dwordx4 v[76:77], v[70:73], off offset:256
	s_nop 1
	v_mov_b32_e32 v66, v220
	v_add_u32_e32 v68, 0x80, v144
	v_ashrrev_i32_e32 v69, 31, v68
	v_lshlrev_b64 v[72:73], 8, v[68:69]
	s_nop 0
	v_mul_f32_e32 v66, 0x3dd53b94, v66
	v_pk_mul_f32 v[70:71], v[64:65], v[66:67] op_sel_hi:[1,0]
	v_pk_mul_f32 v[62:63], v[62:63], v[66:67] op_sel_hi:[1,0]
	v_pk_mul_f32 v[64:65], v[60:61], v[66:67] op_sel_hi:[1,0]
	v_pk_mul_f32 v[60:61], v[58:59], v[66:67] op_sel_hi:[1,0]
	v_lshl_add_u64 v[58:59], s[20:21], 0, v[72:73]
	s_and_saveexec_b64 s[78:79], vcc
	s_cbranch_execz .LBB0_452
	v_lshl_add_u64 v[76:77], v[0:1], 3, v[58:59]
	global_load_dwordx4 v[72:75], v[76:77], off offset:16
	s_nop 0
	global_load_dwordx4 v[76:79], v[76:77], off
	s_waitcnt vmcnt(0)
	v_pk_mul_f32 v[84:85], v[60:61], v[72:73] op_sel:[1,1] op_sel_hi:[0,1]
	v_pk_mul_f32 v[82:83], v[62:63], v[76:77] op_sel:[1,1] op_sel_hi:[0,1]
	v_pk_mul_f32 v[80:81], v[62:63], v[76:77]
	v_pk_fma_f32 v[62:63], v[62:63], v[76:77], v[82:83] op_sel_hi:[1,0,1]
	s_nop 0
	v_mul_f32_e32 v62, v71, v79
	v_pk_fma_f32 v[76:77], v[70:71], v[78:79], v[62:63] op_sel_hi:[1,1,0] neg_lo:[0,0,1] neg_hi:[0,0,1]
	v_mul_f32_e32 v62, v70, v79
	v_pk_fma_f32 v[78:79], v[70:71], v[78:79], v[62:63] op_sel:[1,0,0] op_sel_hi:[0,1,0]
	v_pk_mul_f32 v[70:71], v[60:61], v[72:73]
	v_pk_fma_f32 v[60:61], v[60:61], v[72:73], v[84:85] op_sel_hi:[1,0,1]
	v_sub_f32_e32 v62, v80, v82
	v_mul_f32_e32 v60, v65, v75
	v_pk_fma_f32 v[72:73], v[64:65], v[74:75], v[60:61] op_sel_hi:[1,1,0] neg_lo:[0,0,1] neg_hi:[0,0,1]
	v_mul_f32_e32 v60, v64, v75
	v_pk_fma_f32 v[74:75], v[64:65], v[74:75], v[60:61] op_sel:[1,0,0] op_sel_hi:[0,1,0]
	v_sub_f32_e32 v60, v70, v84
	v_mov_b32_e32 v70, v76
	v_mov_b32_e32 v71, v78
	v_mov_b32_e32 v64, v72
	v_mov_b32_e32 v65, v74

.LBB0_454:
	s_or_b64 exec, exec, s[78:79]
	v_cvt_pk_bf16_f32 v54, v54, v55
	v_cvt_pk_bf16_f32 v55, v56, v57
	v_cvt_pk_bf16_f32 v56, v50, v51
	v_cvt_pk_bf16_f32 v57, v52, v53
	global_store_dwordx4 v[60:61], v[54:57], off offset:256
	s_nop 1
	v_mov_b32_e32 v50, v221
	v_add_u32_e32 v52, 0x90, v144
	v_ashrrev_i32_e32 v53, 31, v52
	v_lshlrev_b64 v[56:57], 8, v[52:53]
	s_nop 0
	v_mul_f32_e32 v50, 0x3dd53b94, v50
	v_pk_mul_f32 v[54:55], v[48:49], v[50:51] op_sel_hi:[1,0]
	v_pk_mul_f32 v[46:47], v[46:47], v[50:51] op_sel_hi:[1,0]
	v_pk_mul_f32 v[48:49], v[44:45], v[50:51] op_sel_hi:[1,0]
	v_pk_mul_f32 v[44:45], v[42:43], v[50:51] op_sel_hi:[1,0]
	v_lshl_add_u64 v[42:43], s[20:21], 0, v[56:57]
	s_and_saveexec_b64 s[78:79], vcc
	s_cbranch_execz .LBB0_456
	v_lshl_add_u64 v[60:61], v[0:1], 3, v[42:43]
	global_load_dwordx4 v[56:59], v[60:61], off offset:16
	s_nop 0
	global_load_dwordx4 v[60:63], v[60:61], off
	s_waitcnt vmcnt(0)
	v_pk_mul_f32 v[68:69], v[44:45], v[56:57] op_sel:[1,1] op_sel_hi:[0,1]
	v_pk_mul_f32 v[66:67], v[46:47], v[60:61] op_sel:[1,1] op_sel_hi:[0,1]
	v_pk_mul_f32 v[64:65], v[46:47], v[60:61]
	v_pk_fma_f32 v[46:47], v[46:47], v[60:61], v[66:67] op_sel_hi:[1,0,1]
	s_nop 0
	v_mul_f32_e32 v46, v55, v63
	v_pk_fma_f32 v[60:61], v[54:55], v[62:63], v[46:47] op_sel_hi:[1,1,0] neg_lo:[0,0,1] neg_hi:[0,0,1]
	v_mul_f32_e32 v46, v54, v63
	v_pk_fma_f32 v[62:63], v[54:55], v[62:63], v[46:47] op_sel:[1,0,0] op_sel_hi:[0,1,0]
	v_pk_mul_f32 v[54:55], v[44:45], v[56:57]
	v_pk_fma_f32 v[44:45], v[44:45], v[56:57], v[68:69] op_sel_hi:[1,0,1]
	v_sub_f32_e32 v46, v64, v66
	v_mul_f32_e32 v44, v49, v59
	v_pk_fma_f32 v[56:57], v[48:49], v[58:59], v[44:45] op_sel_hi:[1,1,0] neg_lo:[0,0,1] neg_hi:[0,0,1]
	v_mul_f32_e32 v44, v48, v59
	v_pk_fma_f32 v[58:59], v[48:49], v[58:59], v[44:45] op_sel:[1,0,0] op_sel_hi:[0,1,0]
	v_sub_f32_e32 v44, v54, v68
	v_mov_b32_e32 v54, v60
	v_mov_b32_e32 v55, v62
	v_mov_b32_e32 v48, v56
	v_mov_b32_e32 v49, v58

.LBB0_458:
	s_or_b64 exec, exec, s[78:79]
	v_cvt_pk_bf16_f32 v38, v38, v39
	v_cvt_pk_bf16_f32 v39, v40, v41
	v_cvt_pk_bf16_f32 v40, v34, v35
	v_cvt_pk_bf16_f32 v41, v36, v37
	global_store_dwordx4 v[44:45], v[38:41], off offset:256
	s_nop 1
	v_mov_b32_e32 v34, v222
	v_add_u32_e32 v36, 0xa0, v144
	v_ashrrev_i32_e32 v37, 31, v36
	v_lshlrev_b64 v[40:41], 8, v[36:37]
	s_nop 0
	v_mul_f32_e32 v34, 0x3dd53b94, v34
	v_pk_mul_f32 v[38:39], v[32:33], v[34:35] op_sel_hi:[1,0]
	v_pk_mul_f32 v[30:31], v[30:31], v[34:35] op_sel_hi:[1,0]
	v_pk_mul_f32 v[32:33], v[28:29], v[34:35] op_sel_hi:[1,0]
	v_pk_mul_f32 v[28:29], v[26:27], v[34:35] op_sel_hi:[1,0]
	v_lshl_add_u64 v[26:27], s[20:21], 0, v[40:41]
	s_and_saveexec_b64 s[78:79], vcc
	s_cbranch_execz .LBB0_460
	v_lshl_add_u64 v[44:45], v[0:1], 3, v[26:27]
	global_load_dwordx4 v[40:43], v[44:45], off offset:16
	s_nop 0
	global_load_dwordx4 v[44:47], v[44:45], off
	s_waitcnt vmcnt(0)
	v_pk_mul_f32 v[52:53], v[28:29], v[40:41] op_sel:[1,1] op_sel_hi:[0,1]
	v_pk_mul_f32 v[50:51], v[30:31], v[44:45] op_sel:[1,1] op_sel_hi:[0,1]
	v_pk_mul_f32 v[48:49], v[30:31], v[44:45]
	v_pk_fma_f32 v[30:31], v[30:31], v[44:45], v[50:51] op_sel_hi:[1,0,1]
	s_nop 0
	v_mul_f32_e32 v30, v39, v47
	v_pk_fma_f32 v[44:45], v[38:39], v[46:47], v[30:31] op_sel_hi:[1,1,0] neg_lo:[0,0,1] neg_hi:[0,0,1]
	v_mul_f32_e32 v30, v38, v47
	v_pk_fma_f32 v[46:47], v[38:39], v[46:47], v[30:31] op_sel:[1,0,0] op_sel_hi:[0,1,0]
	v_pk_mul_f32 v[38:39], v[28:29], v[40:41]
	v_pk_fma_f32 v[28:29], v[28:29], v[40:41], v[52:53] op_sel_hi:[1,0,1]
	v_sub_f32_e32 v30, v48, v50
	v_mul_f32_e32 v28, v33, v43
	v_pk_fma_f32 v[40:41], v[32:33], v[42:43], v[28:29] op_sel_hi:[1,1,0] neg_lo:[0,0,1] neg_hi:[0,0,1]
	v_mul_f32_e32 v28, v32, v43
	v_pk_fma_f32 v[42:43], v[32:33], v[42:43], v[28:29] op_sel:[1,0,0] op_sel_hi:[0,1,0]
	v_sub_f32_e32 v28, v38, v52
	v_mov_b32_e32 v38, v44
	v_mov_b32_e32 v39, v46
	v_mov_b32_e32 v32, v40
	v_mov_b32_e32 v33, v42

.LBB0_462:
	s_or_b64 exec, exec, s[78:79]
	v_cvt_pk_bf16_f32 v22, v22, v23
	v_cvt_pk_bf16_f32 v23, v24, v25
	v_cvt_pk_bf16_f32 v24, v18, v19
	v_cvt_pk_bf16_f32 v25, v20, v21
	global_store_dwordx4 v[28:29], v[22:25], off offset:256
	s_nop 1
	v_mov_b32_e32 v18, v223
	v_add_u32_e32 v20, 0xb0, v144
	v_ashrrev_i32_e32 v21, 31, v20
	v_lshlrev_b64 v[24:25], 8, v[20:21]
	s_nop 0
	v_mul_f32_e32 v18, 0x3dd53b94, v18
	v_pk_mul_f32 v[22:23], v[16:17], v[18:19] op_sel_hi:[1,0]
	v_pk_mul_f32 v[14:15], v[14:15], v[18:19] op_sel_hi:[1,0]
	v_pk_mul_f32 v[16:17], v[12:13], v[18:19] op_sel_hi:[1,0]
	v_pk_mul_f32 v[12:13], v[10:11], v[18:19] op_sel_hi:[1,0]
	v_lshl_add_u64 v[10:11], s[20:21], 0, v[24:25]
	s_and_saveexec_b64 s[78:79], vcc
	s_cbranch_execz .LBB0_464
	v_lshl_add_u64 v[28:29], v[0:1], 3, v[10:11]
	global_load_dwordx4 v[24:27], v[28:29], off offset:16
	s_nop 0
	global_load_dwordx4 v[28:31], v[28:29], off
	s_waitcnt vmcnt(0)
	v_pk_mul_f32 v[36:37], v[12:13], v[24:25] op_sel:[1,1] op_sel_hi:[0,1]
	v_pk_mul_f32 v[34:35], v[14:15], v[28:29] op_sel:[1,1] op_sel_hi:[0,1]
	v_mul_f32_e32 v0, v23, v31
	v_pk_mul_f32 v[32:33], v[14:15], v[28:29]
	v_pk_fma_f32 v[14:15], v[14:15], v[28:29], v[34:35] op_sel_hi:[1,0,1]
	v_pk_fma_f32 v[28:29], v[22:23], v[30:31], v[0:1] op_sel_hi:[1,1,0] neg_lo:[0,0,1] neg_hi:[0,0,1]
	v_mul_f32_e32 v0, v22, v31
	v_pk_fma_f32 v[30:31], v[22:23], v[30:31], v[0:1] op_sel:[1,0,0] op_sel_hi:[0,1,0]
	v_mul_f32_e32 v0, v17, v27
	v_pk_mul_f32 v[22:23], v[12:13], v[24:25]
	v_pk_fma_f32 v[12:13], v[12:13], v[24:25], v[36:37] op_sel_hi:[1,0,1]
	v_pk_fma_f32 v[24:25], v[16:17], v[26:27], v[0:1] op_sel_hi:[1,1,0] neg_lo:[0,0,1] neg_hi:[0,0,1]
	v_mul_f32_e32 v0, v16, v27
	v_pk_fma_f32 v[26:27], v[16:17], v[26:27], v[0:1] op_sel:[1,0,0] op_sel_hi:[0,1,0]
	v_sub_f32_e32 v14, v32, v34
	v_sub_f32_e32 v12, v22, v36
	v_mov_b32_e32 v22, v28
	v_mov_b32_e32 v23, v30
	v_mov_b32_e32 v16, v24
	v_mov_b32_e32 v17, v26

.LBB0_482:
	s_add_u32 s10, s80, 0x100
	s_addc_u32 s11, s81, 0
	s_add_i32 s2, 0, 0x10000
	v_add_u32_e32 v156, s2, v145
	ds_read_b128 v[140:143], v156
	ds_read_b128 v[148:151], v156 offset:1024
	ds_read_b128 v[152:155], v156 offset:2048
	ds_read_b128 v[156:159], v156 offset:3072
	s_cmp_eq_u32 s44, 4
	s_cselect_b32 s93, s77, s11
	s_cselect_b32 s92, s76, s10
	s_cselect_b32 s83, s24, s47
	s_cselect_b32 s82, s25, s46
	v_lshl_add_u64 v[164:165], s[80:81], 0, v[136:137]
	s_add_i32 m0, s58, 0xc000
	ds_read_b128 v[160:163], v147
	ds_read_b128 v[188:191], v147 offset:1024
	ds_read_b128 v[192:195], v147 offset:2048
	ds_read_b128 v[196:199], v147 offset:3072
	ds_read_b128 v[200:203], v147 offset:4096
	ds_read_b128 v[216:219], v147 offset:5120
	ds_read_b128 v[220:223], v147 offset:6144
	ds_read_b128 v[224:227], v147 offset:7168
	global_load_lds_dwordx4 v[164:165], off
	v_lshl_add_u64 v[164:165], s[80:81], 0, v[138:139]
	s_add_i32 m0, s58, 0xe000
	s_nop 0
	global_load_lds_dwordx4 v[164:165], off
	s_waitcnt lgkmcnt(8)
	s_barrier
	s_waitcnt lgkmcnt(0)
	s_waitcnt lgkmcnt(0)
	v_mfma_f32_16x16x32_bf16 v[126:129], v[140:143], v[160:163], v[126:129]
	v_mfma_f32_16x16x32_bf16 v[122:125], v[152:155], v[160:163], v[122:125]
	v_mfma_f32_16x16x32_bf16 v[110:113], v[140:143], v[192:195], v[110:113]
	v_mfma_f32_16x16x32_bf16 v[106:109], v[152:155], v[192:195], v[106:109]
	v_mfma_f32_16x16x32_bf16 v[94:97], v[140:143], v[200:203], v[94:97]
	v_mfma_f32_16x16x32_bf16 v[90:93], v[152:155], v[200:203], v[90:93]
	v_mfma_f32_16x16x32_bf16 v[78:81], v[140:143], v[220:223], v[78:81]
	v_mfma_f32_16x16x32_bf16 v[74:77], v[152:155], v[220:223], v[74:77]
	v_mfma_f32_16x16x32_bf16 v[126:129], v[148:151], v[188:191], v[126:129]
	v_mfma_f32_16x16x32_bf16 v[122:125], v[156:159], v[188:191], v[122:125]
	v_mfma_f32_16x16x32_bf16 v[110:113], v[148:151], v[196:199], v[110:113]
	v_mfma_f32_16x16x32_bf16 v[106:109], v[156:159], v[196:199], v[106:109]
	v_mfma_f32_16x16x32_bf16 v[94:97], v[148:151], v[216:219], v[94:97]
	v_mfma_f32_16x16x32_bf16 v[90:93], v[156:159], v[216:219], v[90:93]
	v_mfma_f32_16x16x32_bf16 v[78:81], v[148:151], v[224:227], v[78:81]
	v_mfma_f32_16x16x32_bf16 v[74:77], v[156:159], v[224:227], v[74:77]
	s_barrier
	s_add_i32 s17, 0, 0x14000
	v_add_u32_e32 v164, s17, v145
	s_add_i32 s2, s2, s3
	ds_read_b128 v[228:231], v164
	ds_read_b128 v[232:235], v164 offset:1024
	ds_read_b128 v[236:239], v164 offset:2048
	ds_read_b128 v[240:243], v164 offset:3072
	v_lshl_add_u64 v[164:165], s[82:83], 0, v[0:1]
	s_mov_b32 m0, s2
	v_lshl_add_u64 v[204:205], s[82:83], 0, v[130:131]
	global_load_lds_dwordx4 v[164:165], off
	s_add_i32 m0, s2, 0x2000
	s_nop 0
	global_load_lds_dwordx4 v[204:205], off
	s_barrier
	s_waitcnt lgkmcnt(0)
	s_waitcnt lgkmcnt(0)
	v_mfma_f32_16x16x32_bf16 v[118:121], v[228:231], v[160:163], v[118:121]
	v_mfma_f32_16x16x32_bf16 v[114:117], v[236:239], v[160:163], v[114:117]
	v_mfma_f32_16x16x32_bf16 v[102:105], v[228:231], v[192:195], v[102:105]
	v_mfma_f32_16x16x32_bf16 v[98:101], v[236:239], v[192:195], v[98:101]
	v_mfma_f32_16x16x32_bf16 v[86:89], v[228:231], v[200:203], v[86:89]
	v_mfma_f32_16x16x32_bf16 v[82:85], v[236:239], v[200:203], v[82:85]
	v_mfma_f32_16x16x32_bf16 v[70:73], v[228:231], v[220:223], v[70:73]
	v_mfma_f32_16x16x32_bf16 v[66:69], v[236:239], v[220:223], v[66:69]
	v_mfma_f32_16x16x32_bf16 v[118:121], v[232:235], v[188:191], v[118:121]
	v_mfma_f32_16x16x32_bf16 v[114:117], v[240:243], v[188:191], v[114:117]
	v_mfma_f32_16x16x32_bf16 v[102:105], v[232:235], v[196:199], v[102:105]
	v_mfma_f32_16x16x32_bf16 v[98:101], v[240:243], v[196:199], v[98:101]
	v_mfma_f32_16x16x32_bf16 v[86:89], v[232:235], v[216:219], v[86:89]
	v_mfma_f32_16x16x32_bf16 v[82:85], v[240:243], v[216:219], v[82:85]
	v_mfma_f32_16x16x32_bf16 v[70:73], v[232:235], v[224:227], v[70:73]
	v_mfma_f32_16x16x32_bf16 v[66:69], v[240:243], v[224:227], v[66:69]
	s_mov_b32 m0, s58
	v_lshl_add_u64 v[244:245], s[92:93], 0, v[134:135]
	s_barrier
	ds_read_b128 v[160:163], v147 offset:16384
	ds_read_b128 v[188:191], v147 offset:17408
	ds_read_b128 v[192:195], v147 offset:18432
	ds_read_b128 v[196:199], v147 offset:19456
	ds_read_b128 v[200:203], v147 offset:20480
	ds_read_b128 v[216:219], v147 offset:21504
	ds_read_b128 v[220:223], v147 offset:22528
	ds_read_b128 v[224:227], v147 offset:23552
	global_load_lds_dwordx4 v[244:245], off
	v_lshl_add_u64 v[246:247], s[92:93], 0, v[132:133]
	s_mov_b32 m0, s69
	s_nop 0
	global_load_lds_dwordx4 v[246:247], off
	s_barrier
	s_waitcnt lgkmcnt(0)
	s_waitcnt lgkmcnt(0)
	v_mfma_f32_16x16x32_bf16 v[62:65], v[140:143], v[160:163], v[62:65]
	v_mfma_f32_16x16x32_bf16 v[58:61], v[152:155], v[160:163], v[58:61]
	v_mfma_f32_16x16x32_bf16 v[46:49], v[140:143], v[192:195], v[46:49]
	v_mfma_f32_16x16x32_bf16 v[42:45], v[152:155], v[192:195], v[42:45]
	v_mfma_f32_16x16x32_bf16 v[30:33], v[140:143], v[200:203], v[30:33]
	v_mfma_f32_16x16x32_bf16 v[26:29], v[152:155], v[200:203], v[26:29]
	v_mfma_f32_16x16x32_bf16 v[14:17], v[140:143], v[220:223], v[14:17]
	v_mfma_f32_16x16x32_bf16 v[10:13], v[152:155], v[220:223], v[10:13]
	v_mfma_f32_16x16x32_bf16 v[62:65], v[148:151], v[188:191], v[62:65]
	v_mfma_f32_16x16x32_bf16 v[58:61], v[156:159], v[188:191], v[58:61]
	v_mfma_f32_16x16x32_bf16 v[46:49], v[148:151], v[196:199], v[46:49]
	v_mfma_f32_16x16x32_bf16 v[42:45], v[156:159], v[196:199], v[42:45]
	v_mfma_f32_16x16x32_bf16 v[30:33], v[148:151], v[216:219], v[30:33]
	v_mfma_f32_16x16x32_bf16 v[26:29], v[156:159], v[216:219], v[26:29]
	v_mfma_f32_16x16x32_bf16 v[14:17], v[148:151], v[224:227], v[14:17]
	v_mfma_f32_16x16x32_bf16 v[10:13], v[156:159], v[224:227], v[10:13]
	s_barrier
	s_add_u32 s26, s82, 0x20000
	s_addc_u32 s27, s83, 0
	s_add_i32 s2, s17, s3
	v_lshl_add_u64 v[140:141], s[26:27], 0, v[0:1]
	s_mov_b32 m0, s2
	s_nop 0
	global_load_lds_dwordx4 v[140:141], off
	v_lshl_add_u64 v[140:141], s[26:27], 0, v[130:131]
	s_add_i32 m0, s2, 0x2000
	s_nop 0
	global_load_lds_dwordx4 v[140:141], off
	s_waitcnt vmcnt(6)
	s_barrier
	v_mfma_f32_16x16x32_bf16 v[54:57], v[228:231], v[160:163], v[54:57]
	v_mfma_f32_16x16x32_bf16 v[50:53], v[236:239], v[160:163], v[50:53]
	v_mfma_f32_16x16x32_bf16 v[38:41], v[228:231], v[192:195], v[38:41]
	v_mfma_f32_16x16x32_bf16 v[34:37], v[236:239], v[192:195], v[34:37]
	v_mfma_f32_16x16x32_bf16 v[22:25], v[228:231], v[200:203], v[22:25]
	v_mfma_f32_16x16x32_bf16 v[18:21], v[236:239], v[200:203], v[18:21]
	v_mfma_f32_16x16x32_bf16 v[6:9], v[228:231], v[220:223], v[6:9]
	v_mfma_f32_16x16x32_bf16 v[2:5], v[236:239], v[220:223], v[2:5]
	v_mfma_f32_16x16x32_bf16 v[54:57], v[232:235], v[188:191], v[54:57]
	v_mfma_f32_16x16x32_bf16 v[50:53], v[240:243], v[188:191], v[50:53]
	v_mfma_f32_16x16x32_bf16 v[38:41], v[232:235], v[196:199], v[38:41]
	v_mfma_f32_16x16x32_bf16 v[34:37], v[240:243], v[196:199], v[34:37]
	v_mfma_f32_16x16x32_bf16 v[22:25], v[232:235], v[216:219], v[22:25]
	v_mfma_f32_16x16x32_bf16 v[18:21], v[240:243], v[216:219], v[18:21]
	v_mfma_f32_16x16x32_bf16 v[6:9], v[232:235], v[224:227], v[6:9]
	v_mfma_f32_16x16x32_bf16 v[2:5], v[240:243], v[224:227], v[2:5]
	s_add_i32 s2, 0, 0x18000
	v_add_u32_e32 v156, s2, v145
	s_barrier
	ds_read_b128 v[140:143], v156
	ds_read_b128 v[148:151], v156 offset:1024
	ds_read_b128 v[152:155], v156 offset:2048
	ds_read_b128 v[156:159], v156 offset:3072
	s_add_u32 s26, s92, 0xd0000
	s_addc_u32 s27, s93, 0
	s_mov_b32 m0, s70
	v_lshl_add_u64 v[228:229], s[26:27], 0, v[134:135]
	ds_read_b128 v[160:163], v147 offset:32768
	ds_read_b128 v[188:191], v147 offset:33792
	ds_read_b128 v[192:195], v147 offset:34816
	ds_read_b128 v[196:199], v147 offset:35840
	ds_read_b128 v[200:203], v147 offset:36864
	ds_read_b128 v[216:219], v147 offset:37888
	ds_read_b128 v[220:223], v147 offset:38912
	ds_read_b128 v[224:227], v147 offset:39936
	global_load_lds_dwordx4 v[228:229], off
	v_lshl_add_u64 v[228:229], s[26:27], 0, v[132:133]
	s_mov_b32 m0, s71
	s_nop 0
	global_load_lds_dwordx4 v[228:229], off
	s_waitcnt lgkmcnt(8)
	s_barrier
	s_waitcnt lgkmcnt(0)
	s_waitcnt lgkmcnt(0)
	v_mfma_f32_16x16x32_bf16 v[126:129], v[140:143], v[160:163], v[126:129]
	v_mfma_f32_16x16x32_bf16 v[122:125], v[152:155], v[160:163], v[122:125]
	v_mfma_f32_16x16x32_bf16 v[110:113], v[140:143], v[192:195], v[110:113]
	v_mfma_f32_16x16x32_bf16 v[106:109], v[152:155], v[192:195], v[106:109]
	v_mfma_f32_16x16x32_bf16 v[94:97], v[140:143], v[200:203], v[94:97]
	v_mfma_f32_16x16x32_bf16 v[90:93], v[152:155], v[200:203], v[90:93]
	v_mfma_f32_16x16x32_bf16 v[78:81], v[140:143], v[220:223], v[78:81]
	v_mfma_f32_16x16x32_bf16 v[74:77], v[152:155], v[220:223], v[74:77]
	v_mfma_f32_16x16x32_bf16 v[126:129], v[148:151], v[188:191], v[126:129]
	v_mfma_f32_16x16x32_bf16 v[122:125], v[156:159], v[188:191], v[122:125]
	v_mfma_f32_16x16x32_bf16 v[110:113], v[148:151], v[196:199], v[110:113]
	v_mfma_f32_16x16x32_bf16 v[106:109], v[156:159], v[196:199], v[106:109]
	v_mfma_f32_16x16x32_bf16 v[94:97], v[148:151], v[216:219], v[94:97]
	v_mfma_f32_16x16x32_bf16 v[90:93], v[156:159], v[216:219], v[90:93]
	v_mfma_f32_16x16x32_bf16 v[78:81], v[148:151], v[224:227], v[78:81]
	v_mfma_f32_16x16x32_bf16 v[74:77], v[156:159], v[224:227], v[74:77]
	s_barrier
	s_add_i32 s17, 0, 0x1c000
	s_add_i32 s2, s2, s3
	v_add_u32_e32 v206, s17, v145
	v_lshl_add_u64 v[164:165], v[164:165], 0, s[28:29]
	s_mov_b32 m0, s2
	ds_read_b128 v[228:231], v206
	ds_read_b128 v[232:235], v206 offset:1024
	ds_read_b128 v[236:239], v206 offset:2048
	ds_read_b128 v[240:243], v206 offset:3072
	global_load_lds_dwordx4 v[164:165], off
	v_lshl_add_u64 v[164:165], v[204:205], 0, s[28:29]
	s_add_i32 m0, s2, 0x2000
	s_nop 0
	global_load_lds_dwordx4 v[164:165], off
	s_barrier
	s_waitcnt lgkmcnt(0)
	s_waitcnt lgkmcnt(0)
	v_mfma_f32_16x16x32_bf16 v[118:121], v[228:231], v[160:163], v[118:121]
	v_mfma_f32_16x16x32_bf16 v[114:117], v[236:239], v[160:163], v[114:117]
	v_mfma_f32_16x16x32_bf16 v[102:105], v[228:231], v[192:195], v[102:105]
	v_mfma_f32_16x16x32_bf16 v[98:101], v[236:239], v[192:195], v[98:101]
	v_mfma_f32_16x16x32_bf16 v[86:89], v[228:231], v[200:203], v[86:89]
	v_mfma_f32_16x16x32_bf16 v[82:85], v[236:239], v[200:203], v[82:85]
	v_mfma_f32_16x16x32_bf16 v[70:73], v[228:231], v[220:223], v[70:73]
	v_mfma_f32_16x16x32_bf16 v[66:69], v[236:239], v[220:223], v[66:69]
	v_mfma_f32_16x16x32_bf16 v[118:121], v[232:235], v[188:191], v[118:121]
	v_mfma_f32_16x16x32_bf16 v[114:117], v[240:243], v[188:191], v[114:117]
	v_mfma_f32_16x16x32_bf16 v[102:105], v[232:235], v[196:199], v[102:105]
	v_mfma_f32_16x16x32_bf16 v[98:101], v[240:243], v[196:199], v[98:101]
	v_mfma_f32_16x16x32_bf16 v[86:89], v[232:235], v[216:219], v[86:89]
	v_mfma_f32_16x16x32_bf16 v[82:85], v[240:243], v[216:219], v[82:85]
	v_mfma_f32_16x16x32_bf16 v[70:73], v[232:235], v[224:227], v[70:73]
	v_mfma_f32_16x16x32_bf16 v[66:69], v[240:243], v[224:227], v[66:69]
	s_mov_b32 m0, s72
	v_lshl_add_u64 v[164:165], v[244:245], 0, s[28:29]
	s_barrier
	ds_read_b128 v[160:163], v147 offset:49152
	ds_read_b128 v[188:191], v147 offset:50176
	ds_read_b128 v[192:195], v147 offset:51200
	ds_read_b128 v[196:199], v147 offset:52224
	ds_read_b128 v[200:203], v147 offset:53248
	ds_read_b128 v[216:219], v147 offset:54272
	ds_read_b128 v[220:223], v147 offset:55296
	ds_read_b128 v[224:227], v147 offset:56320
	global_load_lds_dwordx4 v[164:165], off
	v_lshl_add_u64 v[164:165], v[246:247], 0, s[28:29]
	s_mov_b32 m0, s73
	s_nop 0
	global_load_lds_dwordx4 v[164:165], off
	s_barrier
	s_waitcnt lgkmcnt(0)
	s_waitcnt lgkmcnt(0)
	v_mfma_f32_16x16x32_bf16 v[62:65], v[140:143], v[160:163], v[62:65]
	v_mfma_f32_16x16x32_bf16 v[58:61], v[152:155], v[160:163], v[58:61]
	v_mfma_f32_16x16x32_bf16 v[46:49], v[140:143], v[192:195], v[46:49]
	v_mfma_f32_16x16x32_bf16 v[42:45], v[152:155], v[192:195], v[42:45]
	v_mfma_f32_16x16x32_bf16 v[30:33], v[140:143], v[200:203], v[30:33]
	v_mfma_f32_16x16x32_bf16 v[26:29], v[152:155], v[200:203], v[26:29]
	v_mfma_f32_16x16x32_bf16 v[14:17], v[140:143], v[220:223], v[14:17]
	v_mfma_f32_16x16x32_bf16 v[10:13], v[152:155], v[220:223], v[10:13]
	v_mfma_f32_16x16x32_bf16 v[62:65], v[148:151], v[188:191], v[62:65]
	v_mfma_f32_16x16x32_bf16 v[58:61], v[156:159], v[188:191], v[58:61]
	v_mfma_f32_16x16x32_bf16 v[46:49], v[148:151], v[196:199], v[46:49]
	v_mfma_f32_16x16x32_bf16 v[42:45], v[156:159], v[196:199], v[42:45]
	v_mfma_f32_16x16x32_bf16 v[30:33], v[148:151], v[216:219], v[30:33]
	v_mfma_f32_16x16x32_bf16 v[26:29], v[156:159], v[216:219], v[26:29]
	v_mfma_f32_16x16x32_bf16 v[14:17], v[148:151], v[224:227], v[14:17]
	v_mfma_f32_16x16x32_bf16 v[10:13], v[156:159], v[224:227], v[10:13]
	s_barrier
	s_add_u32 s26, s82, 0x20080
	s_addc_u32 s27, s83, 0
	s_add_i32 s2, s17, s3
	v_lshl_add_u64 v[140:141], s[26:27], 0, v[0:1]
	s_mov_b32 m0, s2
	s_nop 0
	global_load_lds_dwordx4 v[140:141], off
	v_lshl_add_u64 v[140:141], s[26:27], 0, v[130:131]
	s_add_i32 m0, s2, 0x2000
	s_nop 0
	global_load_lds_dwordx4 v[140:141], off
	s_waitcnt vmcnt(6)
	s_barrier
	v_mfma_f32_16x16x32_bf16 v[54:57], v[228:231], v[160:163], v[54:57]
	v_mfma_f32_16x16x32_bf16 v[50:53], v[236:239], v[160:163], v[50:53]
	v_mfma_f32_16x16x32_bf16 v[38:41], v[228:231], v[192:195], v[38:41]
	v_mfma_f32_16x16x32_bf16 v[34:37], v[236:239], v[192:195], v[34:37]
	v_mfma_f32_16x16x32_bf16 v[22:25], v[228:231], v[200:203], v[22:25]
	v_mfma_f32_16x16x32_bf16 v[18:21], v[236:239], v[200:203], v[18:21]
	v_mfma_f32_16x16x32_bf16 v[6:9], v[228:231], v[220:223], v[6:9]
	v_mfma_f32_16x16x32_bf16 v[2:5], v[236:239], v[220:223], v[2:5]
	v_mfma_f32_16x16x32_bf16 v[54:57], v[232:235], v[188:191], v[54:57]
	v_mfma_f32_16x16x32_bf16 v[50:53], v[240:243], v[188:191], v[50:53]
	v_mfma_f32_16x16x32_bf16 v[38:41], v[232:235], v[196:199], v[38:41]
	v_mfma_f32_16x16x32_bf16 v[34:37], v[240:243], v[196:199], v[34:37]
	v_mfma_f32_16x16x32_bf16 v[22:25], v[232:235], v[216:219], v[22:25]
	v_mfma_f32_16x16x32_bf16 v[18:21], v[240:243], v[216:219], v[18:21]
	v_mfma_f32_16x16x32_bf16 v[6:9], v[232:235], v[224:227], v[6:9]
	v_mfma_f32_16x16x32_bf16 v[2:5], v[240:243], v[224:227], v[2:5]
	s_add_i32 s44, s44, 2
	s_add_u32 s46, s46, 0x100
	s_addc_u32 s47, s47, 0
	s_cmp_gt_u32 s44, 5
	s_mov_b64 s[80:81], s[10:11]
	s_barrier
	s_cbranch_scc0 .LBB0_482
	v_lshl_add_u32 v142, s63, 8, v144
	v_ashrrev_i32_e32 v143, 31, v142
	v_lshl_add_u64 v[140:141], v[142:143], 2, s[38:39]
	global_load_dword v216, v[140:141], off
	global_load_dword v218, v[140:141], off offset:64
	global_load_dword v220, v[140:141], off offset:128
	global_load_dword v222, v[140:141], off offset:192
	global_load_dword v224, v[140:141], off offset:512
	global_load_dword v226, v[140:141], off offset:576
	global_load_dword v228, v[140:141], off offset:640
	global_load_dword v230, v[140:141], off offset:704
	v_lshl_or_b32 v148, s62, 8, v146
	v_ashrrev_i32_e32 v149, 31, v148
	s_mov_b32 s2, 0x80000
	s_mov_b64 s[4:5], 0x80000
	s_mov_b32 s62, s74
	s_mov_b32 s63, s41
	s_mov_b64 s[82:83], s[78:79]
	s_mov_b64 s[80:81], s[76:77]
	v_readlane_b32 s93, v251, 60
	s_waitcnt vmcnt(7)
	v_mov_b32_e32 v150, v216
	v_pk_mul_f32 v[128:129], v[128:129], v[150:151] op_sel_hi:[1,0]
	v_pk_mul_f32 v[126:127], v[126:127], v[150:151] op_sel_hi:[1,0]
	v_pk_mul_f32 v[122:123], v[122:123], v[150:151] op_sel_hi:[1,0]
	v_pk_mul_f32 v[124:125], v[124:125], v[150:151] op_sel_hi:[1,0]
	v_cvt_pk_bf16_f32 v126, v126, v127
	v_cvt_pk_bf16_f32 v127, v128, v129
	v_cvt_pk_bf16_f32 v128, v122, v123
	v_lshlrev_b64 v[122:123], 12, v[142:143]
	v_cvt_pk_bf16_f32 v129, v124, v125
	v_lshl_add_u64 v[122:123], s[56:57], 0, v[122:123]
	v_lshlrev_b64 v[124:125], 1, v[148:149]
	v_lshl_add_u64 v[122:123], v[122:123], 0, v[124:125]
	global_store_dwordx4 v[122:123], v[126:129], off
	v_pk_mul_f32 v[120:121], v[120:121], v[150:151] op_sel_hi:[1,0]
	v_pk_mul_f32 v[118:119], v[118:119], v[150:151] op_sel_hi:[1,0]
	v_pk_mul_f32 v[126:127], v[116:117], v[150:151] op_sel_hi:[1,0]
	v_pk_mul_f32 v[116:117], v[114:115], v[150:151] op_sel_hi:[1,0]
	v_cvt_pk_bf16_f32 v114, v118, v119
	v_cvt_pk_bf16_f32 v115, v120, v121
	v_cvt_pk_bf16_f32 v116, v116, v117
	v_cvt_pk_bf16_f32 v117, v126, v127
	global_store_dwordx4 v[122:123], v[114:117], off offset:256
	s_nop 1
	v_or_b32_e32 v114, 16, v142
	v_ashrrev_i32_e32 v115, 31, v114
	v_lshl_add_u64 v[116:117], v[114:115], 2, s[38:39]
	s_waitcnt vmcnt(8)
	v_mov_b32_e32 v116, v218
	v_pk_mul_f32 v[110:111], v[110:111], v[116:117] op_sel_hi:[1,0]
	v_pk_mul_f32 v[118:119], v[108:109], v[116:117] op_sel_hi:[1,0]
	v_pk_mul_f32 v[108:109], v[106:107], v[116:117] op_sel_hi:[1,0]
	v_cvt_pk_bf16_f32 v106, v110, v111
	v_lshlrev_b64 v[110:111], 12, v[114:115]
	v_pk_mul_f32 v[112:113], v[112:113], v[116:117] op_sel_hi:[1,0]
	v_lshl_add_u64 v[110:111], s[56:57], 0, v[110:111]
	v_cvt_pk_bf16_f32 v107, v112, v113
	v_cvt_pk_bf16_f32 v108, v108, v109
	v_cvt_pk_bf16_f32 v109, v118, v119
	v_lshl_add_u64 v[110:111], v[110:111], 0, v[124:125]
	global_store_dwordx4 v[110:111], v[106:109], off
	v_pk_mul_f32 v[104:105], v[104:105], v[116:117] op_sel_hi:[1,0]
	v_pk_mul_f32 v[102:103], v[102:103], v[116:117] op_sel_hi:[1,0]
	v_pk_mul_f32 v[106:107], v[100:101], v[116:117] op_sel_hi:[1,0]
	v_pk_mul_f32 v[100:101], v[98:99], v[116:117] op_sel_hi:[1,0]
	v_cvt_pk_bf16_f32 v98, v102, v103
	v_cvt_pk_bf16_f32 v99, v104, v105
	v_cvt_pk_bf16_f32 v100, v100, v101
	v_cvt_pk_bf16_f32 v101, v106, v107
	global_store_dwordx4 v[110:111], v[98:101], off offset:256
	s_nop 1
	v_or_b32_e32 v98, 32, v142
	v_ashrrev_i32_e32 v99, 31, v98
	v_lshl_add_u64 v[100:101], v[98:99], 2, s[38:39]
	s_waitcnt vmcnt(9)
	v_mov_b32_e32 v100, v220
	v_pk_mul_f32 v[94:95], v[94:95], v[100:101] op_sel_hi:[1,0]
	v_pk_mul_f32 v[102:103], v[92:93], v[100:101] op_sel_hi:[1,0]
	v_pk_mul_f32 v[92:93], v[90:91], v[100:101] op_sel_hi:[1,0]
	v_cvt_pk_bf16_f32 v90, v94, v95
	v_lshlrev_b64 v[94:95], 12, v[98:99]
	v_pk_mul_f32 v[96:97], v[96:97], v[100:101] op_sel_hi:[1,0]
	v_lshl_add_u64 v[94:95], s[56:57], 0, v[94:95]
	v_cvt_pk_bf16_f32 v91, v96, v97
	v_cvt_pk_bf16_f32 v92, v92, v93
	v_cvt_pk_bf16_f32 v93, v102, v103
	v_lshl_add_u64 v[94:95], v[94:95], 0, v[124:125]
	global_store_dwordx4 v[94:95], v[90:93], off
	v_pk_mul_f32 v[88:89], v[88:89], v[100:101] op_sel_hi:[1,0]
	v_pk_mul_f32 v[86:87], v[86:87], v[100:101] op_sel_hi:[1,0]
	v_pk_mul_f32 v[90:91], v[84:85], v[100:101] op_sel_hi:[1,0]
	v_pk_mul_f32 v[84:85], v[82:83], v[100:101] op_sel_hi:[1,0]
	v_cvt_pk_bf16_f32 v82, v86, v87
	v_cvt_pk_bf16_f32 v83, v88, v89
	v_cvt_pk_bf16_f32 v84, v84, v85
	v_cvt_pk_bf16_f32 v85, v90, v91
	global_store_dwordx4 v[94:95], v[82:85], off offset:256
	s_nop 1
	v_or_b32_e32 v82, 48, v142
	v_ashrrev_i32_e32 v83, 31, v82
	v_lshl_add_u64 v[84:85], v[82:83], 2, s[38:39]
	s_waitcnt vmcnt(10)
	v_mov_b32_e32 v84, v222
	v_pk_mul_f32 v[78:79], v[78:79], v[84:85] op_sel_hi:[1,0]
	v_pk_mul_f32 v[86:87], v[76:77], v[84:85] op_sel_hi:[1,0]
	v_pk_mul_f32 v[76:77], v[74:75], v[84:85] op_sel_hi:[1,0]
	v_cvt_pk_bf16_f32 v74, v78, v79
	v_lshlrev_b64 v[78:79], 12, v[82:83]
	v_pk_mul_f32 v[80:81], v[80:81], v[84:85] op_sel_hi:[1,0]
	v_lshl_add_u64 v[78:79], s[56:57], 0, v[78:79]
	v_cvt_pk_bf16_f32 v75, v80, v81
	v_cvt_pk_bf16_f32 v76, v76, v77
	v_cvt_pk_bf16_f32 v77, v86, v87
	v_lshl_add_u64 v[78:79], v[78:79], 0, v[124:125]
	global_store_dwordx4 v[78:79], v[74:77], off
	v_pk_mul_f32 v[72:73], v[72:73], v[84:85] op_sel_hi:[1,0]
	v_pk_mul_f32 v[70:71], v[70:71], v[84:85] op_sel_hi:[1,0]
	v_pk_mul_f32 v[74:75], v[68:69], v[84:85] op_sel_hi:[1,0]
	v_pk_mul_f32 v[68:69], v[66:67], v[84:85] op_sel_hi:[1,0]
	v_cvt_pk_bf16_f32 v66, v70, v71
	v_cvt_pk_bf16_f32 v67, v72, v73
	v_cvt_pk_bf16_f32 v68, v68, v69
	v_cvt_pk_bf16_f32 v69, v74, v75
	global_store_dwordx4 v[78:79], v[66:69], off offset:256
	s_waitcnt vmcnt(11)
	v_mov_b32_e32 v66, v224
	v_pk_mul_f32 v[64:65], v[64:65], v[66:67] op_sel_hi:[1,0]
	v_pk_mul_f32 v[62:63], v[62:63], v[66:67] op_sel_hi:[1,0]
	v_pk_mul_f32 v[68:69], v[60:61], v[66:67] op_sel_hi:[1,0]
	v_pk_mul_f32 v[60:61], v[58:59], v[66:67] op_sel_hi:[1,0]
	v_cvt_pk_bf16_f32 v59, v64, v65
	v_add_co_u32_e32 v64, vcc, s2, v122
	v_cvt_pk_bf16_f32 v58, v62, v63
	v_cvt_pk_bf16_f32 v60, v60, v61
	v_cvt_pk_bf16_f32 v61, v68, v69
	v_addc_co_u32_e32 v65, vcc, 0, v123, vcc
	global_store_dwordx4 v[64:65], v[58:61], off
	v_pk_mul_f32 v[56:57], v[56:57], v[66:67] op_sel_hi:[1,0]
	v_pk_mul_f32 v[54:55], v[54:55], v[66:67] op_sel_hi:[1,0]
	v_pk_mul_f32 v[58:59], v[52:53], v[66:67] op_sel_hi:[1,0]
	v_pk_mul_f32 v[52:53], v[50:51], v[66:67] op_sel_hi:[1,0]
	v_lshl_add_u64 v[62:63], v[122:123], 0, s[4:5]
	v_cvt_pk_bf16_f32 v50, v54, v55
	v_cvt_pk_bf16_f32 v51, v56, v57
	v_cvt_pk_bf16_f32 v52, v52, v53
	v_cvt_pk_bf16_f32 v53, v58, v59
	global_store_dwordx4 v[62:63], v[50:53], off offset:256
	s_mov_b32 s2, 0x90000
	s_mov_b64 s[4:5], 0x90000
	s_waitcnt vmcnt(12)
	v_mov_b32_e32 v50, v226
	v_pk_mul_f32 v[48:49], v[48:49], v[50:51] op_sel_hi:[1,0]
	v_pk_mul_f32 v[46:47], v[46:47], v[50:51] op_sel_hi:[1,0]
	v_pk_mul_f32 v[52:53], v[44:45], v[50:51] op_sel_hi:[1,0]
	v_pk_mul_f32 v[44:45], v[42:43], v[50:51] op_sel_hi:[1,0]
	v_cvt_pk_bf16_f32 v43, v48, v49
	v_add_co_u32_e32 v48, vcc, s2, v122
	v_cvt_pk_bf16_f32 v42, v46, v47
	v_cvt_pk_bf16_f32 v44, v44, v45
	v_cvt_pk_bf16_f32 v45, v52, v53
	v_addc_co_u32_e32 v49, vcc, 0, v123, vcc
	global_store_dwordx4 v[48:49], v[42:45], off
	v_pk_mul_f32 v[40:41], v[40:41], v[50:51] op_sel_hi:[1,0]
	v_pk_mul_f32 v[38:39], v[38:39], v[50:51] op_sel_hi:[1,0]
	v_pk_mul_f32 v[42:43], v[36:37], v[50:51] op_sel_hi:[1,0]
	v_pk_mul_f32 v[36:37], v[34:35], v[50:51] op_sel_hi:[1,0]
	v_lshl_add_u64 v[46:47], v[122:123], 0, s[4:5]
	v_cvt_pk_bf16_f32 v34, v38, v39
	v_cvt_pk_bf16_f32 v35, v40, v41
	v_cvt_pk_bf16_f32 v36, v36, v37
	v_cvt_pk_bf16_f32 v37, v42, v43
	global_store_dwordx4 v[46:47], v[34:37], off offset:256
	s_mov_b32 s2, 0xa0000
	s_mov_b64 s[4:5], 0xa0000
	s_waitcnt vmcnt(13)
	v_mov_b32_e32 v34, v228
	v_pk_mul_f32 v[32:33], v[32:33], v[34:35] op_sel_hi:[1,0]
	v_pk_mul_f32 v[30:31], v[30:31], v[34:35] op_sel_hi:[1,0]
	v_pk_mul_f32 v[36:37], v[28:29], v[34:35] op_sel_hi:[1,0]
	v_pk_mul_f32 v[28:29], v[26:27], v[34:35] op_sel_hi:[1,0]
	v_cvt_pk_bf16_f32 v27, v32, v33
	v_add_co_u32_e32 v32, vcc, s2, v122
	v_cvt_pk_bf16_f32 v26, v30, v31
	v_cvt_pk_bf16_f32 v28, v28, v29
	v_cvt_pk_bf16_f32 v29, v36, v37
	v_addc_co_u32_e32 v33, vcc, 0, v123, vcc
	global_store_dwordx4 v[32:33], v[26:29], off
	v_pk_mul_f32 v[24:25], v[24:25], v[34:35] op_sel_hi:[1,0]
	v_pk_mul_f32 v[22:23], v[22:23], v[34:35] op_sel_hi:[1,0]
	v_pk_mul_f32 v[26:27], v[20:21], v[34:35] op_sel_hi:[1,0]
	v_pk_mul_f32 v[20:21], v[18:19], v[34:35] op_sel_hi:[1,0]
	v_lshl_add_u64 v[30:31], v[122:123], 0, s[4:5]
	v_cvt_pk_bf16_f32 v18, v22, v23
	v_cvt_pk_bf16_f32 v19, v24, v25
	v_cvt_pk_bf16_f32 v20, v20, v21
	v_cvt_pk_bf16_f32 v21, v26, v27
	global_store_dwordx4 v[30:31], v[18:21], off offset:256
	s_mov_b32 s2, 0xb0000
	s_mov_b64 s[4:5], 0xb0000
	s_waitcnt vmcnt(14)
	v_mov_b32_e32 v18, v230
	v_pk_mul_f32 v[16:17], v[16:17], v[18:19] op_sel_hi:[1,0]
	v_pk_mul_f32 v[14:15], v[14:15], v[18:19] op_sel_hi:[1,0]
	v_pk_mul_f32 v[20:21], v[12:13], v[18:19] op_sel_hi:[1,0]
	v_pk_mul_f32 v[12:13], v[10:11], v[18:19] op_sel_hi:[1,0]
	v_cvt_pk_bf16_f32 v11, v16, v17
	v_add_co_u32_e32 v16, vcc, s2, v122
	v_cvt_pk_bf16_f32 v10, v14, v15
	v_cvt_pk_bf16_f32 v12, v12, v13
	v_cvt_pk_bf16_f32 v13, v20, v21
	v_addc_co_u32_e32 v17, vcc, 0, v123, vcc
	global_store_dwordx4 v[16:17], v[10:13], off
	v_pk_mul_f32 v[8:9], v[8:9], v[18:19] op_sel_hi:[1,0]
	v_pk_mul_f32 v[6:7], v[6:7], v[18:19] op_sel_hi:[1,0]
	v_pk_mul_f32 v[10:11], v[4:5], v[18:19] op_sel_hi:[1,0]
	v_pk_mul_f32 v[4:5], v[2:3], v[18:19] op_sel_hi:[1,0]
	v_lshl_add_u64 v[14:15], v[122:123], 0, s[4:5]
	v_cvt_pk_bf16_f32 v2, v6, v7
	v_cvt_pk_bf16_f32 v3, v8, v9
	v_cvt_pk_bf16_f32 v4, v4, v5
	v_cvt_pk_bf16_f32 v5, v10, v11
	s_and_b64 vcc, exec, s[6:7]
	global_store_dwordx4 v[14:15], v[2:5], off offset:256
	s_cbranch_vccz .LBB0_473
	v_readlane_b32 s4, v254, 12
	s_waitcnt vmcnt(0)
	v_readlane_b32 s5, v254, 13
	v_readlane_b32 s84, v251, 38
	v_readlane_b32 s18, v253, 0
	s_andn2_b64 vcc, exec, s[4:5]
	v_readlane_b32 s85, v251, 39
	v_readlane_b32 s86, v251, 40
	v_readlane_b32 s87, v251, 41
	v_readlane_b32 s14, v250, 63
	v_readlane_b32 s19, v253, 1
	s_cbranch_vccnz .LBB0_486
	s_barrier

.LBB0_500:
	s_add_u32 s2, s6, 0xfffe0080
	s_addc_u32 s17, s7, -1
	s_add_i32 s26, 0, 0x10000
	v_add_u32_e32 v156, s26, v145
	ds_read_b128 v[140:143], v156
	ds_read_b128 v[148:151], v156 offset:1024
	ds_read_b128 v[152:155], v156 offset:2048
	ds_read_b128 v[156:159], v156 offset:3072
	s_cmp_eq_u32 s44, 4
	s_cselect_b32 s81, s11, s17
	s_cselect_b32 s80, s24, s2
	s_cselect_b32 s79, s75, s46
	s_cselect_b32 s78, s74, s25
	v_lshl_add_u64 v[164:165], s[6:7], 0, v[136:137]
	s_add_i32 m0, s58, 0xc000
	ds_read_b128 v[160:163], v147
	ds_read_b128 v[188:191], v147 offset:1024
	ds_read_b128 v[192:195], v147 offset:2048
	ds_read_b128 v[196:199], v147 offset:3072
	ds_read_b128 v[200:203], v147 offset:4096
	ds_read_b128 v[216:219], v147 offset:5120
	ds_read_b128 v[220:223], v147 offset:6144
	ds_read_b128 v[224:227], v147 offset:7168
	global_load_lds_dwordx4 v[164:165], off
	v_lshl_add_u64 v[164:165], s[6:7], 0, v[138:139]
	s_add_i32 m0, s58, 0xe000
	s_nop 0
	global_load_lds_dwordx4 v[164:165], off
	s_waitcnt lgkmcnt(8)
	s_barrier
	s_waitcnt lgkmcnt(0)
	s_waitcnt lgkmcnt(0)
	v_mfma_f32_16x16x32_bf16 v[126:129], v[140:143], v[160:163], v[126:129]
	v_mfma_f32_16x16x32_bf16 v[122:125], v[152:155], v[160:163], v[122:125]
	v_mfma_f32_16x16x32_bf16 v[110:113], v[140:143], v[192:195], v[110:113]
	v_mfma_f32_16x16x32_bf16 v[106:109], v[152:155], v[192:195], v[106:109]
	v_mfma_f32_16x16x32_bf16 v[94:97], v[140:143], v[200:203], v[94:97]
	v_mfma_f32_16x16x32_bf16 v[90:93], v[152:155], v[200:203], v[90:93]
	v_mfma_f32_16x16x32_bf16 v[78:81], v[140:143], v[220:223], v[78:81]
	v_mfma_f32_16x16x32_bf16 v[74:77], v[152:155], v[220:223], v[74:77]
	v_mfma_f32_16x16x32_bf16 v[126:129], v[148:151], v[188:191], v[126:129]
	v_mfma_f32_16x16x32_bf16 v[122:125], v[156:159], v[188:191], v[122:125]
	v_mfma_f32_16x16x32_bf16 v[110:113], v[148:151], v[196:199], v[110:113]
	v_mfma_f32_16x16x32_bf16 v[106:109], v[156:159], v[196:199], v[106:109]
	v_mfma_f32_16x16x32_bf16 v[94:97], v[148:151], v[216:219], v[94:97]
	v_mfma_f32_16x16x32_bf16 v[90:93], v[156:159], v[216:219], v[90:93]
	v_mfma_f32_16x16x32_bf16 v[78:81], v[148:151], v[224:227], v[78:81]
	v_mfma_f32_16x16x32_bf16 v[74:77], v[156:159], v[224:227], v[74:77]
	s_barrier
	s_add_i32 s2, 0, 0x14000
	v_add_u32_e32 v164, s2, v145
	s_add_i32 s17, s26, s3
	ds_read_b128 v[228:231], v164
	ds_read_b128 v[232:235], v164 offset:1024
	ds_read_b128 v[236:239], v164 offset:2048
	ds_read_b128 v[240:243], v164 offset:3072
	v_lshl_add_u64 v[164:165], s[78:79], 0, v[0:1]
	s_mov_b32 m0, s17
	v_lshl_add_u64 v[204:205], s[78:79], 0, v[130:131]
	global_load_lds_dwordx4 v[164:165], off
	s_add_i32 m0, s17, 0x2000
	s_nop 0
	global_load_lds_dwordx4 v[204:205], off
	s_barrier
	s_waitcnt lgkmcnt(0)
	s_waitcnt lgkmcnt(0)
	v_mfma_f32_16x16x32_bf16 v[118:121], v[228:231], v[160:163], v[118:121]
	v_mfma_f32_16x16x32_bf16 v[114:117], v[236:239], v[160:163], v[114:117]
	v_mfma_f32_16x16x32_bf16 v[102:105], v[228:231], v[192:195], v[102:105]
	v_mfma_f32_16x16x32_bf16 v[98:101], v[236:239], v[192:195], v[98:101]
	v_mfma_f32_16x16x32_bf16 v[86:89], v[228:231], v[200:203], v[86:89]
	v_mfma_f32_16x16x32_bf16 v[82:85], v[236:239], v[200:203], v[82:85]
	v_mfma_f32_16x16x32_bf16 v[70:73], v[228:231], v[220:223], v[70:73]
	v_mfma_f32_16x16x32_bf16 v[66:69], v[236:239], v[220:223], v[66:69]
	v_mfma_f32_16x16x32_bf16 v[118:121], v[232:235], v[188:191], v[118:121]
	v_mfma_f32_16x16x32_bf16 v[114:117], v[240:243], v[188:191], v[114:117]
	v_mfma_f32_16x16x32_bf16 v[102:105], v[232:235], v[196:199], v[102:105]
	v_mfma_f32_16x16x32_bf16 v[98:101], v[240:243], v[196:199], v[98:101]
	v_mfma_f32_16x16x32_bf16 v[86:89], v[232:235], v[216:219], v[86:89]
	v_mfma_f32_16x16x32_bf16 v[82:85], v[240:243], v[216:219], v[82:85]
	v_mfma_f32_16x16x32_bf16 v[70:73], v[232:235], v[224:227], v[70:73]
	v_mfma_f32_16x16x32_bf16 v[66:69], v[240:243], v[224:227], v[66:69]
	s_mov_b32 m0, s58
	v_lshl_add_u64 v[244:245], s[80:81], 0, v[134:135]
	s_barrier
	ds_read_b128 v[160:163], v147 offset:16384
	ds_read_b128 v[188:191], v147 offset:17408
	ds_read_b128 v[192:195], v147 offset:18432
	ds_read_b128 v[196:199], v147 offset:19456
	ds_read_b128 v[200:203], v147 offset:20480
	ds_read_b128 v[216:219], v147 offset:21504
	ds_read_b128 v[220:223], v147 offset:22528
	ds_read_b128 v[224:227], v147 offset:23552
	global_load_lds_dwordx4 v[244:245], off
	v_lshl_add_u64 v[246:247], s[80:81], 0, v[132:133]
	s_mov_b32 m0, s69
	s_nop 0
	global_load_lds_dwordx4 v[246:247], off
	s_barrier
	s_waitcnt lgkmcnt(0)
	s_waitcnt lgkmcnt(0)
	v_mfma_f32_16x16x32_bf16 v[62:65], v[140:143], v[160:163], v[62:65]
	v_mfma_f32_16x16x32_bf16 v[58:61], v[152:155], v[160:163], v[58:61]
	v_mfma_f32_16x16x32_bf16 v[54:57], v[140:143], v[192:195], v[54:57]
	v_mfma_f32_16x16x32_bf16 v[46:49], v[152:155], v[192:195], v[46:49]
	v_mfma_f32_16x16x32_bf16 v[38:41], v[140:143], v[200:203], v[38:41]
	v_mfma_f32_16x16x32_bf16 v[30:33], v[152:155], v[200:203], v[30:33]
	v_mfma_f32_16x16x32_bf16 v[22:25], v[140:143], v[220:223], v[22:25]
	v_mfma_f32_16x16x32_bf16 v[14:17], v[152:155], v[220:223], v[14:17]
	v_mfma_f32_16x16x32_bf16 v[62:65], v[148:151], v[188:191], v[62:65]
	v_mfma_f32_16x16x32_bf16 v[58:61], v[156:159], v[188:191], v[58:61]
	v_mfma_f32_16x16x32_bf16 v[54:57], v[148:151], v[196:199], v[54:57]
	v_mfma_f32_16x16x32_bf16 v[46:49], v[156:159], v[196:199], v[46:49]
	v_mfma_f32_16x16x32_bf16 v[38:41], v[148:151], v[216:219], v[38:41]
	v_mfma_f32_16x16x32_bf16 v[30:33], v[156:159], v[216:219], v[30:33]
	v_mfma_f32_16x16x32_bf16 v[22:25], v[148:151], v[224:227], v[22:25]
	v_mfma_f32_16x16x32_bf16 v[14:17], v[156:159], v[224:227], v[14:17]
	s_barrier
	s_add_u32 s26, s78, 0xd0000
	s_addc_u32 s27, s79, 0
	s_add_i32 s2, s2, s3
	v_lshl_add_u64 v[140:141], s[26:27], 0, v[0:1]
	s_mov_b32 m0, s2
	s_nop 0
	global_load_lds_dwordx4 v[140:141], off
	v_lshl_add_u64 v[140:141], s[26:27], 0, v[130:131]
	s_add_i32 m0, s2, 0x2000
	s_nop 0
	global_load_lds_dwordx4 v[140:141], off
	s_waitcnt vmcnt(6)
	s_barrier
	v_mfma_f32_16x16x32_bf16 v[50:53], v[228:231], v[160:163], v[50:53]
	v_mfma_f32_16x16x32_bf16 v[42:45], v[236:239], v[160:163], v[42:45]
	v_mfma_f32_16x16x32_bf16 v[34:37], v[228:231], v[192:195], v[34:37]
	v_mfma_f32_16x16x32_bf16 v[26:29], v[236:239], v[192:195], v[26:29]
	v_mfma_f32_16x16x32_bf16 v[18:21], v[228:231], v[200:203], v[18:21]
	v_mfma_f32_16x16x32_bf16 v[10:13], v[236:239], v[200:203], v[10:13]
	v_mfma_f32_16x16x32_bf16 v[6:9], v[228:231], v[220:223], v[6:9]
	v_mfma_f32_16x16x32_bf16 v[2:5], v[236:239], v[220:223], v[2:5]
	v_mfma_f32_16x16x32_bf16 v[50:53], v[232:235], v[188:191], v[50:53]
	v_mfma_f32_16x16x32_bf16 v[42:45], v[240:243], v[188:191], v[42:45]
	v_mfma_f32_16x16x32_bf16 v[34:37], v[232:235], v[196:199], v[34:37]
	v_mfma_f32_16x16x32_bf16 v[26:29], v[240:243], v[196:199], v[26:29]
	v_mfma_f32_16x16x32_bf16 v[18:21], v[232:235], v[216:219], v[18:21]
	v_mfma_f32_16x16x32_bf16 v[10:13], v[240:243], v[216:219], v[10:13]
	v_mfma_f32_16x16x32_bf16 v[6:9], v[232:235], v[224:227], v[6:9]
	v_mfma_f32_16x16x32_bf16 v[2:5], v[240:243], v[224:227], v[2:5]
	s_add_i32 s2, 0, 0x18000
	v_add_u32_e32 v156, s2, v145
	s_barrier
	ds_read_b128 v[140:143], v156
	ds_read_b128 v[148:151], v156 offset:1024
	ds_read_b128 v[152:155], v156 offset:2048
	ds_read_b128 v[156:159], v156 offset:3072
	s_add_u32 s26, s80, 0x20000
	s_addc_u32 s27, s81, 0
	s_mov_b32 m0, s70
	v_lshl_add_u64 v[228:229], s[26:27], 0, v[134:135]
	ds_read_b128 v[160:163], v147 offset:32768
	ds_read_b128 v[188:191], v147 offset:33792
	ds_read_b128 v[192:195], v147 offset:34816
	ds_read_b128 v[196:199], v147 offset:35840
	ds_read_b128 v[200:203], v147 offset:36864
	ds_read_b128 v[216:219], v147 offset:37888
	ds_read_b128 v[220:223], v147 offset:38912
	ds_read_b128 v[224:227], v147 offset:39936
	global_load_lds_dwordx4 v[228:229], off
	v_lshl_add_u64 v[228:229], s[26:27], 0, v[132:133]
	s_mov_b32 m0, s71
	s_nop 0
	global_load_lds_dwordx4 v[228:229], off
	s_waitcnt lgkmcnt(8)
	s_barrier
	s_waitcnt lgkmcnt(0)
	s_waitcnt lgkmcnt(0)
	v_mfma_f32_16x16x32_bf16 v[126:129], v[140:143], v[160:163], v[126:129]
	v_mfma_f32_16x16x32_bf16 v[122:125], v[152:155], v[160:163], v[122:125]
	v_mfma_f32_16x16x32_bf16 v[110:113], v[140:143], v[192:195], v[110:113]
	v_mfma_f32_16x16x32_bf16 v[106:109], v[152:155], v[192:195], v[106:109]
	v_mfma_f32_16x16x32_bf16 v[94:97], v[140:143], v[200:203], v[94:97]
	v_mfma_f32_16x16x32_bf16 v[90:93], v[152:155], v[200:203], v[90:93]
	v_mfma_f32_16x16x32_bf16 v[78:81], v[140:143], v[220:223], v[78:81]
	v_mfma_f32_16x16x32_bf16 v[74:77], v[152:155], v[220:223], v[74:77]
	v_mfma_f32_16x16x32_bf16 v[126:129], v[148:151], v[188:191], v[126:129]
	v_mfma_f32_16x16x32_bf16 v[122:125], v[156:159], v[188:191], v[122:125]
	v_mfma_f32_16x16x32_bf16 v[110:113], v[148:151], v[196:199], v[110:113]
	v_mfma_f32_16x16x32_bf16 v[106:109], v[156:159], v[196:199], v[106:109]
	v_mfma_f32_16x16x32_bf16 v[94:97], v[148:151], v[216:219], v[94:97]
	v_mfma_f32_16x16x32_bf16 v[90:93], v[156:159], v[216:219], v[90:93]
	v_mfma_f32_16x16x32_bf16 v[78:81], v[148:151], v[224:227], v[78:81]
	v_mfma_f32_16x16x32_bf16 v[74:77], v[156:159], v[224:227], v[74:77]
	s_barrier
	s_add_i32 s17, 0, 0x1c000
	s_add_i32 s2, s2, s3
	v_add_u32_e32 v206, s17, v145
	v_lshl_add_u64 v[164:165], v[164:165], 0, s[28:29]
	s_mov_b32 m0, s2
	ds_read_b128 v[228:231], v206
	ds_read_b128 v[232:235], v206 offset:1024
	ds_read_b128 v[236:239], v206 offset:2048
	ds_read_b128 v[240:243], v206 offset:3072
	global_load_lds_dwordx4 v[164:165], off
	v_lshl_add_u64 v[164:165], v[204:205], 0, s[28:29]
	s_add_i32 m0, s2, 0x2000
	s_nop 0
	global_load_lds_dwordx4 v[164:165], off
	s_barrier
	s_waitcnt lgkmcnt(0)
	s_waitcnt lgkmcnt(0)
	v_mfma_f32_16x16x32_bf16 v[118:121], v[228:231], v[160:163], v[118:121]
	v_mfma_f32_16x16x32_bf16 v[114:117], v[236:239], v[160:163], v[114:117]
	v_mfma_f32_16x16x32_bf16 v[102:105], v[228:231], v[192:195], v[102:105]
	v_mfma_f32_16x16x32_bf16 v[98:101], v[236:239], v[192:195], v[98:101]
	v_mfma_f32_16x16x32_bf16 v[86:89], v[228:231], v[200:203], v[86:89]
	v_mfma_f32_16x16x32_bf16 v[82:85], v[236:239], v[200:203], v[82:85]
	v_mfma_f32_16x16x32_bf16 v[70:73], v[228:231], v[220:223], v[70:73]
	v_mfma_f32_16x16x32_bf16 v[66:69], v[236:239], v[220:223], v[66:69]
	v_mfma_f32_16x16x32_bf16 v[118:121], v[232:235], v[188:191], v[118:121]
	v_mfma_f32_16x16x32_bf16 v[114:117], v[240:243], v[188:191], v[114:117]
	v_mfma_f32_16x16x32_bf16 v[102:105], v[232:235], v[196:199], v[102:105]
	v_mfma_f32_16x16x32_bf16 v[98:101], v[240:243], v[196:199], v[98:101]
	v_mfma_f32_16x16x32_bf16 v[86:89], v[232:235], v[216:219], v[86:89]
	v_mfma_f32_16x16x32_bf16 v[82:85], v[240:243], v[216:219], v[82:85]
	v_mfma_f32_16x16x32_bf16 v[70:73], v[232:235], v[224:227], v[70:73]
	v_mfma_f32_16x16x32_bf16 v[66:69], v[240:243], v[224:227], v[66:69]
	s_mov_b32 m0, s72
	v_lshl_add_u64 v[164:165], v[244:245], 0, s[28:29]
	s_barrier
	ds_read_b128 v[160:163], v147 offset:49152
	ds_read_b128 v[188:191], v147 offset:50176
	ds_read_b128 v[192:195], v147 offset:51200
	ds_read_b128 v[196:199], v147 offset:52224
	ds_read_b128 v[200:203], v147 offset:53248
	ds_read_b128 v[216:219], v147 offset:54272
	ds_read_b128 v[220:223], v147 offset:55296
	ds_read_b128 v[224:227], v147 offset:56320
	global_load_lds_dwordx4 v[164:165], off
	v_lshl_add_u64 v[164:165], v[246:247], 0, s[28:29]
	s_mov_b32 m0, s73
	s_nop 0
	global_load_lds_dwordx4 v[164:165], off
	s_barrier
	s_waitcnt lgkmcnt(0)
	s_waitcnt lgkmcnt(0)
	v_mfma_f32_16x16x32_bf16 v[62:65], v[140:143], v[160:163], v[62:65]
	v_mfma_f32_16x16x32_bf16 v[58:61], v[152:155], v[160:163], v[58:61]
	v_mfma_f32_16x16x32_bf16 v[54:57], v[140:143], v[192:195], v[54:57]
	v_mfma_f32_16x16x32_bf16 v[46:49], v[152:155], v[192:195], v[46:49]
	v_mfma_f32_16x16x32_bf16 v[38:41], v[140:143], v[200:203], v[38:41]
	v_mfma_f32_16x16x32_bf16 v[30:33], v[152:155], v[200:203], v[30:33]
	v_mfma_f32_16x16x32_bf16 v[22:25], v[140:143], v[220:223], v[22:25]
	v_mfma_f32_16x16x32_bf16 v[14:17], v[152:155], v[220:223], v[14:17]
	v_mfma_f32_16x16x32_bf16 v[62:65], v[148:151], v[188:191], v[62:65]
	v_mfma_f32_16x16x32_bf16 v[58:61], v[156:159], v[188:191], v[58:61]
	v_mfma_f32_16x16x32_bf16 v[54:57], v[148:151], v[196:199], v[54:57]
	v_mfma_f32_16x16x32_bf16 v[46:49], v[156:159], v[196:199], v[46:49]
	v_mfma_f32_16x16x32_bf16 v[38:41], v[148:151], v[216:219], v[38:41]
	v_mfma_f32_16x16x32_bf16 v[30:33], v[156:159], v[216:219], v[30:33]
	v_mfma_f32_16x16x32_bf16 v[22:25], v[148:151], v[224:227], v[22:25]
	v_mfma_f32_16x16x32_bf16 v[14:17], v[156:159], v[224:227], v[14:17]
	s_barrier
	s_add_u32 s26, s78, 0xd0080
	s_addc_u32 s27, s79, 0
	s_add_i32 s2, s17, s3
	v_lshl_add_u64 v[140:141], s[26:27], 0, v[0:1]
	s_mov_b32 m0, s2
	s_nop 0
	global_load_lds_dwordx4 v[140:141], off
	v_lshl_add_u64 v[140:141], s[26:27], 0, v[130:131]
	s_add_i32 m0, s2, 0x2000
	s_nop 0
	global_load_lds_dwordx4 v[140:141], off
	s_waitcnt vmcnt(6)
	s_barrier
	v_mfma_f32_16x16x32_bf16 v[50:53], v[228:231], v[160:163], v[50:53]
	v_mfma_f32_16x16x32_bf16 v[42:45], v[236:239], v[160:163], v[42:45]
	v_mfma_f32_16x16x32_bf16 v[34:37], v[228:231], v[192:195], v[34:37]
	v_mfma_f32_16x16x32_bf16 v[26:29], v[236:239], v[192:195], v[26:29]
	v_mfma_f32_16x16x32_bf16 v[18:21], v[228:231], v[200:203], v[18:21]
	v_mfma_f32_16x16x32_bf16 v[10:13], v[236:239], v[200:203], v[10:13]
	v_mfma_f32_16x16x32_bf16 v[6:9], v[228:231], v[220:223], v[6:9]
	v_mfma_f32_16x16x32_bf16 v[2:5], v[236:239], v[220:223], v[2:5]
	v_mfma_f32_16x16x32_bf16 v[50:53], v[232:235], v[188:191], v[50:53]
	v_mfma_f32_16x16x32_bf16 v[42:45], v[240:243], v[188:191], v[42:45]
	v_mfma_f32_16x16x32_bf16 v[34:37], v[232:235], v[196:199], v[34:37]
	v_mfma_f32_16x16x32_bf16 v[26:29], v[240:243], v[196:199], v[26:29]
	v_mfma_f32_16x16x32_bf16 v[18:21], v[232:235], v[216:219], v[18:21]
	v_mfma_f32_16x16x32_bf16 v[10:13], v[240:243], v[216:219], v[10:13]
	v_mfma_f32_16x16x32_bf16 v[6:9], v[232:235], v[224:227], v[6:9]
	v_mfma_f32_16x16x32_bf16 v[2:5], v[240:243], v[224:227], v[2:5]
	s_add_i32 s44, s44, 2
	s_add_u32 s6, s6, 0x100
	s_addc_u32 s7, s7, 0
	s_add_u32 s25, s25, 0x100
	s_addc_u32 s46, s46, 0
	s_cmp_gt_u32 s44, 5
	s_barrier
	s_cbranch_scc0 .LBB0_500
	v_lshl_or_b32 v156, s62, 8, v146
	v_ashrrev_i32_e32 v157, 31, v156
	v_lshl_add_u64 v[140:141], v[156:157], 2, s[38:39]
	global_load_dwordx4 v[200:203], v[140:141], off offset:16
	global_load_dwordx4 v[220:223], v[140:141], off
	global_load_dwordx4 v[228:231], v[140:141], off offset:528
	global_load_dwordx4 v[236:239], v[140:141], off offset:512
	v_lshl_add_u32 v142, s63, 8, v144
	v_ashrrev_i32_e32 v143, 31, v142
	s_mov_b32 s2, 0x400000
	s_mov_b64 s[6:7], 0x400000
	s_mov_b32 s62, s41
	s_mov_b32 s63, s10
	s_mov_b64 s[78:79], s[74:75]
	s_mov_b64 s[80:81], s[76:77]
	s_waitcnt vmcnt(0)
	v_mov_b32_e32 v148, v200
	v_mov_b32_e32 v149, v201
	v_mov_b32_e32 v150, v202
	v_mov_b32_e32 v151, v203
	v_mov_b32_e32 v152, v220
	v_mov_b32_e32 v153, v221
	v_mov_b32_e32 v154, v222
	v_mov_b32_e32 v155, v223
	v_pk_mul_f32 v[122:123], v[122:123], v[148:149]
	v_pk_mul_f32 v[126:127], v[126:127], v[152:153]
	v_pk_mul_f32 v[124:125], v[124:125], v[150:151]
	v_cvt_pk_bf16_f32 v150, v122, v123
	v_lshlrev_b64 v[122:123], 15, v[142:143]
	v_pk_mul_f32 v[128:129], v[128:129], v[154:155]
	v_cvt_pk_bf16_f32 v148, v126, v127
	v_cvt_pk_bf16_f32 v151, v124, v125
	v_lshl_add_u64 v[122:123], s[60:61], 0, v[122:123]
	v_lshlrev_b64 v[126:127], 1, v[156:157]
	v_or_b32_e32 v124, 0x80, v156
	v_cvt_pk_bf16_f32 v149, v128, v129
	v_lshl_add_u64 v[122:123], v[122:123], 0, v[126:127]
	v_ashrrev_i32_e32 v125, 31, v124
	global_store_dwordx4 v[122:123], v[148:151], off
	v_lshl_add_u64 v[124:125], v[124:125], 2, s[38:39]
	s_nop 1
	v_mov_b32_e32 v148, v228
	v_mov_b32_e32 v149, v229
	v_mov_b32_e32 v150, v230
	v_mov_b32_e32 v151, v231
	s_nop 1
	v_mov_b32_e32 v152, v236
	v_mov_b32_e32 v153, v237
	v_mov_b32_e32 v154, v238
	v_mov_b32_e32 v155, v239
	s_nop 0
	v_pk_mul_f32 v[128:129], v[116:117], v[150:151]
	v_pk_mul_f32 v[120:121], v[120:121], v[154:155]
	v_pk_mul_f32 v[118:119], v[118:119], v[152:153]
	v_pk_mul_f32 v[116:117], v[114:115], v[148:149]
	v_cvt_pk_bf16_f32 v114, v118, v119
	v_cvt_pk_bf16_f32 v115, v120, v121
	v_cvt_pk_bf16_f32 v116, v116, v117
	v_cvt_pk_bf16_f32 v117, v128, v129
	global_store_dwordx4 v[122:123], v[114:117], off offset:256
	s_nop 1
	v_mov_b32_e32 v114, v200
	v_mov_b32_e32 v115, v201
	v_mov_b32_e32 v116, v202
	v_mov_b32_e32 v117, v203
	s_nop 0
	s_nop 1
	v_mov_b32_e32 v118, v220
	v_mov_b32_e32 v119, v221
	v_mov_b32_e32 v120, v222
	v_mov_b32_e32 v121, v223
	v_or_b32_e32 v128, 16, v142
	v_ashrrev_i32_e32 v129, 31, v128
	s_nop 0
	v_pk_mul_f32 v[116:117], v[108:109], v[116:117]
	v_pk_mul_f32 v[110:111], v[110:111], v[118:119]
	v_pk_mul_f32 v[108:109], v[106:107], v[114:115]
	v_cvt_pk_bf16_f32 v106, v110, v111
	v_lshlrev_b64 v[110:111], 15, v[128:129]
	v_pk_mul_f32 v[112:113], v[112:113], v[120:121]
	v_lshl_add_u64 v[110:111], s[60:61], 0, v[110:111]
	v_cvt_pk_bf16_f32 v107, v112, v113
	v_cvt_pk_bf16_f32 v108, v108, v109
	v_cvt_pk_bf16_f32 v109, v116, v117
	v_lshl_add_u64 v[114:115], v[110:111], 0, v[126:127]
	global_store_dwordx4 v[114:115], v[106:109], off
	s_nop 1
	v_mov_b32_e32 v106, v228
	v_mov_b32_e32 v107, v229
	v_mov_b32_e32 v108, v230
	v_mov_b32_e32 v109, v231
	s_nop 0
	s_nop 1
	v_mov_b32_e32 v110, v236
	v_mov_b32_e32 v111, v237
	v_mov_b32_e32 v112, v238
	v_mov_b32_e32 v113, v239
	s_nop 0
	v_pk_mul_f32 v[108:109], v[100:101], v[108:109]
	v_pk_mul_f32 v[104:105], v[104:105], v[112:113]
	v_pk_mul_f32 v[102:103], v[102:103], v[110:111]
	v_pk_mul_f32 v[100:101], v[98:99], v[106:107]
	v_cvt_pk_bf16_f32 v98, v102, v103
	v_cvt_pk_bf16_f32 v99, v104, v105
	v_cvt_pk_bf16_f32 v100, v100, v101
	v_cvt_pk_bf16_f32 v101, v108, v109
	global_store_dwordx4 v[114:115], v[98:101], off offset:256
	s_nop 1
	v_mov_b32_e32 v98, v200
	v_mov_b32_e32 v99, v201
	v_mov_b32_e32 v100, v202
	v_mov_b32_e32 v101, v203
	s_nop 0
	s_nop 1
	v_mov_b32_e32 v102, v220
	v_mov_b32_e32 v103, v221
	v_mov_b32_e32 v104, v222
	v_mov_b32_e32 v105, v223
	v_or_b32_e32 v106, 32, v142
	v_ashrrev_i32_e32 v107, 31, v106
	s_nop 0
	v_pk_mul_f32 v[100:101], v[92:93], v[100:101]
	v_pk_mul_f32 v[94:95], v[94:95], v[102:103]
	v_pk_mul_f32 v[92:93], v[90:91], v[98:99]
	v_cvt_pk_bf16_f32 v90, v94, v95
	v_lshlrev_b64 v[94:95], 15, v[106:107]
	v_pk_mul_f32 v[96:97], v[96:97], v[104:105]
	v_lshl_add_u64 v[94:95], s[60:61], 0, v[94:95]
	v_cvt_pk_bf16_f32 v91, v96, v97
	v_cvt_pk_bf16_f32 v92, v92, v93
	v_cvt_pk_bf16_f32 v93, v100, v101
	v_lshl_add_u64 v[98:99], v[94:95], 0, v[126:127]
	global_store_dwordx4 v[98:99], v[90:93], off
	s_nop 1
	v_mov_b32_e32 v90, v228
	v_mov_b32_e32 v91, v229
	v_mov_b32_e32 v92, v230
	v_mov_b32_e32 v93, v231
	s_nop 0
	s_nop 1
	v_mov_b32_e32 v94, v236
	v_mov_b32_e32 v95, v237
	v_mov_b32_e32 v96, v238
	v_mov_b32_e32 v97, v239
	s_nop 0
	v_pk_mul_f32 v[92:93], v[84:85], v[92:93]
	v_pk_mul_f32 v[88:89], v[88:89], v[96:97]
	v_pk_mul_f32 v[86:87], v[86:87], v[94:95]
	v_pk_mul_f32 v[84:85], v[82:83], v[90:91]
	v_cvt_pk_bf16_f32 v82, v86, v87
	v_cvt_pk_bf16_f32 v83, v88, v89
	v_cvt_pk_bf16_f32 v84, v84, v85
	v_cvt_pk_bf16_f32 v85, v92, v93
	global_store_dwordx4 v[98:99], v[82:85], off offset:256
	s_nop 1
	v_mov_b32_e32 v82, v200
	v_mov_b32_e32 v83, v201
	v_mov_b32_e32 v84, v202
	v_mov_b32_e32 v85, v203
	s_nop 0
	s_nop 1
	v_mov_b32_e32 v86, v220
	v_mov_b32_e32 v87, v221
	v_mov_b32_e32 v88, v222
	v_mov_b32_e32 v89, v223
	v_or_b32_e32 v90, 48, v142
	v_ashrrev_i32_e32 v91, 31, v90
	s_nop 0
	v_pk_mul_f32 v[84:85], v[76:77], v[84:85]
	v_pk_mul_f32 v[78:79], v[78:79], v[86:87]
	v_pk_mul_f32 v[76:77], v[74:75], v[82:83]
	v_cvt_pk_bf16_f32 v74, v78, v79
	v_lshlrev_b64 v[78:79], 15, v[90:91]
	v_pk_mul_f32 v[80:81], v[80:81], v[88:89]
	v_lshl_add_u64 v[78:79], s[60:61], 0, v[78:79]
	v_cvt_pk_bf16_f32 v75, v80, v81
	v_cvt_pk_bf16_f32 v76, v76, v77
	v_cvt_pk_bf16_f32 v77, v84, v85
	v_lshl_add_u64 v[82:83], v[78:79], 0, v[126:127]
	global_store_dwordx4 v[82:83], v[74:77], off
	s_nop 1
	v_mov_b32_e32 v74, v228
	v_mov_b32_e32 v75, v229
	v_mov_b32_e32 v76, v230
	v_mov_b32_e32 v77, v231
	s_nop 0
	s_nop 1
	v_mov_b32_e32 v78, v236
	v_mov_b32_e32 v79, v237
	v_mov_b32_e32 v80, v238
	v_mov_b32_e32 v81, v239
	s_nop 0
	v_pk_mul_f32 v[76:77], v[68:69], v[76:77]
	v_pk_mul_f32 v[72:73], v[72:73], v[80:81]
	v_pk_mul_f32 v[70:71], v[70:71], v[78:79]
	v_pk_mul_f32 v[68:69], v[66:67], v[74:75]
	v_cvt_pk_bf16_f32 v66, v70, v71
	v_cvt_pk_bf16_f32 v67, v72, v73
	v_cvt_pk_bf16_f32 v68, v68, v69
	v_cvt_pk_bf16_f32 v69, v76, v77
	global_store_dwordx4 v[82:83], v[66:69], off offset:256
	s_nop 1
	v_mov_b32_e32 v66, v200
	v_mov_b32_e32 v67, v201
	v_mov_b32_e32 v68, v202
	v_mov_b32_e32 v69, v203
	s_nop 0
	s_nop 1
	v_mov_b32_e32 v70, v220
	v_mov_b32_e32 v71, v221
	v_mov_b32_e32 v72, v222
	v_mov_b32_e32 v73, v223
	s_nop 0
	v_pk_mul_f32 v[68:69], v[60:61], v[68:69]
	v_pk_mul_f32 v[62:63], v[62:63], v[70:71]
	v_pk_mul_f32 v[64:65], v[64:65], v[72:73]
	v_pk_mul_f32 v[60:61], v[58:59], v[66:67]
	v_cvt_pk_bf16_f32 v58, v62, v63
	v_add_co_u32_e32 v62, vcc, s2, v122
	v_cvt_pk_bf16_f32 v59, v64, v65
	v_cvt_pk_bf16_f32 v60, v60, v61
	v_cvt_pk_bf16_f32 v61, v68, v69
	v_addc_co_u32_e32 v63, vcc, 0, v123, vcc
	global_store_dwordx4 v[62:63], v[58:61], off
	s_nop 1
	v_mov_b32_e32 v58, v228
	v_mov_b32_e32 v59, v229
	v_mov_b32_e32 v60, v230
	v_mov_b32_e32 v61, v231
	s_nop 0
	s_nop 1
	v_mov_b32_e32 v62, v236
	v_mov_b32_e32 v63, v237
	v_mov_b32_e32 v64, v238
	v_mov_b32_e32 v65, v239
	v_lshl_add_u64 v[66:67], v[122:123], 0, s[6:7]
	s_mov_b32 s2, 0x480000
	s_mov_b64 s[6:7], 0x480000
	s_nop 0
	v_pk_mul_f32 v[60:61], v[44:45], v[60:61]
	v_pk_mul_f32 v[52:53], v[52:53], v[64:65]
	v_pk_mul_f32 v[50:51], v[50:51], v[62:63]
	v_pk_mul_f32 v[44:45], v[42:43], v[58:59]
	v_cvt_pk_bf16_f32 v42, v50, v51
	v_cvt_pk_bf16_f32 v43, v52, v53
	v_cvt_pk_bf16_f32 v44, v44, v45
	v_cvt_pk_bf16_f32 v45, v60, v61
	global_store_dwordx4 v[66:67], v[42:45], off offset:256
	s_nop 1
	v_mov_b32_e32 v42, v200
	v_mov_b32_e32 v43, v201
	v_mov_b32_e32 v44, v202
	v_mov_b32_e32 v45, v203
	s_nop 0
	s_nop 1
	v_mov_b32_e32 v50, v220
	v_mov_b32_e32 v51, v221
	v_mov_b32_e32 v52, v222
	v_mov_b32_e32 v53, v223
	s_nop 0
	v_pk_mul_f32 v[48:49], v[48:49], v[44:45]
	v_pk_mul_f32 v[52:53], v[56:57], v[52:53]
	v_pk_mul_f32 v[50:51], v[54:55], v[50:51]
	v_pk_mul_f32 v[44:45], v[46:47], v[42:43]
	v_add_co_u32_e32 v46, vcc, s2, v122
	v_cvt_pk_bf16_f32 v42, v50, v51
	v_cvt_pk_bf16_f32 v43, v52, v53
	v_cvt_pk_bf16_f32 v44, v44, v45
	v_cvt_pk_bf16_f32 v45, v48, v49
	v_addc_co_u32_e32 v47, vcc, 0, v123, vcc
	global_store_dwordx4 v[46:47], v[42:45], off
	s_nop 1
	v_mov_b32_e32 v42, v228
	v_mov_b32_e32 v43, v229
	v_mov_b32_e32 v44, v230
	v_mov_b32_e32 v45, v231
	s_nop 0
	s_nop 1
	v_mov_b32_e32 v46, v236
	v_mov_b32_e32 v47, v237
	v_mov_b32_e32 v48, v238
	v_mov_b32_e32 v49, v239
	v_lshl_add_u64 v[50:51], v[122:123], 0, s[6:7]
	s_mov_b32 s2, 0x500000
	s_mov_b64 s[6:7], 0x500000
	s_nop 0
	v_pk_mul_f32 v[44:45], v[28:29], v[44:45]
	v_pk_mul_f32 v[36:37], v[36:37], v[48:49]
	v_pk_mul_f32 v[34:35], v[34:35], v[46:47]
	v_pk_mul_f32 v[28:29], v[26:27], v[42:43]
	v_cvt_pk_bf16_f32 v26, v34, v35
	v_cvt_pk_bf16_f32 v27, v36, v37
	v_cvt_pk_bf16_f32 v28, v28, v29
	v_cvt_pk_bf16_f32 v29, v44, v45
	global_store_dwordx4 v[50:51], v[26:29], off offset:256
	s_nop 1
	v_mov_b32_e32 v26, v200
	v_mov_b32_e32 v27, v201
	v_mov_b32_e32 v28, v202
	v_mov_b32_e32 v29, v203
	s_nop 0
	s_nop 1
	v_mov_b32_e32 v34, v220
	v_mov_b32_e32 v35, v221
	v_mov_b32_e32 v36, v222
	v_mov_b32_e32 v37, v223
	s_nop 0
	v_pk_mul_f32 v[32:33], v[32:33], v[28:29]
	v_pk_mul_f32 v[36:37], v[40:41], v[36:37]
	v_pk_mul_f32 v[34:35], v[38:39], v[34:35]
	v_pk_mul_f32 v[28:29], v[30:31], v[26:27]
	v_add_co_u32_e32 v30, vcc, s2, v122
	v_cvt_pk_bf16_f32 v26, v34, v35
	v_cvt_pk_bf16_f32 v27, v36, v37
	v_cvt_pk_bf16_f32 v28, v28, v29
	v_cvt_pk_bf16_f32 v29, v32, v33
	v_addc_co_u32_e32 v31, vcc, 0, v123, vcc
	global_store_dwordx4 v[30:31], v[26:29], off
	s_nop 1
	v_mov_b32_e32 v26, v228
	v_mov_b32_e32 v27, v229
	v_mov_b32_e32 v28, v230
	v_mov_b32_e32 v29, v231
	s_nop 0
	s_nop 1
	v_mov_b32_e32 v30, v236
	v_mov_b32_e32 v31, v237
	v_mov_b32_e32 v32, v238
	v_mov_b32_e32 v33, v239
	v_lshl_add_u64 v[34:35], v[122:123], 0, s[6:7]
	s_mov_b32 s2, 0x580000
	s_mov_b64 s[6:7], 0x580000
	s_nop 0
	v_pk_mul_f32 v[28:29], v[12:13], v[28:29]
	v_pk_mul_f32 v[20:21], v[20:21], v[32:33]
	v_pk_mul_f32 v[18:19], v[18:19], v[30:31]
	v_pk_mul_f32 v[12:13], v[10:11], v[26:27]
	v_cvt_pk_bf16_f32 v10, v18, v19
	v_cvt_pk_bf16_f32 v11, v20, v21
	v_cvt_pk_bf16_f32 v12, v12, v13
	v_cvt_pk_bf16_f32 v13, v28, v29
	global_store_dwordx4 v[34:35], v[10:13], off offset:256
	s_nop 1
	v_mov_b32_e32 v10, v200
	v_mov_b32_e32 v11, v201
	v_mov_b32_e32 v12, v202
	v_mov_b32_e32 v13, v203
	s_nop 0
	s_nop 1
	v_mov_b32_e32 v18, v220
	v_mov_b32_e32 v19, v221
	v_mov_b32_e32 v20, v222
	v_mov_b32_e32 v21, v223
	s_nop 0
	v_pk_mul_f32 v[16:17], v[16:17], v[12:13]
	v_pk_mul_f32 v[20:21], v[24:25], v[20:21]
	v_pk_mul_f32 v[18:19], v[22:23], v[18:19]
	v_pk_mul_f32 v[12:13], v[14:15], v[10:11]
	v_add_co_u32_e32 v14, vcc, s2, v122
	v_cvt_pk_bf16_f32 v10, v18, v19
	v_cvt_pk_bf16_f32 v11, v20, v21
	v_cvt_pk_bf16_f32 v12, v12, v13
	v_cvt_pk_bf16_f32 v13, v16, v17
	v_addc_co_u32_e32 v15, vcc, 0, v123, vcc
	global_store_dwordx4 v[14:15], v[10:13], off
	s_nop 1
	v_mov_b32_e32 v10, v228
	v_mov_b32_e32 v11, v229
	v_mov_b32_e32 v12, v230
	v_mov_b32_e32 v13, v231
	s_nop 0
	s_nop 1
	v_mov_b32_e32 v14, v236
	v_mov_b32_e32 v15, v237
	v_mov_b32_e32 v16, v238
	v_mov_b32_e32 v17, v239
	v_lshl_add_u64 v[18:19], v[122:123], 0, s[6:7]
	s_and_b64 vcc, exec, s[0:1]
	s_nop 0
	v_pk_mul_f32 v[12:13], v[4:5], v[12:13]
	v_pk_mul_f32 v[8:9], v[8:9], v[16:17]
	v_pk_mul_f32 v[6:7], v[6:7], v[14:15]
	v_pk_mul_f32 v[4:5], v[2:3], v[10:11]
	v_cvt_pk_bf16_f32 v2, v6, v7
	v_cvt_pk_bf16_f32 v3, v8, v9
	v_cvt_pk_bf16_f32 v4, v4, v5
	v_cvt_pk_bf16_f32 v5, v12, v13
	global_store_dwordx4 v[18:19], v[2:5], off offset:256
	s_cbranch_vccz .LBB0_491
	v_readlane_b32 s0, v254, 12
	s_waitcnt vmcnt(0)
	v_readlane_b32 s1, v254, 13
	v_readlane_b32 s84, v251, 38
	v_readlane_b32 s18, v253, 0
	s_andn2_b64 vcc, exec, s[0:1]
	v_readlane_b32 s85, v251, 39
	v_readlane_b32 s86, v251, 40
	v_readlane_b32 s87, v251, 41
	v_readlane_b32 s14, v250, 63
	v_readlane_b32 s19, v253, 1
	s_cbranch_vccnz .LBB0_504
	s_barrier

.LBB0_655:
	s_add_u32 s2, s68, 0xfff80080
	s_addc_u32 s17, s69, -1
	s_add_i32 s26, 0, 0x10000
	v_add_u32_e32 v156, s26, v141
	ds_read_b128 v[144:147], v156
	ds_read_b128 v[148:151], v156 offset:1024
	ds_read_b128 v[152:155], v156 offset:2048
	ds_read_b128 v[156:159], v156 offset:3072
	s_cmp_eq_u32 s44, 28
	s_cselect_b32 s73, s55, s17
	s_cselect_b32 s72, s83, s2
	s_cselect_b32 s71, s24, s92
	s_cselect_b32 s70, s25, s43
	v_lshl_add_u64 v[164:165], s[68:69], 0, v[136:137]
	s_add_i32 m0, s58, 0xc000
	ds_read_b128 v[160:163], v143
	ds_read_b128 v[188:191], v143 offset:1024
	ds_read_b128 v[192:195], v143 offset:2048
	ds_read_b128 v[196:199], v143 offset:3072
	ds_read_b128 v[200:203], v143 offset:4096
	ds_read_b128 v[216:219], v143 offset:5120
	ds_read_b128 v[220:223], v143 offset:6144
	ds_read_b128 v[224:227], v143 offset:7168
	global_load_lds_dwordx4 v[164:165], off
	v_lshl_add_u64 v[164:165], s[68:69], 0, v[138:139]
	s_add_i32 m0, s58, 0xe000
	s_nop 0
	global_load_lds_dwordx4 v[164:165], off
	s_waitcnt lgkmcnt(8)
	s_barrier
	s_waitcnt lgkmcnt(0)
	s_waitcnt lgkmcnt(0)
	v_mfma_f32_16x16x32_bf16 v[126:129], v[144:147], v[160:163], v[126:129]
	v_mfma_f32_16x16x32_bf16 v[122:125], v[152:155], v[160:163], v[122:125]
	v_mfma_f32_16x16x32_bf16 v[118:121], v[144:147], v[192:195], v[118:121]
	v_mfma_f32_16x16x32_bf16 v[114:117], v[152:155], v[192:195], v[114:117]
	v_mfma_f32_16x16x32_bf16 v[102:105], v[144:147], v[200:203], v[102:105]
	v_mfma_f32_16x16x32_bf16 v[98:101], v[152:155], v[200:203], v[98:101]
	v_mfma_f32_16x16x32_bf16 v[86:89], v[144:147], v[220:223], v[86:89]
	v_mfma_f32_16x16x32_bf16 v[82:85], v[152:155], v[220:223], v[82:85]
	v_mfma_f32_16x16x32_bf16 v[126:129], v[148:151], v[188:191], v[126:129]
	v_mfma_f32_16x16x32_bf16 v[122:125], v[156:159], v[188:191], v[122:125]
	v_mfma_f32_16x16x32_bf16 v[118:121], v[148:151], v[196:199], v[118:121]
	v_mfma_f32_16x16x32_bf16 v[114:117], v[156:159], v[196:199], v[114:117]
	v_mfma_f32_16x16x32_bf16 v[102:105], v[148:151], v[216:219], v[102:105]
	v_mfma_f32_16x16x32_bf16 v[98:101], v[156:159], v[216:219], v[98:101]
	v_mfma_f32_16x16x32_bf16 v[86:89], v[148:151], v[224:227], v[86:89]
	v_mfma_f32_16x16x32_bf16 v[82:85], v[156:159], v[224:227], v[82:85]
	s_barrier
	s_add_i32 s2, 0, 0x14000
	v_add_u32_e32 v164, s2, v141
	s_add_i32 s17, s26, s3
	ds_read_b128 v[228:231], v164
	ds_read_b128 v[232:235], v164 offset:1024
	ds_read_b128 v[236:239], v164 offset:2048
	ds_read_b128 v[240:243], v164 offset:3072
	v_lshl_add_u64 v[164:165], s[70:71], 0, v[0:1]
	s_mov_b32 m0, s17
	v_lshl_add_u64 v[204:205], s[70:71], 0, v[130:131]
	global_load_lds_dwordx4 v[164:165], off
	s_add_i32 m0, s17, 0x2000
	s_nop 0
	global_load_lds_dwordx4 v[204:205], off
	s_barrier
	s_waitcnt lgkmcnt(0)
	s_waitcnt lgkmcnt(0)
	v_mfma_f32_16x16x32_bf16 v[110:113], v[228:231], v[160:163], v[110:113]
	v_mfma_f32_16x16x32_bf16 v[106:109], v[236:239], v[160:163], v[106:109]
	v_mfma_f32_16x16x32_bf16 v[94:97], v[228:231], v[192:195], v[94:97]
	v_mfma_f32_16x16x32_bf16 v[90:93], v[236:239], v[192:195], v[90:93]
	v_mfma_f32_16x16x32_bf16 v[78:81], v[228:231], v[200:203], v[78:81]
	v_mfma_f32_16x16x32_bf16 v[74:77], v[236:239], v[200:203], v[74:77]
	v_mfma_f32_16x16x32_bf16 v[70:73], v[228:231], v[220:223], v[70:73]
	v_mfma_f32_16x16x32_bf16 v[66:69], v[236:239], v[220:223], v[66:69]
	v_mfma_f32_16x16x32_bf16 v[110:113], v[232:235], v[188:191], v[110:113]
	v_mfma_f32_16x16x32_bf16 v[106:109], v[240:243], v[188:191], v[106:109]
	v_mfma_f32_16x16x32_bf16 v[94:97], v[232:235], v[196:199], v[94:97]
	v_mfma_f32_16x16x32_bf16 v[90:93], v[240:243], v[196:199], v[90:93]
	v_mfma_f32_16x16x32_bf16 v[78:81], v[232:235], v[216:219], v[78:81]
	v_mfma_f32_16x16x32_bf16 v[74:77], v[240:243], v[216:219], v[74:77]
	v_mfma_f32_16x16x32_bf16 v[70:73], v[232:235], v[224:227], v[70:73]
	v_mfma_f32_16x16x32_bf16 v[66:69], v[240:243], v[224:227], v[66:69]
	s_mov_b32 m0, s58
	v_lshl_add_u64 v[244:245], s[72:73], 0, v[134:135]
	s_barrier
	ds_read_b128 v[160:163], v143 offset:16384
	ds_read_b128 v[188:191], v143 offset:17408
	ds_read_b128 v[192:195], v143 offset:18432
	ds_read_b128 v[196:199], v143 offset:19456
	ds_read_b128 v[200:203], v143 offset:20480
	ds_read_b128 v[216:219], v143 offset:21504
	ds_read_b128 v[220:223], v143 offset:22528
	ds_read_b128 v[224:227], v143 offset:23552
	global_load_lds_dwordx4 v[244:245], off
	v_lshl_add_u64 v[246:247], s[72:73], 0, v[132:133]
	s_mov_b32 m0, s74
	s_nop 0
	global_load_lds_dwordx4 v[246:247], off
	s_barrier
	s_waitcnt lgkmcnt(0)
	s_waitcnt lgkmcnt(0)
	v_mfma_f32_16x16x32_bf16 v[62:65], v[144:147], v[160:163], v[62:65]
	v_mfma_f32_16x16x32_bf16 v[58:61], v[152:155], v[160:163], v[58:61]
	v_mfma_f32_16x16x32_bf16 v[54:57], v[144:147], v[192:195], v[54:57]
	v_mfma_f32_16x16x32_bf16 v[50:53], v[152:155], v[192:195], v[50:53]
	v_mfma_f32_16x16x32_bf16 v[38:41], v[144:147], v[200:203], v[38:41]
	v_mfma_f32_16x16x32_bf16 v[34:37], v[152:155], v[200:203], v[34:37]
	v_mfma_f32_16x16x32_bf16 v[22:25], v[144:147], v[220:223], v[22:25]
	v_mfma_f32_16x16x32_bf16 v[18:21], v[152:155], v[220:223], v[18:21]
	v_mfma_f32_16x16x32_bf16 v[62:65], v[148:151], v[188:191], v[62:65]
	v_mfma_f32_16x16x32_bf16 v[58:61], v[156:159], v[188:191], v[58:61]
	v_mfma_f32_16x16x32_bf16 v[54:57], v[148:151], v[196:199], v[54:57]
	v_mfma_f32_16x16x32_bf16 v[50:53], v[156:159], v[196:199], v[50:53]
	v_mfma_f32_16x16x32_bf16 v[38:41], v[148:151], v[216:219], v[38:41]
	v_mfma_f32_16x16x32_bf16 v[34:37], v[156:159], v[216:219], v[34:37]
	v_mfma_f32_16x16x32_bf16 v[22:25], v[148:151], v[224:227], v[22:25]
	v_mfma_f32_16x16x32_bf16 v[18:21], v[156:159], v[224:227], v[18:21]
	s_barrier
	s_add_u32 s26, s70, 0x80000
	s_addc_u32 s27, s71, 0
	s_add_i32 s2, s2, s3
	v_lshl_add_u64 v[144:145], s[26:27], 0, v[0:1]
	s_mov_b32 m0, s2
	s_nop 0
	global_load_lds_dwordx4 v[144:145], off
	v_lshl_add_u64 v[144:145], s[26:27], 0, v[130:131]
	s_add_i32 m0, s2, 0x2000
	s_nop 0
	global_load_lds_dwordx4 v[144:145], off
	s_waitcnt vmcnt(6)
	s_barrier
	v_mfma_f32_16x16x32_bf16 v[46:49], v[228:231], v[160:163], v[46:49]
	v_mfma_f32_16x16x32_bf16 v[42:45], v[236:239], v[160:163], v[42:45]
	v_mfma_f32_16x16x32_bf16 v[30:33], v[228:231], v[192:195], v[30:33]
	v_mfma_f32_16x16x32_bf16 v[26:29], v[236:239], v[192:195], v[26:29]
	v_mfma_f32_16x16x32_bf16 v[14:17], v[228:231], v[200:203], v[14:17]
	v_mfma_f32_16x16x32_bf16 v[10:13], v[236:239], v[200:203], v[10:13]
	v_mfma_f32_16x16x32_bf16 v[6:9], v[228:231], v[220:223], v[6:9]
	v_mfma_f32_16x16x32_bf16 v[2:5], v[236:239], v[220:223], v[2:5]
	v_mfma_f32_16x16x32_bf16 v[46:49], v[232:235], v[188:191], v[46:49]
	v_mfma_f32_16x16x32_bf16 v[42:45], v[240:243], v[188:191], v[42:45]
	v_mfma_f32_16x16x32_bf16 v[30:33], v[232:235], v[196:199], v[30:33]
	v_mfma_f32_16x16x32_bf16 v[26:29], v[240:243], v[196:199], v[26:29]
	v_mfma_f32_16x16x32_bf16 v[14:17], v[232:235], v[216:219], v[14:17]
	v_mfma_f32_16x16x32_bf16 v[10:13], v[240:243], v[216:219], v[10:13]
	v_mfma_f32_16x16x32_bf16 v[6:9], v[232:235], v[224:227], v[6:9]
	v_mfma_f32_16x16x32_bf16 v[2:5], v[240:243], v[224:227], v[2:5]
	s_add_i32 s2, 0, 0x18000
	v_add_u32_e32 v156, s2, v141
	s_barrier
	ds_read_b128 v[144:147], v156
	ds_read_b128 v[148:151], v156 offset:1024
	ds_read_b128 v[152:155], v156 offset:2048
	ds_read_b128 v[156:159], v156 offset:3072
	s_add_u32 s26, s72, 0x80000
	s_addc_u32 s27, s73, 0
	s_mov_b32 m0, s75
	v_lshl_add_u64 v[228:229], s[26:27], 0, v[134:135]
	ds_read_b128 v[160:163], v143 offset:32768
	ds_read_b128 v[188:191], v143 offset:33792
	ds_read_b128 v[192:195], v143 offset:34816
	ds_read_b128 v[196:199], v143 offset:35840
	ds_read_b128 v[200:203], v143 offset:36864
	ds_read_b128 v[216:219], v143 offset:37888
	ds_read_b128 v[220:223], v143 offset:38912
	ds_read_b128 v[224:227], v143 offset:39936
	global_load_lds_dwordx4 v[228:229], off
	v_lshl_add_u64 v[228:229], s[26:27], 0, v[132:133]
	s_mov_b32 m0, s79
	s_nop 0
	global_load_lds_dwordx4 v[228:229], off
	s_waitcnt lgkmcnt(8)
	s_barrier
	s_waitcnt lgkmcnt(0)
	s_waitcnt lgkmcnt(0)
	v_mfma_f32_16x16x32_bf16 v[126:129], v[144:147], v[160:163], v[126:129]
	v_mfma_f32_16x16x32_bf16 v[122:125], v[152:155], v[160:163], v[122:125]
	v_mfma_f32_16x16x32_bf16 v[118:121], v[144:147], v[192:195], v[118:121]
	v_mfma_f32_16x16x32_bf16 v[114:117], v[152:155], v[192:195], v[114:117]
	v_mfma_f32_16x16x32_bf16 v[102:105], v[144:147], v[200:203], v[102:105]
	v_mfma_f32_16x16x32_bf16 v[98:101], v[152:155], v[200:203], v[98:101]
	v_mfma_f32_16x16x32_bf16 v[86:89], v[144:147], v[220:223], v[86:89]
	v_mfma_f32_16x16x32_bf16 v[82:85], v[152:155], v[220:223], v[82:85]
	v_mfma_f32_16x16x32_bf16 v[126:129], v[148:151], v[188:191], v[126:129]
	v_mfma_f32_16x16x32_bf16 v[122:125], v[156:159], v[188:191], v[122:125]
	v_mfma_f32_16x16x32_bf16 v[118:121], v[148:151], v[196:199], v[118:121]
	v_mfma_f32_16x16x32_bf16 v[114:117], v[156:159], v[196:199], v[114:117]
	v_mfma_f32_16x16x32_bf16 v[102:105], v[148:151], v[216:219], v[102:105]
	v_mfma_f32_16x16x32_bf16 v[98:101], v[156:159], v[216:219], v[98:101]
	v_mfma_f32_16x16x32_bf16 v[86:89], v[148:151], v[224:227], v[86:89]
	v_mfma_f32_16x16x32_bf16 v[82:85], v[156:159], v[224:227], v[82:85]
	s_barrier
	s_add_i32 s17, 0, 0x1c000
	s_add_i32 s2, s2, s3
	v_add_u32_e32 v206, s17, v141
	v_lshl_add_u64 v[164:165], v[164:165], 0, s[28:29]
	s_mov_b32 m0, s2
	ds_read_b128 v[228:231], v206
	ds_read_b128 v[232:235], v206 offset:1024
	ds_read_b128 v[236:239], v206 offset:2048
	ds_read_b128 v[240:243], v206 offset:3072
	global_load_lds_dwordx4 v[164:165], off
	v_lshl_add_u64 v[164:165], v[204:205], 0, s[28:29]
	s_add_i32 m0, s2, 0x2000
	s_nop 0
	global_load_lds_dwordx4 v[164:165], off
	s_barrier
	s_waitcnt lgkmcnt(0)
	s_waitcnt lgkmcnt(0)
	v_mfma_f32_16x16x32_bf16 v[110:113], v[228:231], v[160:163], v[110:113]
	v_mfma_f32_16x16x32_bf16 v[106:109], v[236:239], v[160:163], v[106:109]
	v_mfma_f32_16x16x32_bf16 v[94:97], v[228:231], v[192:195], v[94:97]
	v_mfma_f32_16x16x32_bf16 v[90:93], v[236:239], v[192:195], v[90:93]
	v_mfma_f32_16x16x32_bf16 v[78:81], v[228:231], v[200:203], v[78:81]
	v_mfma_f32_16x16x32_bf16 v[74:77], v[236:239], v[200:203], v[74:77]
	v_mfma_f32_16x16x32_bf16 v[70:73], v[228:231], v[220:223], v[70:73]
	v_mfma_f32_16x16x32_bf16 v[66:69], v[236:239], v[220:223], v[66:69]
	v_mfma_f32_16x16x32_bf16 v[110:113], v[232:235], v[188:191], v[110:113]
	v_mfma_f32_16x16x32_bf16 v[106:109], v[240:243], v[188:191], v[106:109]
	v_mfma_f32_16x16x32_bf16 v[94:97], v[232:235], v[196:199], v[94:97]
	v_mfma_f32_16x16x32_bf16 v[90:93], v[240:243], v[196:199], v[90:93]
	v_mfma_f32_16x16x32_bf16 v[78:81], v[232:235], v[216:219], v[78:81]
	v_mfma_f32_16x16x32_bf16 v[74:77], v[240:243], v[216:219], v[74:77]
	v_mfma_f32_16x16x32_bf16 v[70:73], v[232:235], v[224:227], v[70:73]
	v_mfma_f32_16x16x32_bf16 v[66:69], v[240:243], v[224:227], v[66:69]
	s_mov_b32 m0, s80
	v_lshl_add_u64 v[164:165], v[244:245], 0, s[28:29]
	s_barrier
	ds_read_b128 v[160:163], v143 offset:49152
	ds_read_b128 v[188:191], v143 offset:50176
	ds_read_b128 v[192:195], v143 offset:51200
	ds_read_b128 v[196:199], v143 offset:52224
	ds_read_b128 v[200:203], v143 offset:53248
	ds_read_b128 v[216:219], v143 offset:54272
	ds_read_b128 v[220:223], v143 offset:55296
	ds_read_b128 v[224:227], v143 offset:56320
	global_load_lds_dwordx4 v[164:165], off
	v_lshl_add_u64 v[164:165], v[246:247], 0, s[28:29]
	s_mov_b32 m0, s81
	s_nop 0
	global_load_lds_dwordx4 v[164:165], off
	s_barrier
	s_waitcnt lgkmcnt(0)
	s_waitcnt lgkmcnt(0)
	v_mfma_f32_16x16x32_bf16 v[62:65], v[144:147], v[160:163], v[62:65]
	v_mfma_f32_16x16x32_bf16 v[58:61], v[152:155], v[160:163], v[58:61]
	v_mfma_f32_16x16x32_bf16 v[54:57], v[144:147], v[192:195], v[54:57]
	v_mfma_f32_16x16x32_bf16 v[50:53], v[152:155], v[192:195], v[50:53]
	v_mfma_f32_16x16x32_bf16 v[38:41], v[144:147], v[200:203], v[38:41]
	v_mfma_f32_16x16x32_bf16 v[34:37], v[152:155], v[200:203], v[34:37]
	v_mfma_f32_16x16x32_bf16 v[22:25], v[144:147], v[220:223], v[22:25]
	v_mfma_f32_16x16x32_bf16 v[18:21], v[152:155], v[220:223], v[18:21]
	v_mfma_f32_16x16x32_bf16 v[62:65], v[148:151], v[188:191], v[62:65]
	v_mfma_f32_16x16x32_bf16 v[58:61], v[156:159], v[188:191], v[58:61]
	v_mfma_f32_16x16x32_bf16 v[54:57], v[148:151], v[196:199], v[54:57]
	v_mfma_f32_16x16x32_bf16 v[50:53], v[156:159], v[196:199], v[50:53]
	v_mfma_f32_16x16x32_bf16 v[38:41], v[148:151], v[216:219], v[38:41]
	v_mfma_f32_16x16x32_bf16 v[34:37], v[156:159], v[216:219], v[34:37]
	v_mfma_f32_16x16x32_bf16 v[22:25], v[148:151], v[224:227], v[22:25]
	v_mfma_f32_16x16x32_bf16 v[18:21], v[156:159], v[224:227], v[18:21]
	s_barrier
	s_add_u32 s26, s70, 0x80080
	s_addc_u32 s27, s71, 0
	s_add_i32 s2, s17, s3
	v_lshl_add_u64 v[144:145], s[26:27], 0, v[0:1]
	s_mov_b32 m0, s2
	s_nop 0
	global_load_lds_dwordx4 v[144:145], off
	v_lshl_add_u64 v[144:145], s[26:27], 0, v[130:131]
	s_add_i32 m0, s2, 0x2000
	s_nop 0
	global_load_lds_dwordx4 v[144:145], off
	s_waitcnt vmcnt(6)
	s_barrier
	v_mfma_f32_16x16x32_bf16 v[46:49], v[228:231], v[160:163], v[46:49]
	v_mfma_f32_16x16x32_bf16 v[42:45], v[236:239], v[160:163], v[42:45]
	v_mfma_f32_16x16x32_bf16 v[30:33], v[228:231], v[192:195], v[30:33]
	v_mfma_f32_16x16x32_bf16 v[26:29], v[236:239], v[192:195], v[26:29]
	v_mfma_f32_16x16x32_bf16 v[14:17], v[228:231], v[200:203], v[14:17]
	v_mfma_f32_16x16x32_bf16 v[10:13], v[236:239], v[200:203], v[10:13]
	v_mfma_f32_16x16x32_bf16 v[6:9], v[228:231], v[220:223], v[6:9]
	v_mfma_f32_16x16x32_bf16 v[2:5], v[236:239], v[220:223], v[2:5]
	v_mfma_f32_16x16x32_bf16 v[46:49], v[232:235], v[188:191], v[46:49]
	v_mfma_f32_16x16x32_bf16 v[42:45], v[240:243], v[188:191], v[42:45]
	v_mfma_f32_16x16x32_bf16 v[30:33], v[232:235], v[196:199], v[30:33]
	v_mfma_f32_16x16x32_bf16 v[26:29], v[240:243], v[196:199], v[26:29]
	v_mfma_f32_16x16x32_bf16 v[14:17], v[232:235], v[216:219], v[14:17]
	v_mfma_f32_16x16x32_bf16 v[10:13], v[240:243], v[216:219], v[10:13]
	v_mfma_f32_16x16x32_bf16 v[6:9], v[232:235], v[224:227], v[6:9]
	v_mfma_f32_16x16x32_bf16 v[2:5], v[240:243], v[224:227], v[2:5]
	s_add_i32 s44, s44, 2
	s_add_u32 s68, s68, 0x100
	s_addc_u32 s69, s69, 0
	s_add_u32 s43, s43, 0x100
	s_addc_u32 s92, s92, 0
	s_cmp_gt_u32 s44, 29
	s_barrier
	s_cbranch_scc0 .LBB0_655
	v_lshl_add_u32 v144, s47, 8, v140
	v_lshl_or_b32 v146, s46, 8, v142
	v_ashrrev_i32_e32 v145, 31, v144
	v_cvt_pk_bf16_f32 v126, v126, v127
	v_cvt_pk_bf16_f32 v127, v128, v129
	v_cvt_pk_bf16_f32 v128, v122, v123
	v_lshlrev_b64 v[122:123], 12, v[144:145]
	v_ashrrev_i32_e32 v147, 31, v146
	v_cvt_pk_bf16_f32 v129, v124, v125
	v_lshl_add_u64 v[122:123], s[22:23], 0, v[122:123]
	v_lshlrev_b64 v[124:125], 1, v[146:147]
	v_lshl_add_u64 v[122:123], v[122:123], 0, v[124:125]
	v_cvt_pk_bf16_f32 v110, v110, v111
	v_cvt_pk_bf16_f32 v111, v112, v113
	v_cvt_pk_bf16_f32 v112, v106, v107
	v_cvt_pk_bf16_f32 v113, v108, v109
	global_store_dwordx4 v[122:123], v[110:113], off offset:256
	v_cvt_pk_bf16_f32 v94, v94, v95
	v_cvt_pk_bf16_f32 v95, v96, v97
	v_or_b32_e32 v110, 16, v144
	v_ashrrev_i32_e32 v111, 31, v110
	v_lshlrev_b64 v[110:111], 12, v[110:111]
	v_lshl_add_u64 v[110:111], s[22:23], 0, v[110:111]
	v_lshl_add_u64 v[110:111], v[110:111], 0, v[124:125]
	v_cvt_pk_bf16_f32 v96, v90, v91
	v_cvt_pk_bf16_f32 v97, v92, v93
	global_store_dwordx4 v[110:111], v[94:97], off offset:256
	s_mov_b32 s2, 0x80000
	v_cvt_pk_bf16_f32 v62, v62, v63
	v_or_b32_e32 v94, 32, v144
	v_ashrrev_i32_e32 v95, 31, v94
	v_cvt_pk_bf16_f32 v63, v64, v65
	v_cvt_pk_bf16_f32 v65, v60, v61
	s_mov_b64 s[4:5], 0x80000
	v_add_co_u32_e32 v60, vcc, s2, v122
	v_lshlrev_b64 v[94:95], 12, v[94:95]
	v_cvt_pk_bf16_f32 v64, v58, v59
	v_lshl_add_u64 v[58:59], v[122:123], 0, s[4:5]
	v_addc_co_u32_e32 v61, vcc, 0, v123, vcc
	v_cvt_pk_bf16_f32 v46, v46, v47
	v_cvt_pk_bf16_f32 v47, v48, v49
	v_cvt_pk_bf16_f32 v48, v42, v43
	v_cvt_pk_bf16_f32 v49, v44, v45
	s_mov_b32 s2, 0x90000
	v_lshl_add_u64 v[94:95], s[22:23], 0, v[94:95]
	global_store_dwordx4 v[58:59], v[46:49], off offset:256
	s_mov_b64 s[4:5], 0x90000
	v_lshl_add_u64 v[94:95], v[94:95], 0, v[124:125]
	v_add_co_u32_e32 v48, vcc, s2, v122
	v_cvt_pk_bf16_f32 v78, v78, v79
	v_cvt_pk_bf16_f32 v79, v80, v81
	v_cvt_pk_bf16_f32 v80, v74, v75
	v_cvt_pk_bf16_f32 v81, v76, v77
	v_lshl_add_u64 v[46:47], v[122:123], 0, s[4:5]
	v_addc_co_u32_e32 v49, vcc, 0, v123, vcc
	v_cvt_pk_bf16_f32 v30, v30, v31
	v_cvt_pk_bf16_f32 v31, v32, v33
	v_cvt_pk_bf16_f32 v32, v26, v27
	v_cvt_pk_bf16_f32 v33, v28, v29
	s_mov_b32 s2, 0xa0000
	global_store_dwordx4 v[94:95], v[78:81], off offset:256
	global_store_dwordx4 v[46:47], v[30:33], off offset:256
	s_mov_b64 s[4:5], 0xa0000
	v_or_b32_e32 v78, 48, v144
	v_add_co_u32_e32 v32, vcc, s2, v122
	v_ashrrev_i32_e32 v79, 31, v78
	v_lshl_add_u64 v[30:31], v[122:123], 0, s[4:5]
	v_addc_co_u32_e32 v33, vcc, 0, v123, vcc
	v_cvt_pk_bf16_f32 v14, v14, v15
	v_cvt_pk_bf16_f32 v15, v16, v17
	v_cvt_pk_bf16_f32 v16, v10, v11
	v_cvt_pk_bf16_f32 v17, v12, v13
	s_mov_b32 s2, 0xb0000
	v_lshlrev_b64 v[78:79], 12, v[78:79]
	global_store_dwordx4 v[30:31], v[14:17], off offset:256
	v_lshl_add_u64 v[78:79], s[22:23], 0, v[78:79]
	s_mov_b64 s[4:5], 0xb0000
	v_add_co_u32_e32 v16, vcc, s2, v122
	v_cvt_pk_bf16_f32 v106, v118, v119
	s_nop 0
	v_addc_co_u32_e32 v17, vcc, 0, v123, vcc
	v_cvt_pk_bf16_f32 v107, v120, v121
	v_cvt_pk_bf16_f32 v108, v114, v115
	v_cvt_pk_bf16_f32 v109, v116, v117
	v_cvt_pk_bf16_f32 v90, v102, v103
	v_cvt_pk_bf16_f32 v91, v104, v105
	v_cvt_pk_bf16_f32 v92, v98, v99
	v_cvt_pk_bf16_f32 v93, v100, v101
	v_cvt_pk_bf16_f32 v74, v86, v87
	v_cvt_pk_bf16_f32 v75, v88, v89
	v_cvt_pk_bf16_f32 v76, v82, v83
	v_cvt_pk_bf16_f32 v77, v84, v85
	v_lshl_add_u64 v[78:79], v[78:79], 0, v[124:125]
	v_cvt_pk_bf16_f32 v70, v70, v71
	v_cvt_pk_bf16_f32 v71, v72, v73
	v_cvt_pk_bf16_f32 v72, v66, v67
	v_cvt_pk_bf16_f32 v73, v68, v69
	v_cvt_pk_bf16_f32 v42, v54, v55
	v_cvt_pk_bf16_f32 v43, v56, v57
	v_cvt_pk_bf16_f32 v44, v50, v51
	v_cvt_pk_bf16_f32 v45, v52, v53
	v_cvt_pk_bf16_f32 v26, v38, v39
	v_cvt_pk_bf16_f32 v27, v40, v41
	v_cvt_pk_bf16_f32 v28, v34, v35
	v_cvt_pk_bf16_f32 v29, v36, v37
	v_cvt_pk_bf16_f32 v10, v22, v23
	v_cvt_pk_bf16_f32 v11, v24, v25
	v_cvt_pk_bf16_f32 v12, v18, v19
	v_cvt_pk_bf16_f32 v13, v20, v21
	v_lshl_add_u64 v[14:15], v[122:123], 0, s[4:5]
	v_cvt_pk_bf16_f32 v6, v6, v7
	v_cvt_pk_bf16_f32 v7, v8, v9
	v_cvt_pk_bf16_f32 v8, v2, v3
	v_cvt_pk_bf16_f32 v9, v4, v5
	s_and_b64 vcc, exec, s[0:1]
	s_mov_b32 s46, s42
	s_mov_b32 s47, s54
	s_mov_b64 s[70:71], s[64:65]
	s_mov_b64 s[68:69], s[62:63]
	global_store_dwordx4 v[122:123], v[126:129], off
	global_store_dwordx4 v[110:111], v[106:109], off
	global_store_dwordx4 v[94:95], v[90:93], off
	global_store_dwordx4 v[78:79], v[74:77], off
	global_store_dwordx4 v[78:79], v[70:73], off offset:256
	global_store_dwordx4 v[60:61], v[62:65], off
	global_store_dwordx4 v[48:49], v[42:45], off
	global_store_dwordx4 v[32:33], v[26:29], off
	global_store_dwordx4 v[16:17], v[10:13], off
	global_store_dwordx4 v[14:15], v[6:9], off offset:256
	s_cbranch_vccz .LBB0_652
	v_readlane_b32 s0, v254, 12
	s_waitcnt vmcnt(0)
	v_readlane_b32 s1, v254, 13
	v_readlane_b32 s84, v251, 38
	s_andn2_b64 vcc, exec, s[0:1]
	v_readlane_b32 s85, v251, 39
	v_readlane_b32 s86, v251, 40
	v_readlane_b32 s87, v251, 41
	s_cbranch_vccnz .LBB0_659
	s_barrier

.LBB0_724:
	s_add_u32 s2, s68, 0xfff80080
	s_addc_u32 s17, s69, -1
	s_add_i32 s26, 0, 0x10000
	v_add_u32_e32 v156, s26, v141
	ds_read_b128 v[144:147], v156
	ds_read_b128 v[148:151], v156 offset:1024
	ds_read_b128 v[152:155], v156 offset:2048
	ds_read_b128 v[156:159], v156 offset:3072
	s_cmp_eq_u32 s83, 28
	s_cselect_b32 s73, s55, s17
	s_cselect_b32 s72, s81, s2
	s_cselect_b32 s71, s24, s82
	s_cselect_b32 s70, s25, s43
	v_lshl_add_u64 v[164:165], s[68:69], 0, v[136:137]
	s_add_i32 m0, s58, 0xc000
	ds_read_b128 v[160:163], v143
	ds_read_b128 v[188:191], v143 offset:1024
	ds_read_b128 v[192:195], v143 offset:2048
	ds_read_b128 v[196:199], v143 offset:3072
	ds_read_b128 v[200:203], v143 offset:4096
	ds_read_b128 v[216:219], v143 offset:5120
	ds_read_b128 v[220:223], v143 offset:6144
	ds_read_b128 v[224:227], v143 offset:7168
	global_load_lds_dwordx4 v[164:165], off
	v_lshl_add_u64 v[164:165], s[68:69], 0, v[138:139]
	s_add_i32 m0, s58, 0xe000
	s_nop 0
	global_load_lds_dwordx4 v[164:165], off
	s_waitcnt lgkmcnt(8)
	s_barrier
	s_waitcnt lgkmcnt(0)
	s_waitcnt lgkmcnt(0)
	v_mfma_f32_16x16x32_bf16 v[126:129], v[144:147], v[160:163], v[126:129]
	v_mfma_f32_16x16x32_bf16 v[122:125], v[152:155], v[160:163], v[122:125]
	v_mfma_f32_16x16x32_bf16 v[118:121], v[144:147], v[192:195], v[118:121]
	v_mfma_f32_16x16x32_bf16 v[114:117], v[152:155], v[192:195], v[114:117]
	v_mfma_f32_16x16x32_bf16 v[102:105], v[144:147], v[200:203], v[102:105]
	v_mfma_f32_16x16x32_bf16 v[98:101], v[152:155], v[200:203], v[98:101]
	v_mfma_f32_16x16x32_bf16 v[86:89], v[144:147], v[220:223], v[86:89]
	v_mfma_f32_16x16x32_bf16 v[82:85], v[152:155], v[220:223], v[82:85]
	v_mfma_f32_16x16x32_bf16 v[126:129], v[148:151], v[188:191], v[126:129]
	v_mfma_f32_16x16x32_bf16 v[122:125], v[156:159], v[188:191], v[122:125]
	v_mfma_f32_16x16x32_bf16 v[118:121], v[148:151], v[196:199], v[118:121]
	v_mfma_f32_16x16x32_bf16 v[114:117], v[156:159], v[196:199], v[114:117]
	v_mfma_f32_16x16x32_bf16 v[102:105], v[148:151], v[216:219], v[102:105]
	v_mfma_f32_16x16x32_bf16 v[98:101], v[156:159], v[216:219], v[98:101]
	v_mfma_f32_16x16x32_bf16 v[86:89], v[148:151], v[224:227], v[86:89]
	v_mfma_f32_16x16x32_bf16 v[82:85], v[156:159], v[224:227], v[82:85]
	s_barrier
	s_add_i32 s2, 0, 0x14000
	v_add_u32_e32 v164, s2, v141
	s_add_i32 s17, s26, s3
	ds_read_b128 v[228:231], v164
	ds_read_b128 v[232:235], v164 offset:1024
	ds_read_b128 v[236:239], v164 offset:2048
	ds_read_b128 v[240:243], v164 offset:3072
	v_lshl_add_u64 v[164:165], s[70:71], 0, v[0:1]
	s_mov_b32 m0, s17
	v_lshl_add_u64 v[204:205], s[70:71], 0, v[130:131]
	global_load_lds_dwordx4 v[164:165], off
	s_add_i32 m0, s17, 0x2000
	s_nop 0
	global_load_lds_dwordx4 v[204:205], off
	s_barrier
	s_waitcnt lgkmcnt(0)
	s_waitcnt lgkmcnt(0)
	v_mfma_f32_16x16x32_bf16 v[110:113], v[228:231], v[160:163], v[110:113]
	v_mfma_f32_16x16x32_bf16 v[106:109], v[236:239], v[160:163], v[106:109]
	v_mfma_f32_16x16x32_bf16 v[94:97], v[228:231], v[192:195], v[94:97]
	v_mfma_f32_16x16x32_bf16 v[90:93], v[236:239], v[192:195], v[90:93]
	v_mfma_f32_16x16x32_bf16 v[78:81], v[228:231], v[200:203], v[78:81]
	v_mfma_f32_16x16x32_bf16 v[74:77], v[236:239], v[200:203], v[74:77]
	v_mfma_f32_16x16x32_bf16 v[70:73], v[228:231], v[220:223], v[70:73]
	v_mfma_f32_16x16x32_bf16 v[66:69], v[236:239], v[220:223], v[66:69]
	v_mfma_f32_16x16x32_bf16 v[110:113], v[232:235], v[188:191], v[110:113]
	v_mfma_f32_16x16x32_bf16 v[106:109], v[240:243], v[188:191], v[106:109]
	v_mfma_f32_16x16x32_bf16 v[94:97], v[232:235], v[196:199], v[94:97]
	v_mfma_f32_16x16x32_bf16 v[90:93], v[240:243], v[196:199], v[90:93]
	v_mfma_f32_16x16x32_bf16 v[78:81], v[232:235], v[216:219], v[78:81]
	v_mfma_f32_16x16x32_bf16 v[74:77], v[240:243], v[216:219], v[74:77]
	v_mfma_f32_16x16x32_bf16 v[70:73], v[232:235], v[224:227], v[70:73]
	v_mfma_f32_16x16x32_bf16 v[66:69], v[240:243], v[224:227], v[66:69]
	s_mov_b32 m0, s58
	v_lshl_add_u64 v[244:245], s[72:73], 0, v[134:135]
	s_barrier
	ds_read_b128 v[160:163], v143 offset:16384
	ds_read_b128 v[188:191], v143 offset:17408
	ds_read_b128 v[192:195], v143 offset:18432
	ds_read_b128 v[196:199], v143 offset:19456
	ds_read_b128 v[200:203], v143 offset:20480
	ds_read_b128 v[216:219], v143 offset:21504
	ds_read_b128 v[220:223], v143 offset:22528
	ds_read_b128 v[224:227], v143 offset:23552
	global_load_lds_dwordx4 v[244:245], off
	v_lshl_add_u64 v[246:247], s[72:73], 0, v[132:133]
	s_mov_b32 m0, s74
	s_nop 0
	global_load_lds_dwordx4 v[246:247], off
	s_barrier
	s_waitcnt lgkmcnt(0)
	s_waitcnt lgkmcnt(0)
	v_mfma_f32_16x16x32_bf16 v[62:65], v[144:147], v[160:163], v[62:65]
	v_mfma_f32_16x16x32_bf16 v[58:61], v[152:155], v[160:163], v[58:61]
	v_mfma_f32_16x16x32_bf16 v[54:57], v[144:147], v[192:195], v[54:57]
	v_mfma_f32_16x16x32_bf16 v[50:53], v[152:155], v[192:195], v[50:53]
	v_mfma_f32_16x16x32_bf16 v[38:41], v[144:147], v[200:203], v[38:41]
	v_mfma_f32_16x16x32_bf16 v[34:37], v[152:155], v[200:203], v[34:37]
	v_mfma_f32_16x16x32_bf16 v[22:25], v[144:147], v[220:223], v[22:25]
	v_mfma_f32_16x16x32_bf16 v[18:21], v[152:155], v[220:223], v[18:21]
	v_mfma_f32_16x16x32_bf16 v[62:65], v[148:151], v[188:191], v[62:65]
	v_mfma_f32_16x16x32_bf16 v[58:61], v[156:159], v[188:191], v[58:61]
	v_mfma_f32_16x16x32_bf16 v[54:57], v[148:151], v[196:199], v[54:57]
	v_mfma_f32_16x16x32_bf16 v[50:53], v[156:159], v[196:199], v[50:53]
	v_mfma_f32_16x16x32_bf16 v[38:41], v[148:151], v[216:219], v[38:41]
	v_mfma_f32_16x16x32_bf16 v[34:37], v[156:159], v[216:219], v[34:37]
	v_mfma_f32_16x16x32_bf16 v[22:25], v[148:151], v[224:227], v[22:25]
	v_mfma_f32_16x16x32_bf16 v[18:21], v[156:159], v[224:227], v[18:21]
	s_barrier
	s_add_u32 s44, s70, 0x80000
	s_addc_u32 s45, s71, 0
	s_add_i32 s2, s2, s3
	v_lshl_add_u64 v[144:145], s[44:45], 0, v[0:1]
	s_mov_b32 m0, s2
	s_nop 0
	global_load_lds_dwordx4 v[144:145], off
	v_lshl_add_u64 v[144:145], s[44:45], 0, v[130:131]
	s_add_i32 m0, s2, 0x2000
	s_nop 0
	global_load_lds_dwordx4 v[144:145], off
	s_waitcnt vmcnt(6)
	s_barrier
	v_mfma_f32_16x16x32_bf16 v[46:49], v[228:231], v[160:163], v[46:49]
	v_mfma_f32_16x16x32_bf16 v[42:45], v[236:239], v[160:163], v[42:45]
	v_mfma_f32_16x16x32_bf16 v[30:33], v[228:231], v[192:195], v[30:33]
	v_mfma_f32_16x16x32_bf16 v[26:29], v[236:239], v[192:195], v[26:29]
	v_mfma_f32_16x16x32_bf16 v[14:17], v[228:231], v[200:203], v[14:17]
	v_mfma_f32_16x16x32_bf16 v[10:13], v[236:239], v[200:203], v[10:13]
	v_mfma_f32_16x16x32_bf16 v[6:9], v[228:231], v[220:223], v[6:9]
	v_mfma_f32_16x16x32_bf16 v[2:5], v[236:239], v[220:223], v[2:5]
	v_mfma_f32_16x16x32_bf16 v[46:49], v[232:235], v[188:191], v[46:49]
	v_mfma_f32_16x16x32_bf16 v[42:45], v[240:243], v[188:191], v[42:45]
	v_mfma_f32_16x16x32_bf16 v[30:33], v[232:235], v[196:199], v[30:33]
	v_mfma_f32_16x16x32_bf16 v[26:29], v[240:243], v[196:199], v[26:29]
	v_mfma_f32_16x16x32_bf16 v[14:17], v[232:235], v[216:219], v[14:17]
	v_mfma_f32_16x16x32_bf16 v[10:13], v[240:243], v[216:219], v[10:13]
	v_mfma_f32_16x16x32_bf16 v[6:9], v[232:235], v[224:227], v[6:9]
	v_mfma_f32_16x16x32_bf16 v[2:5], v[240:243], v[224:227], v[2:5]
	s_add_i32 s2, 0, 0x18000
	v_add_u32_e32 v156, s2, v141
	s_barrier
	ds_read_b128 v[144:147], v156
	ds_read_b128 v[148:151], v156 offset:1024
	ds_read_b128 v[152:155], v156 offset:2048
	ds_read_b128 v[156:159], v156 offset:3072
	s_add_u32 s44, s72, 0x80000
	s_addc_u32 s45, s73, 0
	s_mov_b32 m0, s75
	v_lshl_add_u64 v[228:229], s[44:45], 0, v[134:135]
	ds_read_b128 v[160:163], v143 offset:32768
	ds_read_b128 v[188:191], v143 offset:33792
	ds_read_b128 v[192:195], v143 offset:34816
	ds_read_b128 v[196:199], v143 offset:35840
	ds_read_b128 v[200:203], v143 offset:36864
	ds_read_b128 v[216:219], v143 offset:37888
	ds_read_b128 v[220:223], v143 offset:38912
	ds_read_b128 v[224:227], v143 offset:39936
	global_load_lds_dwordx4 v[228:229], off
	v_lshl_add_u64 v[228:229], s[44:45], 0, v[132:133]
	s_mov_b32 m0, s77
	s_nop 0
	global_load_lds_dwordx4 v[228:229], off
	s_waitcnt lgkmcnt(8)
	s_barrier
	s_waitcnt lgkmcnt(0)
	s_waitcnt lgkmcnt(0)
	v_mfma_f32_16x16x32_bf16 v[126:129], v[144:147], v[160:163], v[126:129]
	v_mfma_f32_16x16x32_bf16 v[122:125], v[152:155], v[160:163], v[122:125]
	v_mfma_f32_16x16x32_bf16 v[118:121], v[144:147], v[192:195], v[118:121]
	v_mfma_f32_16x16x32_bf16 v[114:117], v[152:155], v[192:195], v[114:117]
	v_mfma_f32_16x16x32_bf16 v[102:105], v[144:147], v[200:203], v[102:105]
	v_mfma_f32_16x16x32_bf16 v[98:101], v[152:155], v[200:203], v[98:101]
	v_mfma_f32_16x16x32_bf16 v[86:89], v[144:147], v[220:223], v[86:89]
	v_mfma_f32_16x16x32_bf16 v[82:85], v[152:155], v[220:223], v[82:85]
	v_mfma_f32_16x16x32_bf16 v[126:129], v[148:151], v[188:191], v[126:129]
	v_mfma_f32_16x16x32_bf16 v[122:125], v[156:159], v[188:191], v[122:125]
	v_mfma_f32_16x16x32_bf16 v[118:121], v[148:151], v[196:199], v[118:121]
	v_mfma_f32_16x16x32_bf16 v[114:117], v[156:159], v[196:199], v[114:117]
	v_mfma_f32_16x16x32_bf16 v[102:105], v[148:151], v[216:219], v[102:105]
	v_mfma_f32_16x16x32_bf16 v[98:101], v[156:159], v[216:219], v[98:101]
	v_mfma_f32_16x16x32_bf16 v[86:89], v[148:151], v[224:227], v[86:89]
	v_mfma_f32_16x16x32_bf16 v[82:85], v[156:159], v[224:227], v[82:85]
	s_barrier
	s_add_i32 s17, 0, 0x1c000
	s_add_i32 s2, s2, s3
	v_add_u32_e32 v206, s17, v141
	v_lshl_add_u64 v[164:165], v[164:165], 0, s[28:29]
	s_mov_b32 m0, s2
	ds_read_b128 v[228:231], v206
	ds_read_b128 v[232:235], v206 offset:1024
	ds_read_b128 v[236:239], v206 offset:2048
	ds_read_b128 v[240:243], v206 offset:3072
	global_load_lds_dwordx4 v[164:165], off
	v_lshl_add_u64 v[164:165], v[204:205], 0, s[28:29]
	s_add_i32 m0, s2, 0x2000
	s_nop 0
	global_load_lds_dwordx4 v[164:165], off
	s_barrier
	s_waitcnt lgkmcnt(0)
	s_waitcnt lgkmcnt(0)
	v_mfma_f32_16x16x32_bf16 v[110:113], v[228:231], v[160:163], v[110:113]
	v_mfma_f32_16x16x32_bf16 v[106:109], v[236:239], v[160:163], v[106:109]
	v_mfma_f32_16x16x32_bf16 v[94:97], v[228:231], v[192:195], v[94:97]
	v_mfma_f32_16x16x32_bf16 v[90:93], v[236:239], v[192:195], v[90:93]
	v_mfma_f32_16x16x32_bf16 v[78:81], v[228:231], v[200:203], v[78:81]
	v_mfma_f32_16x16x32_bf16 v[74:77], v[236:239], v[200:203], v[74:77]
	v_mfma_f32_16x16x32_bf16 v[70:73], v[228:231], v[220:223], v[70:73]
	v_mfma_f32_16x16x32_bf16 v[66:69], v[236:239], v[220:223], v[66:69]
	v_mfma_f32_16x16x32_bf16 v[110:113], v[232:235], v[188:191], v[110:113]
	v_mfma_f32_16x16x32_bf16 v[106:109], v[240:243], v[188:191], v[106:109]
	v_mfma_f32_16x16x32_bf16 v[94:97], v[232:235], v[196:199], v[94:97]
	v_mfma_f32_16x16x32_bf16 v[90:93], v[240:243], v[196:199], v[90:93]
	v_mfma_f32_16x16x32_bf16 v[78:81], v[232:235], v[216:219], v[78:81]
	v_mfma_f32_16x16x32_bf16 v[74:77], v[240:243], v[216:219], v[74:77]
	v_mfma_f32_16x16x32_bf16 v[70:73], v[232:235], v[224:227], v[70:73]
	v_mfma_f32_16x16x32_bf16 v[66:69], v[240:243], v[224:227], v[66:69]
	s_mov_b32 m0, s78
	v_lshl_add_u64 v[164:165], v[244:245], 0, s[28:29]
	s_barrier
	ds_read_b128 v[160:163], v143 offset:49152
	ds_read_b128 v[188:191], v143 offset:50176
	ds_read_b128 v[192:195], v143 offset:51200
	ds_read_b128 v[196:199], v143 offset:52224
	ds_read_b128 v[200:203], v143 offset:53248
	ds_read_b128 v[216:219], v143 offset:54272
	ds_read_b128 v[220:223], v143 offset:55296
	ds_read_b128 v[224:227], v143 offset:56320
	global_load_lds_dwordx4 v[164:165], off
	v_lshl_add_u64 v[164:165], v[246:247], 0, s[28:29]
	s_mov_b32 m0, s79
	s_nop 0
	global_load_lds_dwordx4 v[164:165], off
	s_barrier
	s_waitcnt lgkmcnt(0)
	s_waitcnt lgkmcnt(0)
	v_mfma_f32_16x16x32_bf16 v[62:65], v[144:147], v[160:163], v[62:65]
	v_mfma_f32_16x16x32_bf16 v[58:61], v[152:155], v[160:163], v[58:61]
	v_mfma_f32_16x16x32_bf16 v[54:57], v[144:147], v[192:195], v[54:57]
	v_mfma_f32_16x16x32_bf16 v[50:53], v[152:155], v[192:195], v[50:53]
	v_mfma_f32_16x16x32_bf16 v[38:41], v[144:147], v[200:203], v[38:41]
	v_mfma_f32_16x16x32_bf16 v[34:37], v[152:155], v[200:203], v[34:37]
	v_mfma_f32_16x16x32_bf16 v[22:25], v[144:147], v[220:223], v[22:25]
	v_mfma_f32_16x16x32_bf16 v[18:21], v[152:155], v[220:223], v[18:21]
	v_mfma_f32_16x16x32_bf16 v[62:65], v[148:151], v[188:191], v[62:65]
	v_mfma_f32_16x16x32_bf16 v[58:61], v[156:159], v[188:191], v[58:61]
	v_mfma_f32_16x16x32_bf16 v[54:57], v[148:151], v[196:199], v[54:57]
	v_mfma_f32_16x16x32_bf16 v[50:53], v[156:159], v[196:199], v[50:53]
	v_mfma_f32_16x16x32_bf16 v[38:41], v[148:151], v[216:219], v[38:41]
	v_mfma_f32_16x16x32_bf16 v[34:37], v[156:159], v[216:219], v[34:37]
	v_mfma_f32_16x16x32_bf16 v[22:25], v[148:151], v[224:227], v[22:25]
	v_mfma_f32_16x16x32_bf16 v[18:21], v[156:159], v[224:227], v[18:21]
	s_barrier
	s_add_u32 s44, s70, 0x80080
	s_addc_u32 s45, s71, 0
	s_add_i32 s2, s17, s3
	v_lshl_add_u64 v[144:145], s[44:45], 0, v[0:1]
	s_mov_b32 m0, s2
	s_nop 0
	global_load_lds_dwordx4 v[144:145], off
	v_lshl_add_u64 v[144:145], s[44:45], 0, v[130:131]
	s_add_i32 m0, s2, 0x2000
	s_nop 0
	global_load_lds_dwordx4 v[144:145], off
	s_waitcnt vmcnt(6)
	s_barrier
	v_mfma_f32_16x16x32_bf16 v[46:49], v[228:231], v[160:163], v[46:49]
	v_mfma_f32_16x16x32_bf16 v[42:45], v[236:239], v[160:163], v[42:45]
	v_mfma_f32_16x16x32_bf16 v[30:33], v[228:231], v[192:195], v[30:33]
	v_mfma_f32_16x16x32_bf16 v[26:29], v[236:239], v[192:195], v[26:29]
	v_mfma_f32_16x16x32_bf16 v[14:17], v[228:231], v[200:203], v[14:17]
	v_mfma_f32_16x16x32_bf16 v[10:13], v[236:239], v[200:203], v[10:13]
	v_mfma_f32_16x16x32_bf16 v[6:9], v[228:231], v[220:223], v[6:9]
	v_mfma_f32_16x16x32_bf16 v[2:5], v[236:239], v[220:223], v[2:5]
	v_mfma_f32_16x16x32_bf16 v[46:49], v[232:235], v[188:191], v[46:49]
	v_mfma_f32_16x16x32_bf16 v[42:45], v[240:243], v[188:191], v[42:45]
	v_mfma_f32_16x16x32_bf16 v[30:33], v[232:235], v[196:199], v[30:33]
	v_mfma_f32_16x16x32_bf16 v[26:29], v[240:243], v[196:199], v[26:29]
	v_mfma_f32_16x16x32_bf16 v[14:17], v[232:235], v[216:219], v[14:17]
	v_mfma_f32_16x16x32_bf16 v[10:13], v[240:243], v[216:219], v[10:13]
	v_mfma_f32_16x16x32_bf16 v[6:9], v[232:235], v[224:227], v[6:9]
	v_mfma_f32_16x16x32_bf16 v[2:5], v[240:243], v[224:227], v[2:5]
	s_add_i32 s83, s83, 2
	s_add_u32 s68, s68, 0x100
	s_addc_u32 s69, s69, 0
	s_add_u32 s43, s43, 0x100
	s_addc_u32 s82, s82, 0
	s_cmp_gt_u32 s83, 29
	s_barrier
	s_cbranch_scc0 .LBB0_724
	v_lshl_add_u32 v146, s47, 8, v140
	v_lshl_or_b32 v144, s46, 8, v142
	v_cvt_pk_bf16_f32 v126, v126, v127
	v_cvt_pk_bf16_f32 v127, v128, v129
	v_cvt_pk_bf16_f32 v128, v122, v123
	v_mov_b64_e32 v[122:123], s[22:23]
	v_ashrrev_i32_e32 v145, 31, v144
	v_cvt_pk_bf16_f32 v70, v70, v71
	v_cvt_pk_bf16_f32 v71, v72, v73
	v_cvt_pk_bf16_f32 v72, v66, v67
	v_add_u32_e32 v66, 0x80, v146
	v_cvt_pk_bf16_f32 v129, v124, v125
	v_mad_i64_i32 v[124:125], s[24:25], v146, s48, v[122:123]
	v_lshlrev_b64 v[144:145], 1, v[144:145]
	v_cvt_pk_bf16_f32 v62, v62, v63
	v_cvt_pk_bf16_f32 v63, v64, v65
	v_cvt_pk_bf16_f32 v64, v58, v59
	v_mad_i64_i32 v[58:59], s[24:25], v66, s48, v[122:123]
	v_lshl_add_u64 v[124:125], v[124:125], 0, v[144:145]
	v_cvt_pk_bf16_f32 v110, v110, v111
	v_cvt_pk_bf16_f32 v111, v112, v113
	v_cvt_pk_bf16_f32 v112, v106, v107
	v_cvt_pk_bf16_f32 v113, v108, v109
	v_lshl_add_u64 v[58:59], v[58:59], 0, v[144:145]
	v_cvt_pk_bf16_f32 v46, v46, v47
	v_cvt_pk_bf16_f32 v47, v48, v49
	v_cvt_pk_bf16_f32 v48, v42, v43
	v_cvt_pk_bf16_f32 v49, v44, v45
	global_store_dwordx4 v[124:125], v[110:113], off offset:256
	global_store_dwordx4 v[58:59], v[46:49], off offset:256
	v_cvt_pk_bf16_f32 v94, v94, v95
	v_or_b32_e32 v110, 16, v146
	v_add_u32_e32 v46, 0x90, v146
	v_mad_i64_i32 v[110:111], s[24:25], v110, s48, v[122:123]
	v_mad_i64_i32 v[46:47], s[24:25], v46, s48, v[122:123]
	v_lshl_add_u64 v[110:111], v[110:111], 0, v[144:145]
	v_cvt_pk_bf16_f32 v95, v96, v97
	v_cvt_pk_bf16_f32 v96, v90, v91
	v_cvt_pk_bf16_f32 v97, v92, v93
	v_lshl_add_u64 v[46:47], v[46:47], 0, v[144:145]
	v_cvt_pk_bf16_f32 v30, v30, v31
	v_cvt_pk_bf16_f32 v31, v32, v33
	v_cvt_pk_bf16_f32 v32, v26, v27
	v_cvt_pk_bf16_f32 v33, v28, v29
	global_store_dwordx4 v[110:111], v[94:97], off offset:256
	global_store_dwordx4 v[46:47], v[30:33], off offset:256
	v_cvt_pk_bf16_f32 v78, v78, v79
	v_or_b32_e32 v94, 32, v146
	v_add_u32_e32 v30, 0xa0, v146
	v_mad_i64_i32 v[94:95], s[24:25], v94, s48, v[122:123]
	v_mad_i64_i32 v[30:31], s[24:25], v30, s48, v[122:123]
	v_lshl_add_u64 v[94:95], v[94:95], 0, v[144:145]
	v_cvt_pk_bf16_f32 v79, v80, v81
	v_cvt_pk_bf16_f32 v80, v74, v75
	v_cvt_pk_bf16_f32 v81, v76, v77
	v_lshl_add_u64 v[30:31], v[30:31], 0, v[144:145]
	v_cvt_pk_bf16_f32 v14, v14, v15
	v_cvt_pk_bf16_f32 v15, v16, v17
	v_cvt_pk_bf16_f32 v16, v10, v11
	v_cvt_pk_bf16_f32 v17, v12, v13
	global_store_dwordx4 v[94:95], v[78:81], off offset:256
	global_store_dwordx4 v[30:31], v[14:17], off offset:256
	v_cvt_pk_bf16_f32 v106, v118, v119
	v_or_b32_e32 v78, 48, v146
	v_add_u32_e32 v14, 0xb0, v146
	v_mad_i64_i32 v[78:79], s[24:25], v78, s48, v[122:123]
	v_mad_i64_i32 v[14:15], s[24:25], v14, s48, v[122:123]
	v_cvt_pk_bf16_f32 v107, v120, v121
	v_cvt_pk_bf16_f32 v108, v114, v115
	v_cvt_pk_bf16_f32 v109, v116, v117
	v_cvt_pk_bf16_f32 v90, v102, v103
	v_cvt_pk_bf16_f32 v91, v104, v105
	v_cvt_pk_bf16_f32 v92, v98, v99
	v_cvt_pk_bf16_f32 v93, v100, v101
	v_cvt_pk_bf16_f32 v74, v86, v87
	v_cvt_pk_bf16_f32 v75, v88, v89
	v_cvt_pk_bf16_f32 v76, v82, v83
	v_cvt_pk_bf16_f32 v77, v84, v85
	v_lshl_add_u64 v[78:79], v[78:79], 0, v[144:145]
	v_cvt_pk_bf16_f32 v73, v68, v69
	v_cvt_pk_bf16_f32 v65, v60, v61
	v_cvt_pk_bf16_f32 v42, v54, v55
	v_cvt_pk_bf16_f32 v43, v56, v57
	v_cvt_pk_bf16_f32 v44, v50, v51
	v_cvt_pk_bf16_f32 v45, v52, v53
	v_cvt_pk_bf16_f32 v26, v38, v39
	v_cvt_pk_bf16_f32 v27, v40, v41
	v_cvt_pk_bf16_f32 v28, v34, v35
	v_cvt_pk_bf16_f32 v29, v36, v37
	v_cvt_pk_bf16_f32 v10, v22, v23
	v_cvt_pk_bf16_f32 v11, v24, v25
	v_cvt_pk_bf16_f32 v12, v18, v19
	v_cvt_pk_bf16_f32 v13, v20, v21
	v_lshl_add_u64 v[14:15], v[14:15], 0, v[144:145]
	v_cvt_pk_bf16_f32 v6, v6, v7
	v_cvt_pk_bf16_f32 v7, v8, v9
	v_cvt_pk_bf16_f32 v8, v2, v3
	v_cvt_pk_bf16_f32 v9, v4, v5
	s_and_b64 vcc, exec, s[0:1]
	s_mov_b32 s46, s42
	s_mov_b32 s47, s54
	s_mov_b64 s[70:71], s[64:65]
	s_mov_b64 s[68:69], s[62:63]
	global_store_dwordx4 v[124:125], v[126:129], off
	global_store_dwordx4 v[110:111], v[106:109], off
	global_store_dwordx4 v[94:95], v[90:93], off
	global_store_dwordx4 v[78:79], v[74:77], off
	global_store_dwordx4 v[78:79], v[70:73], off offset:256
	global_store_dwordx4 v[58:59], v[62:65], off
	global_store_dwordx4 v[46:47], v[42:45], off
	global_store_dwordx4 v[30:31], v[26:29], off
	global_store_dwordx4 v[14:15], v[10:13], off
	global_store_dwordx4 v[14:15], v[6:9], off offset:256
	s_cbranch_vccz .LBB0_721
	v_readlane_b32 s0, v254, 12
	s_waitcnt vmcnt(0)
	v_readlane_b32 s1, v254, 13
	s_andn2_b64 vcc, exec, s[0:1]
	s_cbranch_vccnz .LBB0_728
	s_barrier

.LBB0_977:
	s_add_u32 s2, s70, 0xfffc0080
	s_addc_u32 s17, s71, -1
	s_add_i32 s26, 0, 0x10000
	v_add_u32_e32 v152, s26, v163
	ds_read_b128 v[130:133], v152
	ds_read_b128 v[134:137], v152 offset:1024
	ds_read_b128 v[148:151], v152 offset:2048
	ds_read_b128 v[152:155], v152 offset:3072
	s_cmp_eq_u32 s44, 12
	s_cselect_b32 s75, s41, s17
	s_cselect_b32 s74, s24, s2
	s_cselect_b32 s73, s25, vcc_hi
	s_cselect_b32 s72, s93, vcc_lo
	v_lshl_add_u64 v[160:161], s[70:71], 0, v[144:145]
	s_add_i32 m0, s58, 0xc000
	ds_read_b128 v[156:159], v165
	ds_read_b128 v[188:191], v165 offset:1024
	ds_read_b128 v[192:195], v165 offset:2048
	ds_read_b128 v[196:199], v165 offset:3072
	ds_read_b128 v[200:203], v165 offset:4096
	ds_read_b128 v[216:219], v165 offset:5120
	ds_read_b128 v[220:223], v165 offset:6144
	ds_read_b128 v[224:227], v165 offset:7168
	global_load_lds_dwordx4 v[160:161], off
	v_lshl_add_u64 v[160:161], s[70:71], 0, v[146:147]
	s_add_i32 m0, s58, 0xe000
	s_nop 0
	global_load_lds_dwordx4 v[160:161], off
	s_waitcnt lgkmcnt(8)
	s_barrier
	s_waitcnt lgkmcnt(0)
	s_waitcnt lgkmcnt(0)
	v_mfma_f32_16x16x32_bf16 v[126:129], v[130:133], v[156:159], v[126:129]
	v_mfma_f32_16x16x32_bf16 v[122:125], v[148:151], v[156:159], v[122:125]
	v_mfma_f32_16x16x32_bf16 v[110:113], v[130:133], v[192:195], v[110:113]
	v_mfma_f32_16x16x32_bf16 v[106:109], v[148:151], v[192:195], v[106:109]
	v_mfma_f32_16x16x32_bf16 v[94:97], v[130:133], v[200:203], v[94:97]
	v_mfma_f32_16x16x32_bf16 v[90:93], v[148:151], v[200:203], v[90:93]
	v_mfma_f32_16x16x32_bf16 v[78:81], v[130:133], v[220:223], v[78:81]
	v_mfma_f32_16x16x32_bf16 v[74:77], v[148:151], v[220:223], v[74:77]
	v_mfma_f32_16x16x32_bf16 v[126:129], v[134:137], v[188:191], v[126:129]
	v_mfma_f32_16x16x32_bf16 v[122:125], v[152:155], v[188:191], v[122:125]
	v_mfma_f32_16x16x32_bf16 v[110:113], v[134:137], v[196:199], v[110:113]
	v_mfma_f32_16x16x32_bf16 v[106:109], v[152:155], v[196:199], v[106:109]
	v_mfma_f32_16x16x32_bf16 v[94:97], v[134:137], v[216:219], v[94:97]
	v_mfma_f32_16x16x32_bf16 v[90:93], v[152:155], v[216:219], v[90:93]
	v_mfma_f32_16x16x32_bf16 v[78:81], v[134:137], v[224:227], v[78:81]
	v_mfma_f32_16x16x32_bf16 v[74:77], v[152:155], v[224:227], v[74:77]
	s_barrier
	s_add_i32 s2, 0, 0x14000
	v_add_u32_e32 v160, s2, v163
	s_add_i32 s17, s26, s3
	ds_read_b128 v[228:231], v160
	ds_read_b128 v[232:235], v160 offset:1024
	ds_read_b128 v[236:239], v160 offset:2048
	ds_read_b128 v[240:243], v160 offset:3072
	v_lshl_add_u64 v[160:161], s[72:73], 0, v[0:1]
	s_mov_b32 m0, s17
	v_lshl_add_u64 v[204:205], s[72:73], 0, v[138:139]
	global_load_lds_dwordx4 v[160:161], off
	s_add_i32 m0, s17, 0x2000
	s_nop 0
	global_load_lds_dwordx4 v[204:205], off
	s_barrier
	s_waitcnt lgkmcnt(0)
	s_waitcnt lgkmcnt(0)
	v_mfma_f32_16x16x32_bf16 v[118:121], v[228:231], v[156:159], v[118:121]
	v_mfma_f32_16x16x32_bf16 v[114:117], v[236:239], v[156:159], v[114:117]
	v_mfma_f32_16x16x32_bf16 v[102:105], v[228:231], v[192:195], v[102:105]
	v_mfma_f32_16x16x32_bf16 v[98:101], v[236:239], v[192:195], v[98:101]
	v_mfma_f32_16x16x32_bf16 v[86:89], v[228:231], v[200:203], v[86:89]
	v_mfma_f32_16x16x32_bf16 v[82:85], v[236:239], v[200:203], v[82:85]
	v_mfma_f32_16x16x32_bf16 v[70:73], v[228:231], v[220:223], v[70:73]
	v_mfma_f32_16x16x32_bf16 v[66:69], v[236:239], v[220:223], v[66:69]
	v_mfma_f32_16x16x32_bf16 v[118:121], v[232:235], v[188:191], v[118:121]
	v_mfma_f32_16x16x32_bf16 v[114:117], v[240:243], v[188:191], v[114:117]
	v_mfma_f32_16x16x32_bf16 v[102:105], v[232:235], v[196:199], v[102:105]
	v_mfma_f32_16x16x32_bf16 v[98:101], v[240:243], v[196:199], v[98:101]
	v_mfma_f32_16x16x32_bf16 v[86:89], v[232:235], v[216:219], v[86:89]
	v_mfma_f32_16x16x32_bf16 v[82:85], v[240:243], v[216:219], v[82:85]
	v_mfma_f32_16x16x32_bf16 v[70:73], v[232:235], v[224:227], v[70:73]
	v_mfma_f32_16x16x32_bf16 v[66:69], v[240:243], v[224:227], v[66:69]
	s_mov_b32 m0, s58
	v_lshl_add_u64 v[244:245], s[74:75], 0, v[142:143]
	s_barrier
	ds_read_b128 v[156:159], v165 offset:16384
	ds_read_b128 v[188:191], v165 offset:17408
	ds_read_b128 v[192:195], v165 offset:18432
	ds_read_b128 v[196:199], v165 offset:19456
	ds_read_b128 v[200:203], v165 offset:20480
	ds_read_b128 v[216:219], v165 offset:21504
	ds_read_b128 v[220:223], v165 offset:22528
	ds_read_b128 v[224:227], v165 offset:23552
	global_load_lds_dwordx4 v[244:245], off
	v_lshl_add_u64 v[246:247], s[74:75], 0, v[140:141]
	s_mov_b32 m0, s76
	s_nop 0
	global_load_lds_dwordx4 v[246:247], off
	s_barrier
	s_waitcnt lgkmcnt(0)
	s_waitcnt lgkmcnt(0)
	v_mfma_f32_16x16x32_bf16 v[62:65], v[130:133], v[156:159], v[62:65]
	v_mfma_f32_16x16x32_bf16 v[58:61], v[148:151], v[156:159], v[58:61]
	v_mfma_f32_16x16x32_bf16 v[46:49], v[130:133], v[192:195], v[46:49]
	v_mfma_f32_16x16x32_bf16 v[42:45], v[148:151], v[192:195], v[42:45]
	v_mfma_f32_16x16x32_bf16 v[30:33], v[130:133], v[200:203], v[30:33]
	v_mfma_f32_16x16x32_bf16 v[26:29], v[148:151], v[200:203], v[26:29]
	v_mfma_f32_16x16x32_bf16 v[14:17], v[130:133], v[220:223], v[14:17]
	v_mfma_f32_16x16x32_bf16 v[10:13], v[148:151], v[220:223], v[10:13]
	v_mfma_f32_16x16x32_bf16 v[62:65], v[134:137], v[188:191], v[62:65]
	v_mfma_f32_16x16x32_bf16 v[58:61], v[152:155], v[188:191], v[58:61]
	v_mfma_f32_16x16x32_bf16 v[46:49], v[134:137], v[196:199], v[46:49]
	v_mfma_f32_16x16x32_bf16 v[42:45], v[152:155], v[196:199], v[42:45]
	v_mfma_f32_16x16x32_bf16 v[30:33], v[134:137], v[216:219], v[30:33]
	v_mfma_f32_16x16x32_bf16 v[26:29], v[152:155], v[216:219], v[26:29]
	v_mfma_f32_16x16x32_bf16 v[14:17], v[134:137], v[224:227], v[14:17]
	v_mfma_f32_16x16x32_bf16 v[10:13], v[152:155], v[224:227], v[10:13]
	s_barrier
	s_add_u32 s26, s72, 0x40000
	s_addc_u32 s27, s73, 0
	s_add_i32 s2, s2, s3
	v_lshl_add_u64 v[130:131], s[26:27], 0, v[0:1]
	s_mov_b32 m0, s2
	s_nop 0
	global_load_lds_dwordx4 v[130:131], off
	v_lshl_add_u64 v[130:131], s[26:27], 0, v[138:139]
	s_add_i32 m0, s2, 0x2000
	s_nop 0
	global_load_lds_dwordx4 v[130:131], off
	s_waitcnt vmcnt(6)
	s_barrier
	v_mfma_f32_16x16x32_bf16 v[54:57], v[228:231], v[156:159], v[54:57]
	v_mfma_f32_16x16x32_bf16 v[50:53], v[236:239], v[156:159], v[50:53]
	v_mfma_f32_16x16x32_bf16 v[38:41], v[228:231], v[192:195], v[38:41]
	v_mfma_f32_16x16x32_bf16 v[34:37], v[236:239], v[192:195], v[34:37]
	v_mfma_f32_16x16x32_bf16 v[22:25], v[228:231], v[200:203], v[22:25]
	v_mfma_f32_16x16x32_bf16 v[18:21], v[236:239], v[200:203], v[18:21]
	v_mfma_f32_16x16x32_bf16 v[6:9], v[228:231], v[220:223], v[6:9]
	v_mfma_f32_16x16x32_bf16 v[2:5], v[236:239], v[220:223], v[2:5]
	v_mfma_f32_16x16x32_bf16 v[54:57], v[232:235], v[188:191], v[54:57]
	v_mfma_f32_16x16x32_bf16 v[50:53], v[240:243], v[188:191], v[50:53]
	v_mfma_f32_16x16x32_bf16 v[38:41], v[232:235], v[196:199], v[38:41]
	v_mfma_f32_16x16x32_bf16 v[34:37], v[240:243], v[196:199], v[34:37]
	v_mfma_f32_16x16x32_bf16 v[22:25], v[232:235], v[216:219], v[22:25]
	v_mfma_f32_16x16x32_bf16 v[18:21], v[240:243], v[216:219], v[18:21]
	v_mfma_f32_16x16x32_bf16 v[6:9], v[232:235], v[224:227], v[6:9]
	v_mfma_f32_16x16x32_bf16 v[2:5], v[240:243], v[224:227], v[2:5]
	s_add_i32 s2, 0, 0x18000
	v_add_u32_e32 v152, s2, v163
	s_barrier
	ds_read_b128 v[130:133], v152
	ds_read_b128 v[134:137], v152 offset:1024
	ds_read_b128 v[148:151], v152 offset:2048
	ds_read_b128 v[152:155], v152 offset:3072
	s_add_u32 s26, s74, 0x40000
	s_addc_u32 s27, s75, 0
	s_mov_b32 m0, s77
	v_lshl_add_u64 v[228:229], s[26:27], 0, v[142:143]
	ds_read_b128 v[156:159], v165 offset:32768
	ds_read_b128 v[188:191], v165 offset:33792
	ds_read_b128 v[192:195], v165 offset:34816
	ds_read_b128 v[196:199], v165 offset:35840
	ds_read_b128 v[200:203], v165 offset:36864
	ds_read_b128 v[216:219], v165 offset:37888
	ds_read_b128 v[220:223], v165 offset:38912
	ds_read_b128 v[224:227], v165 offset:39936
	global_load_lds_dwordx4 v[228:229], off
	v_lshl_add_u64 v[228:229], s[26:27], 0, v[140:141]
	s_mov_b32 m0, s78
	s_nop 0
	global_load_lds_dwordx4 v[228:229], off
	s_waitcnt lgkmcnt(8)
	s_barrier
	s_waitcnt lgkmcnt(0)
	s_waitcnt lgkmcnt(0)
	v_mfma_f32_16x16x32_bf16 v[126:129], v[130:133], v[156:159], v[126:129]
	v_mfma_f32_16x16x32_bf16 v[122:125], v[148:151], v[156:159], v[122:125]
	v_mfma_f32_16x16x32_bf16 v[110:113], v[130:133], v[192:195], v[110:113]
	v_mfma_f32_16x16x32_bf16 v[106:109], v[148:151], v[192:195], v[106:109]
	v_mfma_f32_16x16x32_bf16 v[94:97], v[130:133], v[200:203], v[94:97]
	v_mfma_f32_16x16x32_bf16 v[90:93], v[148:151], v[200:203], v[90:93]
	v_mfma_f32_16x16x32_bf16 v[78:81], v[130:133], v[220:223], v[78:81]
	v_mfma_f32_16x16x32_bf16 v[74:77], v[148:151], v[220:223], v[74:77]
	v_mfma_f32_16x16x32_bf16 v[126:129], v[134:137], v[188:191], v[126:129]
	v_mfma_f32_16x16x32_bf16 v[122:125], v[152:155], v[188:191], v[122:125]
	v_mfma_f32_16x16x32_bf16 v[110:113], v[134:137], v[196:199], v[110:113]
	v_mfma_f32_16x16x32_bf16 v[106:109], v[152:155], v[196:199], v[106:109]
	v_mfma_f32_16x16x32_bf16 v[94:97], v[134:137], v[216:219], v[94:97]
	v_mfma_f32_16x16x32_bf16 v[90:93], v[152:155], v[216:219], v[90:93]
	v_mfma_f32_16x16x32_bf16 v[78:81], v[134:137], v[224:227], v[78:81]
	v_mfma_f32_16x16x32_bf16 v[74:77], v[152:155], v[224:227], v[74:77]
	s_barrier
	s_add_i32 s17, 0, 0x1c000
	s_add_i32 s2, s2, s3
	v_add_u32_e32 v206, s17, v163
	v_lshl_add_u64 v[160:161], v[160:161], 0, s[28:29]
	s_mov_b32 m0, s2
	ds_read_b128 v[228:231], v206
	ds_read_b128 v[232:235], v206 offset:1024
	ds_read_b128 v[236:239], v206 offset:2048
	ds_read_b128 v[240:243], v206 offset:3072
	global_load_lds_dwordx4 v[160:161], off
	v_lshl_add_u64 v[160:161], v[204:205], 0, s[28:29]
	s_add_i32 m0, s2, 0x2000
	s_nop 0
	global_load_lds_dwordx4 v[160:161], off
	s_barrier
	s_waitcnt lgkmcnt(0)
	s_waitcnt lgkmcnt(0)
	v_mfma_f32_16x16x32_bf16 v[118:121], v[228:231], v[156:159], v[118:121]
	v_mfma_f32_16x16x32_bf16 v[114:117], v[236:239], v[156:159], v[114:117]
	v_mfma_f32_16x16x32_bf16 v[102:105], v[228:231], v[192:195], v[102:105]
	v_mfma_f32_16x16x32_bf16 v[98:101], v[236:239], v[192:195], v[98:101]
	v_mfma_f32_16x16x32_bf16 v[86:89], v[228:231], v[200:203], v[86:89]
	v_mfma_f32_16x16x32_bf16 v[82:85], v[236:239], v[200:203], v[82:85]
	v_mfma_f32_16x16x32_bf16 v[70:73], v[228:231], v[220:223], v[70:73]
	v_mfma_f32_16x16x32_bf16 v[66:69], v[236:239], v[220:223], v[66:69]
	v_mfma_f32_16x16x32_bf16 v[118:121], v[232:235], v[188:191], v[118:121]
	v_mfma_f32_16x16x32_bf16 v[114:117], v[240:243], v[188:191], v[114:117]
	v_mfma_f32_16x16x32_bf16 v[102:105], v[232:235], v[196:199], v[102:105]
	v_mfma_f32_16x16x32_bf16 v[98:101], v[240:243], v[196:199], v[98:101]
	v_mfma_f32_16x16x32_bf16 v[86:89], v[232:235], v[216:219], v[86:89]
	v_mfma_f32_16x16x32_bf16 v[82:85], v[240:243], v[216:219], v[82:85]
	v_mfma_f32_16x16x32_bf16 v[70:73], v[232:235], v[224:227], v[70:73]
	v_mfma_f32_16x16x32_bf16 v[66:69], v[240:243], v[224:227], v[66:69]
	s_mov_b32 m0, s79
	v_lshl_add_u64 v[160:161], v[244:245], 0, s[28:29]
	s_barrier
	ds_read_b128 v[156:159], v165 offset:49152
	ds_read_b128 v[188:191], v165 offset:50176
	ds_read_b128 v[192:195], v165 offset:51200
	ds_read_b128 v[196:199], v165 offset:52224
	ds_read_b128 v[200:203], v165 offset:53248
	ds_read_b128 v[216:219], v165 offset:54272
	ds_read_b128 v[220:223], v165 offset:55296
	ds_read_b128 v[224:227], v165 offset:56320
	global_load_lds_dwordx4 v[160:161], off
	v_lshl_add_u64 v[160:161], v[246:247], 0, s[28:29]
	s_mov_b32 m0, s83
	s_nop 0
	global_load_lds_dwordx4 v[160:161], off
	s_barrier
	s_waitcnt lgkmcnt(0)
	s_waitcnt lgkmcnt(0)
	v_mfma_f32_16x16x32_bf16 v[62:65], v[130:133], v[156:159], v[62:65]
	v_mfma_f32_16x16x32_bf16 v[58:61], v[148:151], v[156:159], v[58:61]
	v_mfma_f32_16x16x32_bf16 v[46:49], v[130:133], v[192:195], v[46:49]
	v_mfma_f32_16x16x32_bf16 v[42:45], v[148:151], v[192:195], v[42:45]
	v_mfma_f32_16x16x32_bf16 v[30:33], v[130:133], v[200:203], v[30:33]
	v_mfma_f32_16x16x32_bf16 v[26:29], v[148:151], v[200:203], v[26:29]
	v_mfma_f32_16x16x32_bf16 v[14:17], v[130:133], v[220:223], v[14:17]
	v_mfma_f32_16x16x32_bf16 v[10:13], v[148:151], v[220:223], v[10:13]
	v_mfma_f32_16x16x32_bf16 v[62:65], v[134:137], v[188:191], v[62:65]
	v_mfma_f32_16x16x32_bf16 v[58:61], v[152:155], v[188:191], v[58:61]
	v_mfma_f32_16x16x32_bf16 v[46:49], v[134:137], v[196:199], v[46:49]
	v_mfma_f32_16x16x32_bf16 v[42:45], v[152:155], v[196:199], v[42:45]
	v_mfma_f32_16x16x32_bf16 v[30:33], v[134:137], v[216:219], v[30:33]
	v_mfma_f32_16x16x32_bf16 v[26:29], v[152:155], v[216:219], v[26:29]
	v_mfma_f32_16x16x32_bf16 v[14:17], v[134:137], v[224:227], v[14:17]
	v_mfma_f32_16x16x32_bf16 v[10:13], v[152:155], v[224:227], v[10:13]
	s_barrier
	s_add_u32 s26, s72, 0x40080
	s_addc_u32 s27, s73, 0
	s_add_i32 s2, s17, s3
	v_lshl_add_u64 v[130:131], s[26:27], 0, v[0:1]
	s_mov_b32 m0, s2
	s_nop 0
	global_load_lds_dwordx4 v[130:131], off
	v_lshl_add_u64 v[130:131], s[26:27], 0, v[138:139]
	s_add_i32 m0, s2, 0x2000
	s_nop 0
	global_load_lds_dwordx4 v[130:131], off
	s_waitcnt vmcnt(6)
	s_barrier
	v_mfma_f32_16x16x32_bf16 v[54:57], v[228:231], v[156:159], v[54:57]
	v_mfma_f32_16x16x32_bf16 v[50:53], v[236:239], v[156:159], v[50:53]
	v_mfma_f32_16x16x32_bf16 v[38:41], v[228:231], v[192:195], v[38:41]
	v_mfma_f32_16x16x32_bf16 v[34:37], v[236:239], v[192:195], v[34:37]
	v_mfma_f32_16x16x32_bf16 v[22:25], v[228:231], v[200:203], v[22:25]
	v_mfma_f32_16x16x32_bf16 v[18:21], v[236:239], v[200:203], v[18:21]
	v_mfma_f32_16x16x32_bf16 v[6:9], v[228:231], v[220:223], v[6:9]
	v_mfma_f32_16x16x32_bf16 v[2:5], v[236:239], v[220:223], v[2:5]
	v_mfma_f32_16x16x32_bf16 v[54:57], v[232:235], v[188:191], v[54:57]
	v_mfma_f32_16x16x32_bf16 v[50:53], v[240:243], v[188:191], v[50:53]
	v_mfma_f32_16x16x32_bf16 v[38:41], v[232:235], v[196:199], v[38:41]
	v_mfma_f32_16x16x32_bf16 v[34:37], v[240:243], v[196:199], v[34:37]
	v_mfma_f32_16x16x32_bf16 v[22:25], v[232:235], v[216:219], v[22:25]
	v_mfma_f32_16x16x32_bf16 v[18:21], v[240:243], v[216:219], v[18:21]
	v_mfma_f32_16x16x32_bf16 v[6:9], v[232:235], v[224:227], v[6:9]
	v_mfma_f32_16x16x32_bf16 v[2:5], v[240:243], v[224:227], v[2:5]
	s_add_i32 s44, s44, 2
	s_add_u32 s70, s70, 0x100
	s_addc_u32 s71, s71, 0
	s_add_u32 vcc_lo, vcc_lo, 0x100
	s_addc_u32 vcc_hi, vcc_hi, 0
	s_cmp_gt_u32 s44, 13
	s_barrier
	s_cbranch_scc0 .LBB0_977
	v_lshl_add_u32 v152, s47, 8, v162
	v_lshl_or_b32 v130, s46, 8, v164
	v_ashrrev_i32_e32 v153, 31, v152
	v_lshlrev_b64 v[136:137], 11, v[152:153]
	v_ashrrev_i32_e32 v131, 31, v130
	v_lshl_add_u64 v[136:137], s[56:57], 0, v[136:137]
	v_lshlrev_b64 v[150:151], 1, v[130:131]
	v_mov_b64_e32 v[154:155], s[22:23]
	v_lshl_add_u64 v[156:157], v[136:137], 0, v[150:151]
	v_mad_i64_i32 v[136:137], s[24:25], v152, s48, v[154:155]
	v_lshl_add_u64 v[160:161], v[136:137], 0, s[94:95]
	v_lshl_add_u64 v[148:149], v[130:131], 2, s[54:55]
	v_lshl_add_u64 v[136:137], v[160:161], 0, v[150:151]
	global_load_dwordx4 v[132:135], v[148:149], off offset:16
	global_load_dwordx4 v[188:191], v[148:149], off
	global_load_dwordx4 v[192:195], v[156:157], off
	global_load_dwordx4 v[196:199], v[136:137], off
	s_and_b64 vcc, exec, s[6:7]
	s_mov_b32 s46, s92
	s_mov_b32 s47, s40
	s_mov_b64 s[72:73], s[68:69]
	s_mov_b64 s[70:71], s[42:43]
	v_readlane_b32 s93, v251, 60
	s_waitcnt vmcnt(0)
	v_add_f32_e32 v122, v122, v132
	v_add_f32_e32 v126, v126, v188
	v_add_f32_e32 v127, v127, v189
	v_lshlrev_b32_e32 v158, 16, v196
	v_mul_f32_e32 v131, 0xbfb8aa3b, v158
	v_exp_f32_e32 v131, v131
	v_and_b32_e32 v159, 0xffff0000, v196
	v_mul_f32_e32 v126, 0xbfb8aa3b, v126
	v_mul_f32_e32 v127, 0xbfb8aa3b, v127
	v_add_f32_e32 v131, 1.0, v131
	v_rcp_f32_e32 v188, v131
	v_mul_f32_e32 v131, 0xbfb8aa3b, v159
	v_exp_f32_e32 v126, v126
	v_exp_f32_e32 v127, v127
	v_exp_f32_e32 v131, v131
	v_lshlrev_b32_e32 v136, 16, v192
	v_add_f32_e32 v126, 1.0, v126
	v_add_f32_e32 v127, 1.0, v127
	v_add_f32_e32 v131, 1.0, v131
	v_rcp_f32_e32 v126, v126
	v_rcp_f32_e32 v127, v127
	v_rcp_f32_e32 v189, v131
	v_and_b32_e32 v137, 0xffff0000, v192
	v_add_f32_e32 v123, v123, v133
	v_pk_mul_f32 v[126:127], v[126:127], v[136:137]
	v_pk_mul_f32 v[136:137], v[188:189], v[158:159]
	v_mul_f32_e32 v122, 0xbfb8aa3b, v122
	v_pk_mul_f32 v[126:127], v[126:127], v[136:137]
	v_lshlrev_b32_e32 v136, 16, v198
	v_mul_f32_e32 v131, 0xbfb8aa3b, v136
	v_exp_f32_e32 v131, v131
	v_and_b32_e32 v137, 0xffff0000, v198
	v_mul_f32_e32 v123, 0xbfb8aa3b, v123
	v_exp_f32_e32 v122, v122
	v_add_f32_e32 v131, 1.0, v131
	v_rcp_f32_e32 v158, v131
	v_mul_f32_e32 v131, 0xbfb8aa3b, v137
	v_exp_f32_e32 v123, v123
	v_exp_f32_e32 v131, v131
	v_add_f32_e32 v122, 1.0, v122
	v_rcp_f32_e32 v122, v122
	v_add_f32_e32 v123, 1.0, v123
	v_add_f32_e32 v131, 1.0, v131
	v_rcp_f32_e32 v123, v123
	v_rcp_f32_e32 v159, v131
	v_lshlrev_b32_e32 v132, 16, v194
	v_and_b32_e32 v133, 0xffff0000, v194
	v_pk_mul_f32 v[122:123], v[122:123], v[132:133]
	v_pk_mul_f32 v[132:133], v[158:159], v[136:137]
	v_lshlrev_b32_e32 v136, 16, v197
	v_pk_mul_f32 v[132:133], v[122:123], v[132:133]
	v_add_f32_e32 v123, v124, v134
	v_mul_f32_e32 v123, 0xbfb8aa3b, v123
	v_exp_f32_e32 v123, v123
	v_add_f32_e32 v122, v128, v190
	v_mul_f32_e32 v122, 0xbfb8aa3b, v122
	v_exp_f32_e32 v122, v122
	v_add_f32_e32 v123, 1.0, v123
	v_rcp_f32_e32 v124, v123
	v_add_f32_e32 v123, v129, v191
	v_mul_f32_e32 v123, 0xbfb8aa3b, v123
	v_exp_f32_e32 v123, v123
	v_add_f32_e32 v122, 1.0, v122
	v_rcp_f32_e32 v122, v122
	v_lshlrev_b32_e32 v128, 16, v193
	v_add_f32_e32 v123, 1.0, v123
	v_rcp_f32_e32 v123, v123
	v_and_b32_e32 v129, 0xffff0000, v193
	v_and_b32_e32 v137, 0xffff0000, v197
	v_mul_f32_e32 v131, 0xbfb8aa3b, v136
	v_pk_mul_f32 v[122:123], v[122:123], v[128:129]
	v_mul_f32_e32 v128, 0xbfb8aa3b, v137
	v_exp_f32_e32 v131, v131
	v_exp_f32_e32 v128, v128
	v_lshlrev_b32_e32 v134, 16, v199
	v_add_f32_e32 v131, 1.0, v131
	v_add_f32_e32 v128, 1.0, v128
	v_rcp_f32_e32 v158, v131
	v_rcp_f32_e32 v159, v128
	v_mul_f32_e32 v131, 0xbfb8aa3b, v134
	v_exp_f32_e32 v131, v131
	v_pk_mul_f32 v[128:129], v[158:159], v[136:137]
	s_nop 0
	v_pk_mul_f32 v[128:129], v[122:123], v[128:129]
	v_add_f32_e32 v122, v125, v135
	v_mul_f32_e32 v122, 0xbfb8aa3b, v122
	v_exp_f32_e32 v122, v122
	v_and_b32_e32 v123, 0xffff0000, v195
	v_and_b32_e32 v135, 0xffff0000, v199
	v_add_f32_e32 v131, 1.0, v131
	v_add_f32_e32 v122, 1.0, v122
	v_rcp_f32_e32 v125, v122
	v_lshlrev_b32_e32 v122, 16, v195
	v_rcp_f32_e32 v136, v131
	v_pk_mul_f32 v[122:123], v[124:125], v[122:123]
	v_mul_f32_e32 v124, 0xbfb8aa3b, v135
	v_exp_f32_e32 v124, v124
	s_nop 0
	v_add_f32_e32 v124, 1.0, v124
	v_rcp_f32_e32 v137, v124
	s_nop 0
	v_pk_mul_f32 v[124:125], v[136:137], v[134:135]
	s_nop 0
	v_pk_mul_f32 v[134:135], v[122:123], v[124:125]
	v_cvt_pk_bf16_f32 v122, v126, v127
	v_lshlrev_b64 v[126:127], 12, v[152:153]
	v_lshl_add_u64 v[126:127], s[36:37], 0, v[126:127]
	v_cvt_pk_bf16_f32 v123, v128, v129
	v_cvt_pk_bf16_f32 v124, v132, v133
	v_cvt_pk_bf16_f32 v125, v134, v135
	v_lshl_add_u64 v[158:159], v[126:127], 0, v[150:151]
	v_or_b32_e32 v126, 0x80, v130
	global_store_dwordx4 v[158:159], v[122:125], off offset:2048
	v_ashrrev_i32_e32 v127, 31, v126
	global_load_dwordx4 v[130:133], v[148:149], off offset:528
	global_load_dwordx4 v[134:137], v[148:149], off offset:512
	global_load_dwordx4 v[122:125], v[156:157], off offset:256
	v_lshlrev_b64 v[156:157], 1, v[126:127]
	v_lshl_add_u64 v[126:127], v[160:161], 0, v[156:157]
	global_load_dwordx4 v[126:129], v[126:127], off
	s_waitcnt vmcnt(0)
	v_add_f32_e32 v114, v114, v130
	v_add_f32_e32 v118, v118, v134
	v_add_f32_e32 v119, v119, v135
	v_lshlrev_b32_e32 v134, 16, v122
	v_and_b32_e32 v135, 0xffff0000, v122
	v_lshlrev_b32_e32 v160, 16, v126
	v_mul_f32_e32 v122, 0xbfb8aa3b, v160
	v_exp_f32_e32 v122, v122
	v_and_b32_e32 v161, 0xffff0000, v126
	v_mul_f32_e32 v118, 0xbfb8aa3b, v118
	v_mul_f32_e32 v119, 0xbfb8aa3b, v119
	v_add_f32_e32 v122, 1.0, v122
	v_rcp_f32_e32 v188, v122
	v_mul_f32_e32 v122, 0xbfb8aa3b, v161
	v_exp_f32_e32 v118, v118
	v_exp_f32_e32 v119, v119
	v_exp_f32_e32 v122, v122
	v_add_f32_e32 v120, v120, v136
	v_add_f32_e32 v118, 1.0, v118
	v_add_f32_e32 v119, 1.0, v119
	v_add_f32_e32 v122, 1.0, v122
	v_rcp_f32_e32 v118, v118
	v_rcp_f32_e32 v119, v119
	v_rcp_f32_e32 v189, v122
	v_add_f32_e32 v121, v121, v137
	v_mul_f32_e32 v120, 0xbfb8aa3b, v120
	v_pk_mul_f32 v[118:119], v[118:119], v[134:135]
	v_pk_mul_f32 v[134:135], v[188:189], v[160:161]
	v_mul_f32_e32 v121, 0xbfb8aa3b, v121
	v_pk_mul_f32 v[118:119], v[118:119], v[134:135]
	v_lshlrev_b32_e32 v134, 16, v128
	v_mul_f32_e32 v122, 0xbfb8aa3b, v134
	v_exp_f32_e32 v122, v122
	v_exp_f32_e32 v120, v120
	v_exp_f32_e32 v121, v121
	v_and_b32_e32 v135, 0xffff0000, v128
	v_add_f32_e32 v122, 1.0, v122
	v_rcp_f32_e32 v160, v122
	v_mul_f32_e32 v122, 0xbfb8aa3b, v135
	v_add_f32_e32 v115, v115, v131
	v_exp_f32_e32 v122, v122
	v_mul_f32_e32 v114, 0xbfb8aa3b, v114
	v_mul_f32_e32 v115, 0xbfb8aa3b, v115
	v_add_f32_e32 v120, 1.0, v120
	v_add_f32_e32 v121, 1.0, v121
	v_exp_f32_e32 v114, v114
	v_exp_f32_e32 v115, v115
	v_rcp_f32_e32 v120, v120
	v_rcp_f32_e32 v121, v121
	v_add_f32_e32 v122, 1.0, v122
	v_rcp_f32_e32 v161, v122
	v_lshlrev_b32_e32 v122, 16, v123
	v_and_b32_e32 v123, 0xffff0000, v123
	v_lshlrev_b32_e32 v126, 16, v127
	v_and_b32_e32 v127, 0xffff0000, v127
	v_add_f32_e32 v114, 1.0, v114
	v_add_f32_e32 v115, 1.0, v115
	v_lshlrev_b32_e32 v130, 16, v124
	v_and_b32_e32 v131, 0xffff0000, v124
	v_mul_f32_e32 v124, 0xbfb8aa3b, v126
	v_pk_mul_f32 v[120:121], v[120:121], v[122:123]
	v_mul_f32_e32 v122, 0xbfb8aa3b, v127
	v_rcp_f32_e32 v114, v114
	v_rcp_f32_e32 v115, v115
	v_add_f32_e32 v116, v116, v132
	v_exp_f32_e32 v124, v124
	v_exp_f32_e32 v122, v122
	v_add_f32_e32 v117, v117, v133
	v_mul_f32_e32 v116, 0xbfb8aa3b, v116
	v_mul_f32_e32 v117, 0xbfb8aa3b, v117
	v_exp_f32_e32 v116, v116
	v_exp_f32_e32 v117, v117
	v_pk_mul_f32 v[114:115], v[114:115], v[130:131]
	v_pk_mul_f32 v[130:131], v[160:161], v[134:135]
	v_add_f32_e32 v124, 1.0, v124
	v_add_f32_e32 v122, 1.0, v122
	v_pk_mul_f32 v[114:115], v[114:115], v[130:131]
	v_rcp_f32_e32 v130, v124
	v_rcp_f32_e32 v131, v122
	v_add_f32_e32 v116, 1.0, v116
	v_add_f32_e32 v117, 1.0, v117
	v_rcp_f32_e32 v116, v116
	v_rcp_f32_e32 v117, v117
	v_pk_mul_f32 v[122:123], v[130:131], v[126:127]
	v_lshlrev_b32_e32 v124, 16, v129
	v_pk_mul_f32 v[120:121], v[120:121], v[122:123]
	v_lshlrev_b32_e32 v122, 16, v125
	v_and_b32_e32 v123, 0xffff0000, v125
	v_and_b32_e32 v125, 0xffff0000, v129
	v_mul_f32_e32 v126, 0xbfb8aa3b, v124
	v_pk_mul_f32 v[116:117], v[116:117], v[122:123]
	v_mul_f32_e32 v122, 0xbfb8aa3b, v125
	v_exp_f32_e32 v126, v126
	v_exp_f32_e32 v122, v122
	v_or_b32_e32 v132, 16, v152
	v_ashrrev_i32_e32 v133, 31, v132
	v_add_f32_e32 v126, 1.0, v126
	v_add_f32_e32 v122, 1.0, v122
	v_rcp_f32_e32 v126, v126
	v_rcp_f32_e32 v127, v122
	s_nop 0
	v_pk_mul_f32 v[122:123], v[126:127], v[124:125]
	s_nop 0
	v_pk_mul_f32 v[122:123], v[116:117], v[122:123]
	v_cvt_pk_bf16_f32 v116, v118, v119
	v_cvt_pk_bf16_f32 v117, v120, v121
	v_cvt_pk_bf16_f32 v118, v114, v115
	v_cvt_pk_bf16_f32 v119, v122, v123
	global_store_dwordx4 v[158:159], v[116:119], off offset:2304
	global_load_dwordx4 v[114:117], v[148:149], off offset:16
	s_nop 0
	global_load_dwordx4 v[120:123], v[148:149], off
	v_lshlrev_b64 v[118:119], 11, v[132:133]
	v_lshl_add_u64 v[118:119], s[56:57], 0, v[118:119]
	v_lshl_add_u64 v[134:135], v[118:119], 0, v[150:151]
	v_mad_i64_i32 v[118:119], s[24:25], v132, s48, v[154:155]
	v_lshl_add_u64 v[118:119], v[118:119], 0, s[94:95]
	v_lshl_add_u64 v[128:129], v[118:119], 0, v[150:151]
	global_load_dwordx4 v[124:127], v[134:135], off
	v_lshl_add_u64 v[118:119], v[118:119], 0, v[156:157]
	global_load_dwordx4 v[128:131], v[128:129], off
	s_waitcnt vmcnt(0)
	v_add_f32_e32 v106, v106, v114
	v_add_f32_e32 v110, v110, v120
	v_add_f32_e32 v111, v111, v121
	v_mul_f32_e32 v110, 0xbfb8aa3b, v110
	v_mul_f32_e32 v111, 0xbfb8aa3b, v111
	v_exp_f32_e32 v110, v110
	v_exp_f32_e32 v111, v111
	v_add_f32_e32 v107, v107, v115
	v_mul_f32_e32 v106, 0xbfb8aa3b, v106
	v_mul_f32_e32 v107, 0xbfb8aa3b, v107
	v_exp_f32_e32 v106, v106
	v_lshlrev_b32_e32 v136, 16, v128
	v_mul_f32_e32 v114, 0xbfb8aa3b, v136
	v_exp_f32_e32 v114, v114
	v_and_b32_e32 v137, 0xffff0000, v128
	v_exp_f32_e32 v107, v107
	v_add_f32_e32 v110, 1.0, v110
	v_add_f32_e32 v114, 1.0, v114
	v_rcp_f32_e32 v158, v114
	v_mul_f32_e32 v114, 0xbfb8aa3b, v137
	v_exp_f32_e32 v114, v114
	v_add_f32_e32 v111, 1.0, v111
	v_rcp_f32_e32 v110, v110
	v_rcp_f32_e32 v111, v111
	v_add_f32_e32 v114, 1.0, v114
	v_rcp_f32_e32 v159, v114
	v_add_f32_e32 v106, 1.0, v106
	v_add_f32_e32 v107, 1.0, v107
	v_rcp_f32_e32 v106, v106
	v_rcp_f32_e32 v107, v107
	v_lshlrev_b32_e32 v120, 16, v124
	v_and_b32_e32 v121, 0xffff0000, v124
	v_pk_mul_f32 v[110:111], v[110:111], v[120:121]
	v_pk_mul_f32 v[120:121], v[158:159], v[136:137]
	v_lshlrev_b32_e32 v114, 16, v126
	v_pk_mul_f32 v[110:111], v[110:111], v[120:121]
	v_and_b32_e32 v115, 0xffff0000, v126
	v_lshlrev_b32_e32 v120, 16, v130
	v_and_b32_e32 v121, 0xffff0000, v130
	v_mul_f32_e32 v124, 0xbfb8aa3b, v120
	v_pk_mul_f32 v[106:107], v[106:107], v[114:115]
	v_mul_f32_e32 v114, 0xbfb8aa3b, v121
	v_exp_f32_e32 v124, v124
	v_exp_f32_e32 v114, v114
	v_add_f32_e32 v124, 1.0, v124
	v_add_f32_e32 v114, 1.0, v114
	v_rcp_f32_e32 v136, v124
	v_rcp_f32_e32 v137, v114
	s_nop 0
	v_pk_mul_f32 v[114:115], v[136:137], v[120:121]
	s_nop 0
	v_pk_mul_f32 v[114:115], v[106:107], v[114:115]
	v_add_f32_e32 v107, v108, v116
	v_mul_f32_e32 v107, 0xbfb8aa3b, v107
	v_exp_f32_e32 v107, v107
	v_add_f32_e32 v106, v112, v122
	v_mul_f32_e32 v106, 0xbfb8aa3b, v106
	v_exp_f32_e32 v106, v106
	v_add_f32_e32 v107, 1.0, v107
	v_rcp_f32_e32 v108, v107
	v_add_f32_e32 v107, v113, v123
	v_mul_f32_e32 v107, 0xbfb8aa3b, v107
	v_exp_f32_e32 v107, v107
	v_add_f32_e32 v106, 1.0, v106
	v_rcp_f32_e32 v106, v106
	v_lshlrev_b32_e32 v112, 16, v125
	v_add_f32_e32 v107, 1.0, v107
	v_rcp_f32_e32 v107, v107
	v_and_b32_e32 v113, 0xffff0000, v125
	v_lshlrev_b32_e32 v120, 16, v129
	v_and_b32_e32 v121, 0xffff0000, v129
	v_mul_f32_e32 v116, 0xbfb8aa3b, v120
	v_pk_mul_f32 v[106:107], v[106:107], v[112:113]
	v_mul_f32_e32 v112, 0xbfb8aa3b, v121
	v_exp_f32_e32 v116, v116
	v_exp_f32_e32 v112, v112
	v_add_f32_e32 v116, 1.0, v116
	v_add_f32_e32 v112, 1.0, v112
	v_rcp_f32_e32 v122, v116
	v_rcp_f32_e32 v123, v112
	v_lshlrev_b32_e32 v116, 16, v131
	v_pk_mul_f32 v[112:113], v[122:123], v[120:121]
	s_nop 0
	v_pk_mul_f32 v[112:113], v[106:107], v[112:113]
	v_add_f32_e32 v106, v109, v117
	v_mul_f32_e32 v106, 0xbfb8aa3b, v106
	v_exp_f32_e32 v106, v106
	v_and_b32_e32 v107, 0xffff0000, v127
	v_and_b32_e32 v117, 0xffff0000, v131
	v_mul_f32_e32 v120, 0xbfb8aa3b, v116
	v_add_f32_e32 v106, 1.0, v106
	v_rcp_f32_e32 v109, v106
	v_lshlrev_b32_e32 v106, 16, v127
	v_exp_f32_e32 v120, v120
	v_pk_mul_f32 v[106:107], v[108:109], v[106:107]
	v_mul_f32_e32 v108, 0xbfb8aa3b, v117
	v_exp_f32_e32 v108, v108
	v_add_f32_e32 v120, 1.0, v120
	v_rcp_f32_e32 v120, v120
	v_add_f32_e32 v108, 1.0, v108
	v_rcp_f32_e32 v121, v108
	s_nop 0
	v_pk_mul_f32 v[108:109], v[120:121], v[116:117]
	s_nop 0
	v_pk_mul_f32 v[116:117], v[106:107], v[108:109]
	v_cvt_pk_bf16_f32 v106, v110, v111
	v_lshlrev_b64 v[110:111], 12, v[132:133]
	v_lshl_add_u64 v[110:111], s[36:37], 0, v[110:111]
	v_cvt_pk_bf16_f32 v107, v112, v113
	v_cvt_pk_bf16_f32 v108, v114, v115
	v_cvt_pk_bf16_f32 v109, v116, v117
	v_lshl_add_u64 v[122:123], v[110:111], 0, v[150:151]
	global_store_dwordx4 v[122:123], v[106:109], off offset:2048
	global_load_dwordx4 v[110:113], v[148:149], off offset:528
	global_load_dwordx4 v[114:117], v[148:149], off offset:512
	s_nop 0
	global_load_dwordx4 v[106:109], v[134:135], off offset:256
	s_waitcnt vmcnt(0)
	v_add_f32_e32 v98, v98, v110
	global_load_dwordx4 v[118:121], v[118:119], off
	v_add_f32_e32 v102, v102, v114
	v_add_f32_e32 v103, v103, v115
	v_lshlrev_b32_e32 v114, 16, v106
	v_and_b32_e32 v115, 0xffff0000, v106
	v_mul_f32_e32 v102, 0xbfb8aa3b, v102
	v_mul_f32_e32 v103, 0xbfb8aa3b, v103
	v_exp_f32_e32 v102, v102
	v_exp_f32_e32 v103, v103
	v_add_f32_e32 v99, v99, v111
	v_mul_f32_e32 v98, 0xbfb8aa3b, v98
	v_add_f32_e32 v102, 1.0, v102
	v_add_f32_e32 v103, 1.0, v103
	v_rcp_f32_e32 v102, v102
	v_rcp_f32_e32 v103, v103
	v_mul_f32_e32 v99, 0xbfb8aa3b, v99
	v_exp_f32_e32 v98, v98
	v_exp_f32_e32 v99, v99
	v_pk_mul_f32 v[102:103], v[102:103], v[114:115]
	v_lshlrev_b32_e32 v110, 16, v108
	v_add_f32_e32 v98, 1.0, v98
	v_add_f32_e32 v99, 1.0, v99
	v_rcp_f32_e32 v98, v98
	v_rcp_f32_e32 v99, v99
	v_and_b32_e32 v111, 0xffff0000, v108
	v_pk_mul_f32 v[98:99], v[98:99], v[110:111]
	s_waitcnt vmcnt(0)
	v_lshlrev_b32_e32 v124, 16, v118
	v_mul_f32_e32 v106, 0xbfb8aa3b, v124
	v_exp_f32_e32 v106, v106
	v_and_b32_e32 v125, 0xffff0000, v118
	v_or_b32_e32 v118, 32, v152
	v_add_f32_e32 v106, 1.0, v106
	v_rcp_f32_e32 v126, v106
	v_mul_f32_e32 v106, 0xbfb8aa3b, v125
	v_exp_f32_e32 v106, v106
	s_nop 0
	v_add_f32_e32 v106, 1.0, v106
	v_rcp_f32_e32 v127, v106
	s_nop 0
	v_pk_mul_f32 v[114:115], v[126:127], v[124:125]
	s_nop 0
	v_pk_mul_f32 v[102:103], v[102:103], v[114:115]
	v_lshlrev_b32_e32 v114, 16, v120
	v_mul_f32_e32 v106, 0xbfb8aa3b, v114
	v_exp_f32_e32 v106, v106
	v_and_b32_e32 v115, 0xffff0000, v120
	v_add_f32_e32 v106, 1.0, v106
	v_rcp_f32_e32 v124, v106
	v_mul_f32_e32 v106, 0xbfb8aa3b, v115
	v_exp_f32_e32 v106, v106
	s_nop 0
	v_add_f32_e32 v106, 1.0, v106
	v_rcp_f32_e32 v125, v106
	v_lshlrev_b32_e32 v106, 16, v119
	v_mul_f32_e32 v108, 0xbfb8aa3b, v106
	v_exp_f32_e32 v108, v108
	v_pk_mul_f32 v[110:111], v[124:125], v[114:115]
	v_add_f32_e32 v108, 1.0, v108
	v_pk_mul_f32 v[110:111], v[98:99], v[110:111]
	v_add_f32_e32 v99, v100, v112
	v_mul_f32_e32 v99, 0xbfb8aa3b, v99
	v_exp_f32_e32 v99, v99
	v_add_f32_e32 v98, v104, v116
	v_mul_f32_e32 v98, 0xbfb8aa3b, v98
	v_exp_f32_e32 v98, v98
	v_add_f32_e32 v99, 1.0, v99
	v_rcp_f32_e32 v100, v99
	v_add_f32_e32 v99, v105, v117
	v_mul_f32_e32 v99, 0xbfb8aa3b, v99
	v_exp_f32_e32 v99, v99
	v_add_f32_e32 v98, 1.0, v98
	v_rcp_f32_e32 v98, v98
	v_lshlrev_b32_e32 v104, 16, v107
	v_add_f32_e32 v99, 1.0, v99
	v_rcp_f32_e32 v99, v99
	v_and_b32_e32 v105, 0xffff0000, v107
	v_and_b32_e32 v107, 0xffff0000, v119
	v_rcp_f32_e32 v114, v108
	v_pk_mul_f32 v[98:99], v[98:99], v[104:105]
	v_mul_f32_e32 v104, 0xbfb8aa3b, v107
	v_exp_f32_e32 v104, v104
	v_ashrrev_i32_e32 v119, 31, v118
	v_add_f32_e32 v104, 1.0, v104
	v_rcp_f32_e32 v115, v104
	s_nop 0
	v_pk_mul_f32 v[104:105], v[114:115], v[106:107]
	s_nop 0
	v_pk_mul_f32 v[104:105], v[98:99], v[104:105]
	v_add_f32_e32 v98, v101, v113
	v_mul_f32_e32 v98, 0xbfb8aa3b, v98
	v_exp_f32_e32 v98, v98
	v_and_b32_e32 v99, 0xffff0000, v109
	v_lshlrev_b32_e32 v106, 16, v121
	v_and_b32_e32 v107, 0xffff0000, v121
	v_add_f32_e32 v98, 1.0, v98
	v_rcp_f32_e32 v101, v98
	v_lshlrev_b32_e32 v98, 16, v109
	v_mul_f32_e32 v108, 0xbfb8aa3b, v106
	v_exp_f32_e32 v108, v108
	v_pk_mul_f32 v[98:99], v[100:101], v[98:99]
	v_mul_f32_e32 v100, 0xbfb8aa3b, v107
	v_exp_f32_e32 v100, v100
	v_add_f32_e32 v108, 1.0, v108
	v_rcp_f32_e32 v108, v108
	v_add_f32_e32 v100, 1.0, v100
	v_rcp_f32_e32 v109, v100
	s_nop 0
	v_pk_mul_f32 v[100:101], v[108:109], v[106:107]
	s_nop 0
	v_pk_mul_f32 v[106:107], v[98:99], v[100:101]
	v_cvt_pk_bf16_f32 v98, v102, v103
	v_cvt_pk_bf16_f32 v99, v104, v105
	v_cvt_pk_bf16_f32 v100, v110, v111
	v_cvt_pk_bf16_f32 v101, v106, v107
	global_store_dwordx4 v[122:123], v[98:101], off offset:2304
	global_load_dwordx4 v[102:105], v[148:149], off offset:16
	global_load_dwordx4 v[106:109], v[148:149], off
	v_lshlrev_b64 v[98:99], 11, v[118:119]
	v_lshl_add_u64 v[98:99], s[56:57], 0, v[98:99]
	v_lshl_add_u64 v[100:101], v[98:99], 0, v[150:151]
	v_mad_i64_i32 v[98:99], s[24:25], v118, s48, v[154:155]
	v_lshl_add_u64 v[98:99], v[98:99], 0, s[94:95]
	v_lshl_add_u64 v[114:115], v[98:99], 0, v[150:151]
	global_load_dwordx4 v[110:113], v[100:101], off
	v_lshl_add_u64 v[98:99], v[98:99], 0, v[156:157]
	global_load_dwordx4 v[114:117], v[114:115], off
	s_waitcnt vmcnt(0)
	v_add_f32_e32 v90, v90, v102
	v_add_f32_e32 v94, v94, v106
	v_add_f32_e32 v95, v95, v107
	v_mul_f32_e32 v94, 0xbfb8aa3b, v94
	v_mul_f32_e32 v95, 0xbfb8aa3b, v95
	v_exp_f32_e32 v94, v94
	v_exp_f32_e32 v95, v95
	v_add_f32_e32 v91, v91, v103
	v_mul_f32_e32 v90, 0xbfb8aa3b, v90
	v_mul_f32_e32 v91, 0xbfb8aa3b, v91
	v_exp_f32_e32 v90, v90
	v_lshlrev_b32_e32 v120, 16, v114
	v_mul_f32_e32 v102, 0xbfb8aa3b, v120
	v_exp_f32_e32 v102, v102
	v_and_b32_e32 v121, 0xffff0000, v114
	v_exp_f32_e32 v91, v91
	v_add_f32_e32 v94, 1.0, v94
	v_add_f32_e32 v102, 1.0, v102
	v_rcp_f32_e32 v122, v102
	v_mul_f32_e32 v102, 0xbfb8aa3b, v121
	v_exp_f32_e32 v102, v102
	v_add_f32_e32 v95, 1.0, v95
	v_rcp_f32_e32 v94, v94
	v_rcp_f32_e32 v95, v95
	v_add_f32_e32 v102, 1.0, v102
	v_rcp_f32_e32 v123, v102
	v_add_f32_e32 v90, 1.0, v90
	v_add_f32_e32 v91, 1.0, v91
	v_rcp_f32_e32 v90, v90
	v_rcp_f32_e32 v91, v91
	v_lshlrev_b32_e32 v106, 16, v110
	v_and_b32_e32 v107, 0xffff0000, v110
	v_pk_mul_f32 v[94:95], v[94:95], v[106:107]
	v_pk_mul_f32 v[106:107], v[122:123], v[120:121]
	v_lshlrev_b32_e32 v102, 16, v112
	v_pk_mul_f32 v[94:95], v[94:95], v[106:107]
	v_and_b32_e32 v103, 0xffff0000, v112
	v_lshlrev_b32_e32 v106, 16, v116
	v_and_b32_e32 v107, 0xffff0000, v116
	v_mul_f32_e32 v110, 0xbfb8aa3b, v106
	v_pk_mul_f32 v[90:91], v[90:91], v[102:103]
	v_mul_f32_e32 v102, 0xbfb8aa3b, v107
	v_exp_f32_e32 v110, v110
	v_exp_f32_e32 v102, v102
	v_add_f32_e32 v110, 1.0, v110
	v_add_f32_e32 v102, 1.0, v102
	v_rcp_f32_e32 v120, v110
	v_rcp_f32_e32 v121, v102
	s_nop 0
	v_pk_mul_f32 v[102:103], v[120:121], v[106:107]
	s_nop 0
	v_pk_mul_f32 v[102:103], v[90:91], v[102:103]
	v_add_f32_e32 v91, v92, v104
	v_mul_f32_e32 v91, 0xbfb8aa3b, v91
	v_exp_f32_e32 v91, v91
	v_add_f32_e32 v90, v96, v108
	v_mul_f32_e32 v90, 0xbfb8aa3b, v90
	v_exp_f32_e32 v90, v90
	v_add_f32_e32 v91, 1.0, v91
	v_rcp_f32_e32 v92, v91
	v_add_f32_e32 v91, v97, v109
	v_mul_f32_e32 v91, 0xbfb8aa3b, v91
	v_exp_f32_e32 v91, v91
	v_add_f32_e32 v90, 1.0, v90
	v_rcp_f32_e32 v90, v90
	v_lshlrev_b32_e32 v96, 16, v111
	v_add_f32_e32 v91, 1.0, v91
	v_rcp_f32_e32 v91, v91
	v_and_b32_e32 v97, 0xffff0000, v111
	v_lshlrev_b32_e32 v106, 16, v115
	v_and_b32_e32 v107, 0xffff0000, v115
	v_mul_f32_e32 v104, 0xbfb8aa3b, v106
	v_pk_mul_f32 v[90:91], v[90:91], v[96:97]
	v_mul_f32_e32 v96, 0xbfb8aa3b, v107
	v_exp_f32_e32 v104, v104
	v_exp_f32_e32 v96, v96
	v_add_f32_e32 v104, 1.0, v104
	v_add_f32_e32 v96, 1.0, v96
	v_rcp_f32_e32 v108, v104
	v_rcp_f32_e32 v109, v96
	v_lshlrev_b32_e32 v104, 16, v117
	v_pk_mul_f32 v[96:97], v[108:109], v[106:107]
	s_nop 0
	v_pk_mul_f32 v[96:97], v[90:91], v[96:97]
	v_add_f32_e32 v90, v93, v105
	v_mul_f32_e32 v90, 0xbfb8aa3b, v90
	v_exp_f32_e32 v90, v90
	v_and_b32_e32 v91, 0xffff0000, v113
	v_and_b32_e32 v105, 0xffff0000, v117
	v_mul_f32_e32 v106, 0xbfb8aa3b, v104
	v_add_f32_e32 v90, 1.0, v90
	v_rcp_f32_e32 v93, v90
	v_lshlrev_b32_e32 v90, 16, v113
	v_exp_f32_e32 v106, v106
	v_pk_mul_f32 v[90:91], v[92:93], v[90:91]
	v_mul_f32_e32 v92, 0xbfb8aa3b, v105
	v_exp_f32_e32 v92, v92
	v_add_f32_e32 v106, 1.0, v106
	v_rcp_f32_e32 v106, v106
	v_add_f32_e32 v92, 1.0, v92
	v_rcp_f32_e32 v107, v92
	s_nop 0
	v_pk_mul_f32 v[92:93], v[106:107], v[104:105]
	s_nop 0
	v_pk_mul_f32 v[104:105], v[90:91], v[92:93]
	v_cvt_pk_bf16_f32 v90, v94, v95
	v_lshlrev_b64 v[94:95], 12, v[118:119]
	v_lshl_add_u64 v[94:95], s[36:37], 0, v[94:95]
	v_cvt_pk_bf16_f32 v91, v96, v97
	v_cvt_pk_bf16_f32 v92, v102, v103
	v_cvt_pk_bf16_f32 v93, v104, v105
	v_lshl_add_u64 v[106:107], v[94:95], 0, v[150:151]
	global_store_dwordx4 v[106:107], v[90:93], off offset:2048
	global_load_dwordx4 v[90:93], v[148:149], off offset:528
	s_nop 0
	global_load_dwordx4 v[94:97], v[148:149], off offset:512
	global_load_dwordx4 v[102:105], v[100:101], off offset:256
	s_waitcnt vmcnt(0)
	v_add_f32_e32 v82, v82, v90
	global_load_dwordx4 v[98:101], v[98:99], off
	v_add_f32_e32 v86, v86, v94
	v_add_f32_e32 v87, v87, v95
	v_mul_f32_e32 v86, 0xbfb8aa3b, v86
	v_mul_f32_e32 v87, 0xbfb8aa3b, v87
	v_exp_f32_e32 v86, v86
	v_exp_f32_e32 v87, v87
	v_add_f32_e32 v83, v83, v91
	v_mul_f32_e32 v82, 0xbfb8aa3b, v82
	v_mul_f32_e32 v83, 0xbfb8aa3b, v83
	v_exp_f32_e32 v82, v82
	v_exp_f32_e32 v83, v83
	v_add_f32_e32 v86, 1.0, v86
	v_add_f32_e32 v87, 1.0, v87
	v_rcp_f32_e32 v86, v86
	v_rcp_f32_e32 v87, v87
	v_add_f32_e32 v82, 1.0, v82
	v_add_f32_e32 v83, 1.0, v83
	v_rcp_f32_e32 v82, v82
	v_rcp_f32_e32 v83, v83
	v_lshlrev_b32_e32 v94, 16, v102
	v_and_b32_e32 v95, 0xffff0000, v102
	v_pk_mul_f32 v[86:87], v[86:87], v[94:95]
	v_and_b32_e32 v91, 0xffff0000, v104
	v_or_b32_e32 v102, 48, v152
	s_waitcnt vmcnt(0)
	v_lshlrev_b32_e32 v108, 16, v98
	v_mul_f32_e32 v90, 0xbfb8aa3b, v108
	v_exp_f32_e32 v90, v90
	v_and_b32_e32 v109, 0xffff0000, v98
	v_add_f32_e32 v90, 1.0, v90
	v_rcp_f32_e32 v110, v90
	v_mul_f32_e32 v90, 0xbfb8aa3b, v109
	v_exp_f32_e32 v90, v90
	s_nop 0
	v_add_f32_e32 v90, 1.0, v90
	v_rcp_f32_e32 v111, v90
	v_lshlrev_b32_e32 v90, 16, v104
	v_pk_mul_f32 v[82:83], v[82:83], v[90:91]
	v_pk_mul_f32 v[94:95], v[110:111], v[108:109]
	s_nop 0
	v_pk_mul_f32 v[86:87], v[86:87], v[94:95]
	v_lshlrev_b32_e32 v94, 16, v100
	v_and_b32_e32 v95, 0xffff0000, v100
	v_mul_f32_e32 v98, 0xbfb8aa3b, v94
	v_mul_f32_e32 v90, 0xbfb8aa3b, v95
	v_exp_f32_e32 v98, v98
	v_exp_f32_e32 v90, v90
	v_add_f32_e32 v98, 1.0, v98
	v_add_f32_e32 v90, 1.0, v90
	v_rcp_f32_e32 v108, v98
	v_rcp_f32_e32 v109, v90
	s_nop 0
	v_pk_mul_f32 v[90:91], v[108:109], v[94:95]
	s_nop 0
	v_pk_mul_f32 v[90:91], v[82:83], v[90:91]
	v_add_f32_e32 v83, v84, v92
	v_mul_f32_e32 v83, 0xbfb8aa3b, v83
	v_exp_f32_e32 v83, v83
	v_add_f32_e32 v82, v88, v96
	v_mul_f32_e32 v82, 0xbfb8aa3b, v82
	v_exp_f32_e32 v82, v82
	v_add_f32_e32 v83, 1.0, v83
	v_rcp_f32_e32 v84, v83
	v_add_f32_e32 v83, v89, v97
	v_mul_f32_e32 v83, 0xbfb8aa3b, v83
	v_exp_f32_e32 v83, v83
	v_add_f32_e32 v82, 1.0, v82
	v_rcp_f32_e32 v82, v82
	v_lshlrev_b32_e32 v88, 16, v103
	v_add_f32_e32 v83, 1.0, v83
	v_rcp_f32_e32 v83, v83
	v_and_b32_e32 v89, 0xffff0000, v103
	v_lshlrev_b32_e32 v94, 16, v99
	v_and_b32_e32 v95, 0xffff0000, v99
	v_mul_f32_e32 v92, 0xbfb8aa3b, v94
	v_pk_mul_f32 v[82:83], v[82:83], v[88:89]
	v_mul_f32_e32 v88, 0xbfb8aa3b, v95
	v_exp_f32_e32 v92, v92
	v_exp_f32_e32 v88, v88
	v_ashrrev_i32_e32 v103, 31, v102
	v_add_f32_e32 v92, 1.0, v92
	v_add_f32_e32 v88, 1.0, v88
	v_rcp_f32_e32 v96, v92
	v_rcp_f32_e32 v97, v88
	v_lshlrev_b32_e32 v92, 16, v101
	v_pk_mul_f32 v[88:89], v[96:97], v[94:95]
	s_nop 0
	v_pk_mul_f32 v[88:89], v[82:83], v[88:89]
	v_add_f32_e32 v82, v85, v93
	v_mul_f32_e32 v82, 0xbfb8aa3b, v82
	v_exp_f32_e32 v82, v82
	v_and_b32_e32 v83, 0xffff0000, v105
	v_and_b32_e32 v93, 0xffff0000, v101
	v_mul_f32_e32 v94, 0xbfb8aa3b, v92
	v_add_f32_e32 v82, 1.0, v82
	v_rcp_f32_e32 v85, v82
	v_lshlrev_b32_e32 v82, 16, v105
	v_exp_f32_e32 v94, v94
	v_pk_mul_f32 v[82:83], v[84:85], v[82:83]
	v_mul_f32_e32 v84, 0xbfb8aa3b, v93
	v_exp_f32_e32 v84, v84
	v_add_f32_e32 v94, 1.0, v94
	v_rcp_f32_e32 v94, v94
	v_add_f32_e32 v84, 1.0, v84
	v_rcp_f32_e32 v95, v84
	s_nop 0
	v_pk_mul_f32 v[84:85], v[94:95], v[92:93]
	s_nop 0
	v_pk_mul_f32 v[92:93], v[82:83], v[84:85]
	v_cvt_pk_bf16_f32 v82, v86, v87
	v_cvt_pk_bf16_f32 v83, v88, v89
	v_cvt_pk_bf16_f32 v84, v90, v91
	v_cvt_pk_bf16_f32 v85, v92, v93
	global_store_dwordx4 v[106:107], v[82:85], off offset:2304
	global_load_dwordx4 v[86:89], v[148:149], off offset:16
	global_load_dwordx4 v[90:93], v[148:149], off
	v_lshlrev_b64 v[82:83], 11, v[102:103]
	v_lshl_add_u64 v[82:83], s[56:57], 0, v[82:83]
	v_lshl_add_u64 v[84:85], v[82:83], 0, v[150:151]
	v_mad_i64_i32 v[82:83], s[24:25], v102, s48, v[154:155]
	v_lshl_add_u64 v[82:83], v[82:83], 0, s[94:95]
	v_lshl_add_u64 v[98:99], v[82:83], 0, v[150:151]
	global_load_dwordx4 v[94:97], v[84:85], off
	v_lshl_add_u64 v[82:83], v[82:83], 0, v[156:157]
	global_load_dwordx4 v[98:101], v[98:99], off
	s_waitcnt vmcnt(0)
	v_add_f32_e32 v74, v74, v86
	v_add_f32_e32 v78, v78, v90
	v_add_f32_e32 v79, v79, v91
	v_mul_f32_e32 v78, 0xbfb8aa3b, v78
	v_mul_f32_e32 v79, 0xbfb8aa3b, v79
	v_exp_f32_e32 v78, v78
	v_exp_f32_e32 v79, v79
	v_add_f32_e32 v75, v75, v87
	v_mul_f32_e32 v74, 0xbfb8aa3b, v74
	v_mul_f32_e32 v75, 0xbfb8aa3b, v75
	v_exp_f32_e32 v74, v74
	v_lshlrev_b32_e32 v104, 16, v98
	v_mul_f32_e32 v86, 0xbfb8aa3b, v104
	v_exp_f32_e32 v86, v86
	v_and_b32_e32 v105, 0xffff0000, v98
	v_exp_f32_e32 v75, v75
	v_add_f32_e32 v78, 1.0, v78
	v_add_f32_e32 v86, 1.0, v86
	v_rcp_f32_e32 v106, v86
	v_mul_f32_e32 v86, 0xbfb8aa3b, v105
	v_exp_f32_e32 v86, v86
	v_add_f32_e32 v79, 1.0, v79
	v_rcp_f32_e32 v78, v78
	v_rcp_f32_e32 v79, v79
	v_add_f32_e32 v86, 1.0, v86
	v_rcp_f32_e32 v107, v86
	v_add_f32_e32 v74, 1.0, v74
	v_add_f32_e32 v75, 1.0, v75
	v_rcp_f32_e32 v74, v74
	v_rcp_f32_e32 v75, v75
	v_lshlrev_b32_e32 v90, 16, v94
	v_and_b32_e32 v91, 0xffff0000, v94
	v_pk_mul_f32 v[78:79], v[78:79], v[90:91]
	v_pk_mul_f32 v[90:91], v[106:107], v[104:105]
	v_lshlrev_b32_e32 v86, 16, v96
	v_pk_mul_f32 v[78:79], v[78:79], v[90:91]
	v_and_b32_e32 v87, 0xffff0000, v96
	v_lshlrev_b32_e32 v90, 16, v100
	v_and_b32_e32 v91, 0xffff0000, v100
	v_mul_f32_e32 v94, 0xbfb8aa3b, v90
	v_pk_mul_f32 v[74:75], v[74:75], v[86:87]
	v_mul_f32_e32 v86, 0xbfb8aa3b, v91
	v_exp_f32_e32 v94, v94
	v_exp_f32_e32 v86, v86
	v_add_f32_e32 v94, 1.0, v94
	v_add_f32_e32 v86, 1.0, v86
	v_rcp_f32_e32 v104, v94
	v_rcp_f32_e32 v105, v86
	s_nop 0
	v_pk_mul_f32 v[86:87], v[104:105], v[90:91]
	s_nop 0
	v_pk_mul_f32 v[86:87], v[74:75], v[86:87]
	v_add_f32_e32 v75, v76, v88
	v_mul_f32_e32 v75, 0xbfb8aa3b, v75
	v_exp_f32_e32 v75, v75
	v_add_f32_e32 v74, v80, v92
	v_mul_f32_e32 v74, 0xbfb8aa3b, v74
	v_exp_f32_e32 v74, v74
	v_add_f32_e32 v75, 1.0, v75
	v_rcp_f32_e32 v76, v75
	v_add_f32_e32 v75, v81, v93
	v_mul_f32_e32 v75, 0xbfb8aa3b, v75
	v_exp_f32_e32 v75, v75
	v_add_f32_e32 v74, 1.0, v74
	v_rcp_f32_e32 v74, v74
	v_lshlrev_b32_e32 v80, 16, v95
	v_add_f32_e32 v75, 1.0, v75
	v_rcp_f32_e32 v75, v75
	v_and_b32_e32 v81, 0xffff0000, v95
	v_lshlrev_b32_e32 v90, 16, v99
	v_and_b32_e32 v91, 0xffff0000, v99
	v_mul_f32_e32 v88, 0xbfb8aa3b, v90
	v_pk_mul_f32 v[74:75], v[74:75], v[80:81]
	v_mul_f32_e32 v80, 0xbfb8aa3b, v91
	v_exp_f32_e32 v88, v88
	v_exp_f32_e32 v80, v80
	v_add_f32_e32 v88, 1.0, v88
	v_add_f32_e32 v80, 1.0, v80
	v_rcp_f32_e32 v92, v88
	v_rcp_f32_e32 v93, v80
	v_lshlrev_b32_e32 v88, 16, v101
	v_pk_mul_f32 v[80:81], v[92:93], v[90:91]
	s_nop 0
	v_pk_mul_f32 v[80:81], v[74:75], v[80:81]
	v_add_f32_e32 v74, v77, v89
	v_mul_f32_e32 v74, 0xbfb8aa3b, v74
	v_exp_f32_e32 v74, v74
	v_and_b32_e32 v75, 0xffff0000, v97
	v_and_b32_e32 v89, 0xffff0000, v101
	v_mul_f32_e32 v90, 0xbfb8aa3b, v88
	v_add_f32_e32 v74, 1.0, v74
	v_rcp_f32_e32 v77, v74
	v_lshlrev_b32_e32 v74, 16, v97
	v_exp_f32_e32 v90, v90
	v_pk_mul_f32 v[74:75], v[76:77], v[74:75]
	v_mul_f32_e32 v76, 0xbfb8aa3b, v89
	v_exp_f32_e32 v76, v76
	v_add_f32_e32 v90, 1.0, v90
	v_rcp_f32_e32 v90, v90
	v_add_f32_e32 v76, 1.0, v76
	v_rcp_f32_e32 v91, v76
	s_nop 0
	v_pk_mul_f32 v[76:77], v[90:91], v[88:89]
	s_nop 0
	v_pk_mul_f32 v[88:89], v[74:75], v[76:77]
	v_cvt_pk_bf16_f32 v74, v78, v79
	v_lshlrev_b64 v[78:79], 12, v[102:103]
	v_lshl_add_u64 v[78:79], s[36:37], 0, v[78:79]
	v_cvt_pk_bf16_f32 v75, v80, v81
	v_cvt_pk_bf16_f32 v76, v86, v87
	v_cvt_pk_bf16_f32 v77, v88, v89
	v_lshl_add_u64 v[90:91], v[78:79], 0, v[150:151]
	global_store_dwordx4 v[90:91], v[74:77], off offset:2048
	global_load_dwordx4 v[74:77], v[148:149], off offset:528
	s_nop 0
	global_load_dwordx4 v[78:81], v[148:149], off offset:512
	global_load_dwordx4 v[86:89], v[84:85], off offset:256
	s_waitcnt vmcnt(0)
	v_add_f32_e32 v66, v66, v74
	global_load_dwordx4 v[82:85], v[82:83], off
	v_add_f32_e32 v70, v70, v78
	v_add_f32_e32 v71, v71, v79
	v_mul_f32_e32 v70, 0xbfb8aa3b, v70
	v_mul_f32_e32 v71, 0xbfb8aa3b, v71
	v_exp_f32_e32 v70, v70
	v_exp_f32_e32 v71, v71
	v_add_f32_e32 v67, v67, v75
	v_mul_f32_e32 v66, 0xbfb8aa3b, v66
	v_mul_f32_e32 v67, 0xbfb8aa3b, v67
	v_exp_f32_e32 v66, v66
	v_exp_f32_e32 v67, v67
	v_add_f32_e32 v70, 1.0, v70
	v_add_f32_e32 v71, 1.0, v71
	v_rcp_f32_e32 v70, v70
	v_rcp_f32_e32 v71, v71
	v_add_f32_e32 v66, 1.0, v66
	v_add_f32_e32 v67, 1.0, v67
	v_rcp_f32_e32 v66, v66
	v_rcp_f32_e32 v67, v67
	v_lshlrev_b32_e32 v78, 16, v86
	v_and_b32_e32 v79, 0xffff0000, v86
	v_pk_mul_f32 v[70:71], v[70:71], v[78:79]
	v_and_b32_e32 v75, 0xffff0000, v88
	v_add_u32_e32 v86, 0x80, v152
	s_waitcnt vmcnt(0)
	v_lshlrev_b32_e32 v92, 16, v82
	v_mul_f32_e32 v74, 0xbfb8aa3b, v92
	v_exp_f32_e32 v74, v74
	v_and_b32_e32 v93, 0xffff0000, v82
	v_add_f32_e32 v74, 1.0, v74
	v_rcp_f32_e32 v94, v74
	v_mul_f32_e32 v74, 0xbfb8aa3b, v93
	v_exp_f32_e32 v74, v74
	s_nop 0
	v_add_f32_e32 v74, 1.0, v74
	v_rcp_f32_e32 v95, v74
	v_lshlrev_b32_e32 v74, 16, v88
	v_pk_mul_f32 v[66:67], v[66:67], v[74:75]
	v_pk_mul_f32 v[78:79], v[94:95], v[92:93]
	s_nop 0
	v_pk_mul_f32 v[70:71], v[70:71], v[78:79]
	v_lshlrev_b32_e32 v78, 16, v84
	v_and_b32_e32 v79, 0xffff0000, v84
	v_mul_f32_e32 v82, 0xbfb8aa3b, v78
	v_mul_f32_e32 v74, 0xbfb8aa3b, v79
	v_exp_f32_e32 v82, v82
	v_exp_f32_e32 v74, v74
	v_add_f32_e32 v82, 1.0, v82
	v_add_f32_e32 v74, 1.0, v74
	v_rcp_f32_e32 v92, v82
	v_rcp_f32_e32 v93, v74
	s_nop 0
	v_pk_mul_f32 v[74:75], v[92:93], v[78:79]
	s_nop 0
	v_pk_mul_f32 v[74:75], v[66:67], v[74:75]
	v_add_f32_e32 v67, v68, v76
	v_mul_f32_e32 v67, 0xbfb8aa3b, v67
	v_exp_f32_e32 v67, v67
	v_add_f32_e32 v66, v72, v80
	v_mul_f32_e32 v66, 0xbfb8aa3b, v66
	v_exp_f32_e32 v66, v66
	v_add_f32_e32 v67, 1.0, v67
	v_rcp_f32_e32 v68, v67
	v_add_f32_e32 v67, v73, v81
	v_mul_f32_e32 v67, 0xbfb8aa3b, v67
	v_exp_f32_e32 v67, v67
	v_add_f32_e32 v66, 1.0, v66
	v_rcp_f32_e32 v66, v66
	v_lshlrev_b32_e32 v72, 16, v87
	v_add_f32_e32 v67, 1.0, v67
	v_rcp_f32_e32 v67, v67
	v_and_b32_e32 v73, 0xffff0000, v87
	v_lshlrev_b32_e32 v78, 16, v83
	v_and_b32_e32 v79, 0xffff0000, v83
	v_mul_f32_e32 v76, 0xbfb8aa3b, v78
	v_pk_mul_f32 v[66:67], v[66:67], v[72:73]
	v_mul_f32_e32 v72, 0xbfb8aa3b, v79
	v_exp_f32_e32 v76, v76
	v_exp_f32_e32 v72, v72
	v_ashrrev_i32_e32 v87, 31, v86
	v_add_f32_e32 v76, 1.0, v76
	v_add_f32_e32 v72, 1.0, v72
	v_rcp_f32_e32 v80, v76
	v_rcp_f32_e32 v81, v72
	v_lshlrev_b32_e32 v76, 16, v85
	v_pk_mul_f32 v[72:73], v[80:81], v[78:79]
	s_nop 0
	v_pk_mul_f32 v[72:73], v[66:67], v[72:73]
	v_add_f32_e32 v66, v69, v77
	v_mul_f32_e32 v66, 0xbfb8aa3b, v66
	v_exp_f32_e32 v66, v66
	v_and_b32_e32 v67, 0xffff0000, v89
	v_and_b32_e32 v77, 0xffff0000, v85
	v_mul_f32_e32 v78, 0xbfb8aa3b, v76
	v_add_f32_e32 v66, 1.0, v66
	v_rcp_f32_e32 v69, v66
	v_lshlrev_b32_e32 v66, 16, v89
	v_exp_f32_e32 v78, v78
	v_pk_mul_f32 v[66:67], v[68:69], v[66:67]
	v_mul_f32_e32 v68, 0xbfb8aa3b, v77
	v_exp_f32_e32 v68, v68
	v_add_f32_e32 v78, 1.0, v78
	v_rcp_f32_e32 v78, v78
	v_add_f32_e32 v68, 1.0, v68
	v_rcp_f32_e32 v79, v68
	s_nop 0
	v_pk_mul_f32 v[68:69], v[78:79], v[76:77]
	s_nop 0
	v_pk_mul_f32 v[76:77], v[66:67], v[68:69]
	v_cvt_pk_bf16_f32 v66, v70, v71
	v_cvt_pk_bf16_f32 v67, v72, v73
	v_cvt_pk_bf16_f32 v68, v74, v75
	v_cvt_pk_bf16_f32 v69, v76, v77
	global_store_dwordx4 v[90:91], v[66:69], off offset:2304
	global_load_dwordx4 v[70:73], v[148:149], off offset:16
	global_load_dwordx4 v[74:77], v[148:149], off
	v_lshlrev_b64 v[66:67], 11, v[86:87]
	v_lshl_add_u64 v[66:67], s[56:57], 0, v[66:67]
	v_lshl_add_u64 v[68:69], v[66:67], 0, v[150:151]
	v_mad_i64_i32 v[66:67], s[24:25], v86, s48, v[154:155]
	v_lshl_add_u64 v[66:67], v[66:67], 0, s[94:95]
	v_lshl_add_u64 v[82:83], v[66:67], 0, v[150:151]
	global_load_dwordx4 v[78:81], v[68:69], off
	v_lshl_add_u64 v[66:67], v[66:67], 0, v[156:157]
	global_load_dwordx4 v[82:85], v[82:83], off
	s_waitcnt vmcnt(0)
	v_add_f32_e32 v58, v58, v70
	v_add_f32_e32 v62, v62, v74
	v_add_f32_e32 v63, v63, v75
	v_mul_f32_e32 v62, 0xbfb8aa3b, v62
	v_mul_f32_e32 v63, 0xbfb8aa3b, v63
	v_exp_f32_e32 v62, v62
	v_exp_f32_e32 v63, v63
	v_add_f32_e32 v59, v59, v71
	v_mul_f32_e32 v58, 0xbfb8aa3b, v58
	v_mul_f32_e32 v59, 0xbfb8aa3b, v59
	v_exp_f32_e32 v58, v58
	v_lshlrev_b32_e32 v88, 16, v82
	v_mul_f32_e32 v70, 0xbfb8aa3b, v88
	v_exp_f32_e32 v70, v70
	v_and_b32_e32 v89, 0xffff0000, v82
	v_exp_f32_e32 v59, v59
	v_add_f32_e32 v62, 1.0, v62
	v_add_f32_e32 v70, 1.0, v70
	v_rcp_f32_e32 v90, v70
	v_mul_f32_e32 v70, 0xbfb8aa3b, v89
	v_exp_f32_e32 v70, v70
	v_add_f32_e32 v63, 1.0, v63
	v_rcp_f32_e32 v62, v62
	v_rcp_f32_e32 v63, v63
	v_add_f32_e32 v70, 1.0, v70
	v_rcp_f32_e32 v91, v70
	v_add_f32_e32 v58, 1.0, v58
	v_add_f32_e32 v59, 1.0, v59
	v_rcp_f32_e32 v58, v58
	v_rcp_f32_e32 v59, v59
	v_lshlrev_b32_e32 v74, 16, v78
	v_and_b32_e32 v75, 0xffff0000, v78
	v_pk_mul_f32 v[62:63], v[62:63], v[74:75]
	v_pk_mul_f32 v[74:75], v[90:91], v[88:89]
	v_lshlrev_b32_e32 v70, 16, v80
	v_pk_mul_f32 v[62:63], v[62:63], v[74:75]
	v_and_b32_e32 v71, 0xffff0000, v80
	v_lshlrev_b32_e32 v74, 16, v84
	v_and_b32_e32 v75, 0xffff0000, v84
	v_mul_f32_e32 v78, 0xbfb8aa3b, v74
	v_pk_mul_f32 v[58:59], v[58:59], v[70:71]
	v_mul_f32_e32 v70, 0xbfb8aa3b, v75
	v_exp_f32_e32 v78, v78
	v_exp_f32_e32 v70, v70
	v_add_f32_e32 v78, 1.0, v78
	v_add_f32_e32 v70, 1.0, v70
	v_rcp_f32_e32 v88, v78
	v_rcp_f32_e32 v89, v70
	s_nop 0
	v_pk_mul_f32 v[70:71], v[88:89], v[74:75]
	s_nop 0
	v_pk_mul_f32 v[70:71], v[58:59], v[70:71]
	v_add_f32_e32 v59, v60, v72
	v_mul_f32_e32 v59, 0xbfb8aa3b, v59
	v_exp_f32_e32 v59, v59
	v_add_f32_e32 v58, v64, v76
	v_mul_f32_e32 v58, 0xbfb8aa3b, v58
	v_exp_f32_e32 v58, v58
	v_add_f32_e32 v59, 1.0, v59
	v_rcp_f32_e32 v60, v59
	v_add_f32_e32 v59, v65, v77
	v_mul_f32_e32 v59, 0xbfb8aa3b, v59
	v_exp_f32_e32 v59, v59
	v_add_f32_e32 v58, 1.0, v58
	v_rcp_f32_e32 v58, v58
	v_lshlrev_b32_e32 v64, 16, v79
	v_add_f32_e32 v59, 1.0, v59
	v_rcp_f32_e32 v59, v59
	v_and_b32_e32 v65, 0xffff0000, v79
	v_lshlrev_b32_e32 v74, 16, v83
	v_and_b32_e32 v75, 0xffff0000, v83
	v_mul_f32_e32 v72, 0xbfb8aa3b, v74
	v_pk_mul_f32 v[58:59], v[58:59], v[64:65]
	v_mul_f32_e32 v64, 0xbfb8aa3b, v75
	v_exp_f32_e32 v72, v72
	v_exp_f32_e32 v64, v64
	v_add_f32_e32 v72, 1.0, v72
	v_add_f32_e32 v64, 1.0, v64
	v_rcp_f32_e32 v76, v72
	v_rcp_f32_e32 v77, v64
	v_lshlrev_b32_e32 v72, 16, v85
	v_pk_mul_f32 v[64:65], v[76:77], v[74:75]
	s_nop 0
	v_pk_mul_f32 v[64:65], v[58:59], v[64:65]
	v_add_f32_e32 v58, v61, v73
	v_mul_f32_e32 v58, 0xbfb8aa3b, v58
	v_exp_f32_e32 v58, v58
	v_and_b32_e32 v59, 0xffff0000, v81
	v_and_b32_e32 v73, 0xffff0000, v85
	v_mul_f32_e32 v74, 0xbfb8aa3b, v72
	v_add_f32_e32 v58, 1.0, v58
	v_rcp_f32_e32 v61, v58
	v_lshlrev_b32_e32 v58, 16, v81
	v_exp_f32_e32 v74, v74
	v_pk_mul_f32 v[58:59], v[60:61], v[58:59]
	v_mul_f32_e32 v60, 0xbfb8aa3b, v73
	v_exp_f32_e32 v60, v60
	v_add_f32_e32 v74, 1.0, v74
	v_rcp_f32_e32 v74, v74
	v_add_f32_e32 v60, 1.0, v60
	v_rcp_f32_e32 v75, v60
	s_nop 0
	v_pk_mul_f32 v[60:61], v[74:75], v[72:73]
	s_nop 0
	v_pk_mul_f32 v[72:73], v[58:59], v[60:61]
	v_cvt_pk_bf16_f32 v58, v62, v63
	v_lshlrev_b64 v[62:63], 12, v[86:87]
	v_lshl_add_u64 v[62:63], s[36:37], 0, v[62:63]
	v_cvt_pk_bf16_f32 v59, v64, v65
	v_cvt_pk_bf16_f32 v60, v70, v71
	v_cvt_pk_bf16_f32 v61, v72, v73
	v_lshl_add_u64 v[74:75], v[62:63], 0, v[150:151]
	global_store_dwordx4 v[74:75], v[58:61], off offset:2048
	global_load_dwordx4 v[58:61], v[148:149], off offset:528
	s_nop 0
	global_load_dwordx4 v[62:65], v[148:149], off offset:512
	global_load_dwordx4 v[70:73], v[68:69], off offset:256
	s_waitcnt vmcnt(0)
	v_add_f32_e32 v50, v50, v58
	global_load_dwordx4 v[66:69], v[66:67], off
	v_add_f32_e32 v54, v54, v62
	v_add_f32_e32 v55, v55, v63
	v_mul_f32_e32 v54, 0xbfb8aa3b, v54
	v_mul_f32_e32 v55, 0xbfb8aa3b, v55
	v_exp_f32_e32 v54, v54
	v_exp_f32_e32 v55, v55
	v_add_f32_e32 v51, v51, v59
	v_mul_f32_e32 v50, 0xbfb8aa3b, v50
	v_mul_f32_e32 v51, 0xbfb8aa3b, v51
	v_exp_f32_e32 v50, v50
	v_exp_f32_e32 v51, v51
	v_add_f32_e32 v54, 1.0, v54
	v_add_f32_e32 v55, 1.0, v55
	v_rcp_f32_e32 v54, v54
	v_rcp_f32_e32 v55, v55
	v_add_f32_e32 v50, 1.0, v50
	v_add_f32_e32 v51, 1.0, v51
	v_rcp_f32_e32 v50, v50
	v_rcp_f32_e32 v51, v51
	v_lshlrev_b32_e32 v62, 16, v70
	v_and_b32_e32 v63, 0xffff0000, v70
	v_pk_mul_f32 v[54:55], v[54:55], v[62:63]
	v_and_b32_e32 v59, 0xffff0000, v72
	v_add_u32_e32 v70, 0x90, v152
	s_waitcnt vmcnt(0)
	v_lshlrev_b32_e32 v76, 16, v66
	v_mul_f32_e32 v58, 0xbfb8aa3b, v76
	v_exp_f32_e32 v58, v58
	v_and_b32_e32 v77, 0xffff0000, v66
	v_add_f32_e32 v58, 1.0, v58
	v_rcp_f32_e32 v78, v58
	v_mul_f32_e32 v58, 0xbfb8aa3b, v77
	v_exp_f32_e32 v58, v58
	s_nop 0
	v_add_f32_e32 v58, 1.0, v58
	v_rcp_f32_e32 v79, v58
	v_lshlrev_b32_e32 v58, 16, v72
	v_pk_mul_f32 v[50:51], v[50:51], v[58:59]
	v_pk_mul_f32 v[62:63], v[78:79], v[76:77]
	s_nop 0
	v_pk_mul_f32 v[54:55], v[54:55], v[62:63]
	v_lshlrev_b32_e32 v62, 16, v68
	v_and_b32_e32 v63, 0xffff0000, v68
	v_mul_f32_e32 v66, 0xbfb8aa3b, v62
	v_mul_f32_e32 v58, 0xbfb8aa3b, v63
	v_exp_f32_e32 v66, v66
	v_exp_f32_e32 v58, v58
	v_add_f32_e32 v66, 1.0, v66
	v_add_f32_e32 v58, 1.0, v58
	v_rcp_f32_e32 v76, v66
	v_rcp_f32_e32 v77, v58
	s_nop 0
	v_pk_mul_f32 v[58:59], v[76:77], v[62:63]
	s_nop 0
	v_pk_mul_f32 v[58:59], v[50:51], v[58:59]
	v_add_f32_e32 v51, v52, v60
	v_mul_f32_e32 v51, 0xbfb8aa3b, v51
	v_exp_f32_e32 v51, v51
	v_add_f32_e32 v50, v56, v64
	v_mul_f32_e32 v50, 0xbfb8aa3b, v50
	v_exp_f32_e32 v50, v50
	v_add_f32_e32 v51, 1.0, v51
	v_rcp_f32_e32 v52, v51
	v_add_f32_e32 v51, v57, v65
	v_mul_f32_e32 v51, 0xbfb8aa3b, v51
	v_exp_f32_e32 v51, v51
	v_add_f32_e32 v50, 1.0, v50
	v_rcp_f32_e32 v50, v50
	v_lshlrev_b32_e32 v56, 16, v71
	v_add_f32_e32 v51, 1.0, v51
	v_rcp_f32_e32 v51, v51
	v_and_b32_e32 v57, 0xffff0000, v71
	v_lshlrev_b32_e32 v62, 16, v67
	v_and_b32_e32 v63, 0xffff0000, v67
	v_mul_f32_e32 v60, 0xbfb8aa3b, v62
	v_pk_mul_f32 v[50:51], v[50:51], v[56:57]
	v_mul_f32_e32 v56, 0xbfb8aa3b, v63
	v_exp_f32_e32 v60, v60
	v_exp_f32_e32 v56, v56
	v_ashrrev_i32_e32 v71, 31, v70
	v_add_f32_e32 v60, 1.0, v60
	v_add_f32_e32 v56, 1.0, v56
	v_rcp_f32_e32 v64, v60
	v_rcp_f32_e32 v65, v56
	v_lshlrev_b32_e32 v60, 16, v69
	v_pk_mul_f32 v[56:57], v[64:65], v[62:63]
	s_nop 0
	v_pk_mul_f32 v[56:57], v[50:51], v[56:57]
	v_add_f32_e32 v50, v53, v61
	v_mul_f32_e32 v50, 0xbfb8aa3b, v50
	v_exp_f32_e32 v50, v50
	v_and_b32_e32 v51, 0xffff0000, v73
	v_and_b32_e32 v61, 0xffff0000, v69
	v_mul_f32_e32 v62, 0xbfb8aa3b, v60
	v_add_f32_e32 v50, 1.0, v50
	v_rcp_f32_e32 v53, v50
	v_lshlrev_b32_e32 v50, 16, v73
	v_exp_f32_e32 v62, v62
	v_pk_mul_f32 v[50:51], v[52:53], v[50:51]
	v_mul_f32_e32 v52, 0xbfb8aa3b, v61
	v_exp_f32_e32 v52, v52
	v_add_f32_e32 v62, 1.0, v62
	v_rcp_f32_e32 v62, v62
	v_add_f32_e32 v52, 1.0, v52
	v_rcp_f32_e32 v63, v52
	s_nop 0
	v_pk_mul_f32 v[52:53], v[62:63], v[60:61]
	s_nop 0
	v_pk_mul_f32 v[60:61], v[50:51], v[52:53]
	v_cvt_pk_bf16_f32 v50, v54, v55
	v_cvt_pk_bf16_f32 v51, v56, v57
	v_cvt_pk_bf16_f32 v52, v58, v59
	v_cvt_pk_bf16_f32 v53, v60, v61
	global_store_dwordx4 v[74:75], v[50:53], off offset:2304
	global_load_dwordx4 v[54:57], v[148:149], off offset:16
	global_load_dwordx4 v[58:61], v[148:149], off
	v_lshlrev_b64 v[50:51], 11, v[70:71]
	v_lshl_add_u64 v[50:51], s[56:57], 0, v[50:51]
	v_lshl_add_u64 v[52:53], v[50:51], 0, v[150:151]
	v_mad_i64_i32 v[50:51], s[24:25], v70, s48, v[154:155]
	v_lshl_add_u64 v[50:51], v[50:51], 0, s[94:95]
	v_lshl_add_u64 v[66:67], v[50:51], 0, v[150:151]
	global_load_dwordx4 v[62:65], v[52:53], off
	v_lshl_add_u64 v[50:51], v[50:51], 0, v[156:157]
	global_load_dwordx4 v[66:69], v[66:67], off
	s_waitcnt vmcnt(0)
	v_add_f32_e32 v42, v42, v54
	v_add_f32_e32 v46, v46, v58
	v_add_f32_e32 v47, v47, v59
	v_mul_f32_e32 v46, 0xbfb8aa3b, v46
	v_mul_f32_e32 v47, 0xbfb8aa3b, v47
	v_exp_f32_e32 v46, v46
	v_exp_f32_e32 v47, v47
	v_add_f32_e32 v43, v43, v55
	v_mul_f32_e32 v42, 0xbfb8aa3b, v42
	v_mul_f32_e32 v43, 0xbfb8aa3b, v43
	v_exp_f32_e32 v42, v42
	v_lshlrev_b32_e32 v72, 16, v66
	v_mul_f32_e32 v54, 0xbfb8aa3b, v72
	v_exp_f32_e32 v54, v54
	v_and_b32_e32 v73, 0xffff0000, v66
	v_exp_f32_e32 v43, v43
	v_add_f32_e32 v46, 1.0, v46
	v_add_f32_e32 v54, 1.0, v54
	v_rcp_f32_e32 v74, v54
	v_mul_f32_e32 v54, 0xbfb8aa3b, v73
	v_exp_f32_e32 v54, v54
	v_add_f32_e32 v47, 1.0, v47
	v_rcp_f32_e32 v46, v46
	v_rcp_f32_e32 v47, v47
	v_add_f32_e32 v54, 1.0, v54
	v_rcp_f32_e32 v75, v54
	v_add_f32_e32 v42, 1.0, v42
	v_add_f32_e32 v43, 1.0, v43
	v_rcp_f32_e32 v42, v42
	v_rcp_f32_e32 v43, v43
	v_lshlrev_b32_e32 v58, 16, v62
	v_and_b32_e32 v59, 0xffff0000, v62
	v_pk_mul_f32 v[46:47], v[46:47], v[58:59]
	v_pk_mul_f32 v[58:59], v[74:75], v[72:73]
	v_lshlrev_b32_e32 v54, 16, v64
	v_pk_mul_f32 v[46:47], v[46:47], v[58:59]
	v_and_b32_e32 v55, 0xffff0000, v64
	v_lshlrev_b32_e32 v58, 16, v68
	v_and_b32_e32 v59, 0xffff0000, v68
	v_mul_f32_e32 v62, 0xbfb8aa3b, v58
	v_pk_mul_f32 v[42:43], v[42:43], v[54:55]
	v_mul_f32_e32 v54, 0xbfb8aa3b, v59
	v_exp_f32_e32 v62, v62
	v_exp_f32_e32 v54, v54
	v_add_f32_e32 v62, 1.0, v62
	v_add_f32_e32 v54, 1.0, v54
	v_rcp_f32_e32 v72, v62
	v_rcp_f32_e32 v73, v54
	s_nop 0
	v_pk_mul_f32 v[54:55], v[72:73], v[58:59]
	s_nop 0
	v_pk_mul_f32 v[54:55], v[42:43], v[54:55]
	v_add_f32_e32 v43, v44, v56
	v_mul_f32_e32 v43, 0xbfb8aa3b, v43
	v_exp_f32_e32 v43, v43
	v_add_f32_e32 v42, v48, v60
	v_mul_f32_e32 v42, 0xbfb8aa3b, v42
	v_exp_f32_e32 v42, v42
	v_add_f32_e32 v43, 1.0, v43
	v_rcp_f32_e32 v44, v43
	v_add_f32_e32 v43, v49, v61
	v_mul_f32_e32 v43, 0xbfb8aa3b, v43
	v_exp_f32_e32 v43, v43
	v_add_f32_e32 v42, 1.0, v42
	v_rcp_f32_e32 v42, v42
	v_lshlrev_b32_e32 v48, 16, v63
	v_add_f32_e32 v43, 1.0, v43
	v_rcp_f32_e32 v43, v43
	v_and_b32_e32 v49, 0xffff0000, v63
	v_lshlrev_b32_e32 v58, 16, v67
	v_and_b32_e32 v59, 0xffff0000, v67
	v_mul_f32_e32 v56, 0xbfb8aa3b, v58
	v_pk_mul_f32 v[42:43], v[42:43], v[48:49]
	v_mul_f32_e32 v48, 0xbfb8aa3b, v59
	v_exp_f32_e32 v56, v56
	v_exp_f32_e32 v48, v48
	v_add_f32_e32 v56, 1.0, v56
	v_add_f32_e32 v48, 1.0, v48
	v_rcp_f32_e32 v60, v56
	v_rcp_f32_e32 v61, v48
	v_lshlrev_b32_e32 v56, 16, v69
	v_pk_mul_f32 v[48:49], v[60:61], v[58:59]
	s_nop 0
	v_pk_mul_f32 v[48:49], v[42:43], v[48:49]
	v_add_f32_e32 v42, v45, v57
	v_mul_f32_e32 v42, 0xbfb8aa3b, v42
	v_exp_f32_e32 v42, v42
	v_and_b32_e32 v43, 0xffff0000, v65
	v_and_b32_e32 v57, 0xffff0000, v69
	v_mul_f32_e32 v58, 0xbfb8aa3b, v56
	v_add_f32_e32 v42, 1.0, v42
	v_rcp_f32_e32 v45, v42
	v_lshlrev_b32_e32 v42, 16, v65
	v_exp_f32_e32 v58, v58
	v_pk_mul_f32 v[42:43], v[44:45], v[42:43]
	v_mul_f32_e32 v44, 0xbfb8aa3b, v57
	v_exp_f32_e32 v44, v44
	v_add_f32_e32 v58, 1.0, v58
	v_rcp_f32_e32 v58, v58
	v_add_f32_e32 v44, 1.0, v44
	v_rcp_f32_e32 v59, v44
	s_nop 0
	v_pk_mul_f32 v[44:45], v[58:59], v[56:57]
	s_nop 0
	v_pk_mul_f32 v[56:57], v[42:43], v[44:45]
	v_cvt_pk_bf16_f32 v42, v46, v47
	v_lshlrev_b64 v[46:47], 12, v[70:71]
	v_lshl_add_u64 v[46:47], s[36:37], 0, v[46:47]
	v_cvt_pk_bf16_f32 v43, v48, v49
	v_cvt_pk_bf16_f32 v44, v54, v55
	v_cvt_pk_bf16_f32 v45, v56, v57
	v_lshl_add_u64 v[58:59], v[46:47], 0, v[150:151]
	global_store_dwordx4 v[58:59], v[42:45], off offset:2048
	global_load_dwordx4 v[42:45], v[148:149], off offset:528
	s_nop 0
	global_load_dwordx4 v[46:49], v[148:149], off offset:512
	global_load_dwordx4 v[54:57], v[52:53], off offset:256
	s_waitcnt vmcnt(0)
	v_add_f32_e32 v34, v34, v42
	global_load_dwordx4 v[50:53], v[50:51], off
	v_add_f32_e32 v38, v38, v46
	v_add_f32_e32 v39, v39, v47
	v_mul_f32_e32 v38, 0xbfb8aa3b, v38
	v_mul_f32_e32 v39, 0xbfb8aa3b, v39
	v_exp_f32_e32 v38, v38
	v_exp_f32_e32 v39, v39
	v_add_f32_e32 v35, v35, v43
	v_mul_f32_e32 v34, 0xbfb8aa3b, v34
	v_mul_f32_e32 v35, 0xbfb8aa3b, v35
	v_exp_f32_e32 v34, v34
	v_exp_f32_e32 v35, v35
	v_add_f32_e32 v38, 1.0, v38
	v_add_f32_e32 v39, 1.0, v39
	v_rcp_f32_e32 v38, v38
	v_rcp_f32_e32 v39, v39
	v_add_f32_e32 v34, 1.0, v34
	v_add_f32_e32 v35, 1.0, v35
	v_rcp_f32_e32 v34, v34
	v_rcp_f32_e32 v35, v35
	v_lshlrev_b32_e32 v46, 16, v54
	v_and_b32_e32 v47, 0xffff0000, v54
	v_pk_mul_f32 v[38:39], v[38:39], v[46:47]
	v_and_b32_e32 v43, 0xffff0000, v56
	v_add_u32_e32 v54, 0xa0, v152
	s_waitcnt vmcnt(0)
	v_lshlrev_b32_e32 v60, 16, v50
	v_mul_f32_e32 v42, 0xbfb8aa3b, v60
	v_exp_f32_e32 v42, v42
	v_and_b32_e32 v61, 0xffff0000, v50
	v_add_f32_e32 v42, 1.0, v42
	v_rcp_f32_e32 v62, v42
	v_mul_f32_e32 v42, 0xbfb8aa3b, v61
	v_exp_f32_e32 v42, v42
	s_nop 0
	v_add_f32_e32 v42, 1.0, v42
	v_rcp_f32_e32 v63, v42
	v_lshlrev_b32_e32 v42, 16, v56
	v_pk_mul_f32 v[34:35], v[34:35], v[42:43]
	v_pk_mul_f32 v[46:47], v[62:63], v[60:61]
	s_nop 0
	v_pk_mul_f32 v[38:39], v[38:39], v[46:47]
	v_lshlrev_b32_e32 v46, 16, v52
	v_and_b32_e32 v47, 0xffff0000, v52
	v_mul_f32_e32 v50, 0xbfb8aa3b, v46
	v_mul_f32_e32 v42, 0xbfb8aa3b, v47
	v_exp_f32_e32 v50, v50
	v_exp_f32_e32 v42, v42
	v_add_f32_e32 v50, 1.0, v50
	v_add_f32_e32 v42, 1.0, v42
	v_rcp_f32_e32 v60, v50
	v_rcp_f32_e32 v61, v42
	s_nop 0
	v_pk_mul_f32 v[42:43], v[60:61], v[46:47]
	s_nop 0
	v_pk_mul_f32 v[42:43], v[34:35], v[42:43]
	v_add_f32_e32 v35, v36, v44
	v_mul_f32_e32 v35, 0xbfb8aa3b, v35
	v_exp_f32_e32 v35, v35
	v_add_f32_e32 v34, v40, v48
	v_mul_f32_e32 v34, 0xbfb8aa3b, v34
	v_exp_f32_e32 v34, v34
	v_add_f32_e32 v35, 1.0, v35
	v_rcp_f32_e32 v36, v35
	v_add_f32_e32 v35, v41, v49
	v_mul_f32_e32 v35, 0xbfb8aa3b, v35
	v_exp_f32_e32 v35, v35
	v_add_f32_e32 v34, 1.0, v34
	v_rcp_f32_e32 v34, v34
	v_lshlrev_b32_e32 v40, 16, v55
	v_add_f32_e32 v35, 1.0, v35
	v_rcp_f32_e32 v35, v35
	v_and_b32_e32 v41, 0xffff0000, v55
	v_lshlrev_b32_e32 v46, 16, v51
	v_and_b32_e32 v47, 0xffff0000, v51
	v_mul_f32_e32 v44, 0xbfb8aa3b, v46
	v_pk_mul_f32 v[34:35], v[34:35], v[40:41]
	v_mul_f32_e32 v40, 0xbfb8aa3b, v47
	v_exp_f32_e32 v44, v44
	v_exp_f32_e32 v40, v40
	v_ashrrev_i32_e32 v55, 31, v54
	v_add_f32_e32 v44, 1.0, v44
	v_add_f32_e32 v40, 1.0, v40
	v_rcp_f32_e32 v48, v44
	v_rcp_f32_e32 v49, v40
	v_lshlrev_b32_e32 v44, 16, v53
	v_pk_mul_f32 v[40:41], v[48:49], v[46:47]
	s_nop 0
	v_pk_mul_f32 v[40:41], v[34:35], v[40:41]
	v_add_f32_e32 v34, v37, v45
	v_mul_f32_e32 v34, 0xbfb8aa3b, v34
	v_exp_f32_e32 v34, v34
	v_and_b32_e32 v35, 0xffff0000, v57
	v_and_b32_e32 v45, 0xffff0000, v53
	v_mul_f32_e32 v46, 0xbfb8aa3b, v44
	v_add_f32_e32 v34, 1.0, v34
	v_rcp_f32_e32 v37, v34
	v_lshlrev_b32_e32 v34, 16, v57
	v_exp_f32_e32 v46, v46
	v_pk_mul_f32 v[34:35], v[36:37], v[34:35]
	v_mul_f32_e32 v36, 0xbfb8aa3b, v45
	v_exp_f32_e32 v36, v36
	v_add_f32_e32 v46, 1.0, v46
	v_rcp_f32_e32 v46, v46
	v_add_f32_e32 v36, 1.0, v36
	v_rcp_f32_e32 v47, v36
	s_nop 0
	v_pk_mul_f32 v[36:37], v[46:47], v[44:45]
	s_nop 0
	v_pk_mul_f32 v[44:45], v[34:35], v[36:37]
	v_cvt_pk_bf16_f32 v34, v38, v39
	v_cvt_pk_bf16_f32 v35, v40, v41
	v_cvt_pk_bf16_f32 v36, v42, v43
	v_cvt_pk_bf16_f32 v37, v44, v45
	global_store_dwordx4 v[58:59], v[34:37], off offset:2304
	global_load_dwordx4 v[38:41], v[148:149], off offset:16
	global_load_dwordx4 v[42:45], v[148:149], off
	v_lshlrev_b64 v[34:35], 11, v[54:55]
	v_lshl_add_u64 v[34:35], s[56:57], 0, v[34:35]
	v_lshl_add_u64 v[36:37], v[34:35], 0, v[150:151]
	v_mad_i64_i32 v[34:35], s[24:25], v54, s48, v[154:155]
	v_lshl_add_u64 v[34:35], v[34:35], 0, s[94:95]
	v_lshl_add_u64 v[50:51], v[34:35], 0, v[150:151]
	global_load_dwordx4 v[46:49], v[36:37], off
	v_lshl_add_u64 v[34:35], v[34:35], 0, v[156:157]
	global_load_dwordx4 v[50:53], v[50:51], off
	s_waitcnt vmcnt(0)
	v_add_f32_e32 v26, v26, v38
	v_add_f32_e32 v30, v30, v42
	v_add_f32_e32 v31, v31, v43
	v_mul_f32_e32 v30, 0xbfb8aa3b, v30
	v_mul_f32_e32 v31, 0xbfb8aa3b, v31
	v_exp_f32_e32 v30, v30
	v_exp_f32_e32 v31, v31
	v_add_f32_e32 v27, v27, v39
	v_mul_f32_e32 v26, 0xbfb8aa3b, v26
	v_mul_f32_e32 v27, 0xbfb8aa3b, v27
	v_exp_f32_e32 v26, v26
	v_lshlrev_b32_e32 v56, 16, v50
	v_mul_f32_e32 v38, 0xbfb8aa3b, v56
	v_exp_f32_e32 v38, v38
	v_and_b32_e32 v57, 0xffff0000, v50
	v_exp_f32_e32 v27, v27
	v_add_f32_e32 v30, 1.0, v30
	v_add_f32_e32 v38, 1.0, v38
	v_rcp_f32_e32 v58, v38
	v_mul_f32_e32 v38, 0xbfb8aa3b, v57
	v_exp_f32_e32 v38, v38
	v_add_f32_e32 v31, 1.0, v31
	v_rcp_f32_e32 v30, v30
	v_rcp_f32_e32 v31, v31
	v_add_f32_e32 v38, 1.0, v38
	v_rcp_f32_e32 v59, v38
	v_add_f32_e32 v26, 1.0, v26
	v_add_f32_e32 v27, 1.0, v27
	v_rcp_f32_e32 v26, v26
	v_rcp_f32_e32 v27, v27
	v_lshlrev_b32_e32 v42, 16, v46
	v_and_b32_e32 v43, 0xffff0000, v46
	v_pk_mul_f32 v[30:31], v[30:31], v[42:43]
	v_pk_mul_f32 v[42:43], v[58:59], v[56:57]
	v_lshlrev_b32_e32 v38, 16, v48
	v_pk_mul_f32 v[30:31], v[30:31], v[42:43]
	v_and_b32_e32 v39, 0xffff0000, v48
	v_lshlrev_b32_e32 v42, 16, v52
	v_and_b32_e32 v43, 0xffff0000, v52
	v_mul_f32_e32 v46, 0xbfb8aa3b, v42
	v_pk_mul_f32 v[26:27], v[26:27], v[38:39]
	v_mul_f32_e32 v38, 0xbfb8aa3b, v43
	v_exp_f32_e32 v46, v46
	v_exp_f32_e32 v38, v38
	v_add_f32_e32 v46, 1.0, v46
	v_add_f32_e32 v38, 1.0, v38
	v_rcp_f32_e32 v56, v46
	v_rcp_f32_e32 v57, v38
	s_nop 0
	v_pk_mul_f32 v[38:39], v[56:57], v[42:43]
	s_nop 0
	v_pk_mul_f32 v[38:39], v[26:27], v[38:39]
	v_add_f32_e32 v27, v28, v40
	v_mul_f32_e32 v27, 0xbfb8aa3b, v27
	v_exp_f32_e32 v27, v27
	v_add_f32_e32 v26, v32, v44
	v_mul_f32_e32 v26, 0xbfb8aa3b, v26
	v_exp_f32_e32 v26, v26
	v_add_f32_e32 v27, 1.0, v27
	v_rcp_f32_e32 v28, v27
	v_add_f32_e32 v27, v33, v45
	v_mul_f32_e32 v27, 0xbfb8aa3b, v27
	v_exp_f32_e32 v27, v27
	v_add_f32_e32 v26, 1.0, v26
	v_rcp_f32_e32 v26, v26
	v_lshlrev_b32_e32 v32, 16, v47
	v_add_f32_e32 v27, 1.0, v27
	v_rcp_f32_e32 v27, v27
	v_and_b32_e32 v33, 0xffff0000, v47
	v_lshlrev_b32_e32 v42, 16, v51
	v_and_b32_e32 v43, 0xffff0000, v51
	v_mul_f32_e32 v40, 0xbfb8aa3b, v42
	v_pk_mul_f32 v[26:27], v[26:27], v[32:33]
	v_mul_f32_e32 v32, 0xbfb8aa3b, v43
	v_exp_f32_e32 v40, v40
	v_exp_f32_e32 v32, v32
	v_add_f32_e32 v40, 1.0, v40
	v_add_f32_e32 v32, 1.0, v32
	v_rcp_f32_e32 v44, v40
	v_rcp_f32_e32 v45, v32
	v_lshlrev_b32_e32 v40, 16, v53
	v_pk_mul_f32 v[32:33], v[44:45], v[42:43]
	s_nop 0
	v_pk_mul_f32 v[32:33], v[26:27], v[32:33]
	v_add_f32_e32 v26, v29, v41
	v_mul_f32_e32 v26, 0xbfb8aa3b, v26
	v_exp_f32_e32 v26, v26
	v_and_b32_e32 v27, 0xffff0000, v49
	v_and_b32_e32 v41, 0xffff0000, v53
	v_mul_f32_e32 v42, 0xbfb8aa3b, v40
	v_add_f32_e32 v26, 1.0, v26
	v_rcp_f32_e32 v29, v26
	v_lshlrev_b32_e32 v26, 16, v49
	v_exp_f32_e32 v42, v42
	v_pk_mul_f32 v[26:27], v[28:29], v[26:27]
	v_mul_f32_e32 v28, 0xbfb8aa3b, v41
	v_exp_f32_e32 v28, v28
	v_add_f32_e32 v42, 1.0, v42
	v_rcp_f32_e32 v42, v42
	v_add_f32_e32 v28, 1.0, v28
	v_rcp_f32_e32 v43, v28
	s_nop 0
	v_pk_mul_f32 v[28:29], v[42:43], v[40:41]
	s_nop 0
	v_pk_mul_f32 v[40:41], v[26:27], v[28:29]
	v_cvt_pk_bf16_f32 v26, v30, v31
	v_lshlrev_b64 v[30:31], 12, v[54:55]
	v_lshl_add_u64 v[30:31], s[36:37], 0, v[30:31]
	v_cvt_pk_bf16_f32 v27, v32, v33
	v_cvt_pk_bf16_f32 v28, v38, v39
	v_cvt_pk_bf16_f32 v29, v40, v41
	v_lshl_add_u64 v[42:43], v[30:31], 0, v[150:151]
	global_store_dwordx4 v[42:43], v[26:29], off offset:2048
	global_load_dwordx4 v[26:29], v[148:149], off offset:528
	s_nop 0
	global_load_dwordx4 v[30:33], v[148:149], off offset:512
	global_load_dwordx4 v[38:41], v[36:37], off offset:256
	s_waitcnt vmcnt(0)
	v_add_f32_e32 v18, v18, v26
	global_load_dwordx4 v[34:37], v[34:35], off
	v_add_f32_e32 v22, v22, v30
	v_add_f32_e32 v23, v23, v31
	v_mul_f32_e32 v22, 0xbfb8aa3b, v22
	v_mul_f32_e32 v23, 0xbfb8aa3b, v23
	v_exp_f32_e32 v22, v22
	v_exp_f32_e32 v23, v23
	v_add_f32_e32 v19, v19, v27
	v_mul_f32_e32 v18, 0xbfb8aa3b, v18
	v_mul_f32_e32 v19, 0xbfb8aa3b, v19
	v_exp_f32_e32 v18, v18
	v_exp_f32_e32 v19, v19
	v_add_f32_e32 v22, 1.0, v22
	v_add_f32_e32 v23, 1.0, v23
	v_rcp_f32_e32 v22, v22
	v_rcp_f32_e32 v23, v23
	v_add_f32_e32 v18, 1.0, v18
	v_add_f32_e32 v19, 1.0, v19
	v_rcp_f32_e32 v18, v18
	v_rcp_f32_e32 v19, v19
	v_lshlrev_b32_e32 v30, 16, v38
	v_and_b32_e32 v31, 0xffff0000, v38
	v_pk_mul_f32 v[22:23], v[22:23], v[30:31]
	v_and_b32_e32 v27, 0xffff0000, v40
	v_add_u32_e32 v38, 0xb0, v152
	s_waitcnt vmcnt(0)
	v_lshlrev_b32_e32 v44, 16, v34
	v_mul_f32_e32 v26, 0xbfb8aa3b, v44
	v_exp_f32_e32 v26, v26
	v_and_b32_e32 v45, 0xffff0000, v34
	v_add_f32_e32 v26, 1.0, v26
	v_rcp_f32_e32 v46, v26
	v_mul_f32_e32 v26, 0xbfb8aa3b, v45
	v_exp_f32_e32 v26, v26
	s_nop 0
	v_add_f32_e32 v26, 1.0, v26
	v_rcp_f32_e32 v47, v26
	v_lshlrev_b32_e32 v26, 16, v40
	v_pk_mul_f32 v[18:19], v[18:19], v[26:27]
	v_pk_mul_f32 v[30:31], v[46:47], v[44:45]
	s_nop 0
	v_pk_mul_f32 v[22:23], v[22:23], v[30:31]
	v_lshlrev_b32_e32 v30, 16, v36
	v_and_b32_e32 v31, 0xffff0000, v36
	v_mul_f32_e32 v34, 0xbfb8aa3b, v30
	v_mul_f32_e32 v26, 0xbfb8aa3b, v31
	v_exp_f32_e32 v34, v34
	v_exp_f32_e32 v26, v26
	v_add_f32_e32 v34, 1.0, v34
	v_add_f32_e32 v26, 1.0, v26
	v_rcp_f32_e32 v44, v34
	v_rcp_f32_e32 v45, v26
	s_nop 0
	v_pk_mul_f32 v[26:27], v[44:45], v[30:31]
	s_nop 0
	v_pk_mul_f32 v[26:27], v[18:19], v[26:27]
	v_add_f32_e32 v19, v20, v28
	v_mul_f32_e32 v19, 0xbfb8aa3b, v19
	v_exp_f32_e32 v19, v19
	v_add_f32_e32 v18, v24, v32
	v_mul_f32_e32 v18, 0xbfb8aa3b, v18
	v_exp_f32_e32 v18, v18
	v_add_f32_e32 v19, 1.0, v19
	v_rcp_f32_e32 v20, v19
	v_add_f32_e32 v19, v25, v33
	v_mul_f32_e32 v19, 0xbfb8aa3b, v19
	v_exp_f32_e32 v19, v19
	v_add_f32_e32 v18, 1.0, v18
	v_rcp_f32_e32 v18, v18
	v_lshlrev_b32_e32 v24, 16, v39
	v_add_f32_e32 v19, 1.0, v19
	v_rcp_f32_e32 v19, v19
	v_and_b32_e32 v25, 0xffff0000, v39
	v_lshlrev_b32_e32 v30, 16, v35
	v_and_b32_e32 v31, 0xffff0000, v35
	v_mul_f32_e32 v28, 0xbfb8aa3b, v30
	v_pk_mul_f32 v[18:19], v[18:19], v[24:25]
	v_mul_f32_e32 v24, 0xbfb8aa3b, v31
	v_exp_f32_e32 v28, v28
	v_exp_f32_e32 v24, v24
	v_ashrrev_i32_e32 v39, 31, v38
	v_add_f32_e32 v28, 1.0, v28
	v_add_f32_e32 v24, 1.0, v24
	v_rcp_f32_e32 v32, v28
	v_rcp_f32_e32 v33, v24
	v_lshlrev_b32_e32 v28, 16, v37
	v_pk_mul_f32 v[24:25], v[32:33], v[30:31]
	s_nop 0
	v_pk_mul_f32 v[24:25], v[18:19], v[24:25]
	v_add_f32_e32 v18, v21, v29
	v_mul_f32_e32 v18, 0xbfb8aa3b, v18
	v_exp_f32_e32 v18, v18
	v_and_b32_e32 v19, 0xffff0000, v41
	v_and_b32_e32 v29, 0xffff0000, v37
	v_mul_f32_e32 v30, 0xbfb8aa3b, v28
	v_add_f32_e32 v18, 1.0, v18
	v_rcp_f32_e32 v21, v18
	v_lshlrev_b32_e32 v18, 16, v41
	v_exp_f32_e32 v30, v30
	v_pk_mul_f32 v[18:19], v[20:21], v[18:19]
	v_mul_f32_e32 v20, 0xbfb8aa3b, v29
	v_exp_f32_e32 v20, v20
	v_add_f32_e32 v30, 1.0, v30
	v_rcp_f32_e32 v30, v30
	v_add_f32_e32 v20, 1.0, v20
	v_rcp_f32_e32 v31, v20
	s_nop 0
	v_pk_mul_f32 v[20:21], v[30:31], v[28:29]
	s_nop 0
	v_pk_mul_f32 v[28:29], v[18:19], v[20:21]
	v_cvt_pk_bf16_f32 v18, v22, v23
	v_cvt_pk_bf16_f32 v19, v24, v25
	v_cvt_pk_bf16_f32 v20, v26, v27
	v_cvt_pk_bf16_f32 v21, v28, v29
	global_store_dwordx4 v[42:43], v[18:21], off offset:2304
	global_load_dwordx4 v[22:25], v[148:149], off offset:16
	global_load_dwordx4 v[26:29], v[148:149], off
	v_lshlrev_b64 v[18:19], 11, v[38:39]
	v_lshl_add_u64 v[18:19], s[56:57], 0, v[18:19]
	v_lshl_add_u64 v[20:21], v[18:19], 0, v[150:151]
	v_mad_i64_i32 v[18:19], s[24:25], v38, s48, v[154:155]
	v_lshl_add_u64 v[18:19], v[18:19], 0, s[94:95]
	v_lshl_add_u64 v[34:35], v[18:19], 0, v[150:151]
	global_load_dwordx4 v[30:33], v[20:21], off
	v_lshl_add_u64 v[18:19], v[18:19], 0, v[156:157]
	global_load_dwordx4 v[34:37], v[34:35], off
	s_waitcnt vmcnt(0)
	v_add_f32_e32 v10, v10, v22
	v_add_f32_e32 v14, v14, v26
	v_add_f32_e32 v15, v15, v27
	v_mul_f32_e32 v14, 0xbfb8aa3b, v14
	v_mul_f32_e32 v15, 0xbfb8aa3b, v15
	v_exp_f32_e32 v14, v14
	v_exp_f32_e32 v15, v15
	v_add_f32_e32 v11, v11, v23
	v_mul_f32_e32 v10, 0xbfb8aa3b, v10
	v_mul_f32_e32 v11, 0xbfb8aa3b, v11
	v_exp_f32_e32 v10, v10
	v_lshlrev_b32_e32 v40, 16, v34
	v_mul_f32_e32 v22, 0xbfb8aa3b, v40
	v_exp_f32_e32 v22, v22
	v_and_b32_e32 v41, 0xffff0000, v34
	v_exp_f32_e32 v11, v11
	v_add_f32_e32 v14, 1.0, v14
	v_add_f32_e32 v22, 1.0, v22
	v_rcp_f32_e32 v42, v22
	v_mul_f32_e32 v22, 0xbfb8aa3b, v41
	v_exp_f32_e32 v22, v22
	v_add_f32_e32 v15, 1.0, v15
	v_rcp_f32_e32 v14, v14
	v_rcp_f32_e32 v15, v15
	v_add_f32_e32 v22, 1.0, v22
	v_rcp_f32_e32 v43, v22
	v_add_f32_e32 v10, 1.0, v10
	v_add_f32_e32 v11, 1.0, v11
	v_rcp_f32_e32 v10, v10
	v_rcp_f32_e32 v11, v11
	v_lshlrev_b32_e32 v26, 16, v30
	v_and_b32_e32 v27, 0xffff0000, v30
	v_pk_mul_f32 v[14:15], v[14:15], v[26:27]
	v_pk_mul_f32 v[26:27], v[42:43], v[40:41]
	v_lshlrev_b32_e32 v22, 16, v32
	v_pk_mul_f32 v[14:15], v[14:15], v[26:27]
	v_and_b32_e32 v23, 0xffff0000, v32
	v_lshlrev_b32_e32 v26, 16, v36
	v_and_b32_e32 v27, 0xffff0000, v36
	v_mul_f32_e32 v30, 0xbfb8aa3b, v26
	v_pk_mul_f32 v[10:11], v[10:11], v[22:23]
	v_mul_f32_e32 v22, 0xbfb8aa3b, v27
	v_exp_f32_e32 v30, v30
	v_exp_f32_e32 v22, v22
	v_add_f32_e32 v30, 1.0, v30
	v_add_f32_e32 v22, 1.0, v22
	v_rcp_f32_e32 v40, v30
	v_rcp_f32_e32 v41, v22
	s_nop 0
	v_pk_mul_f32 v[22:23], v[40:41], v[26:27]
	s_nop 0
	v_pk_mul_f32 v[22:23], v[10:11], v[22:23]
	v_add_f32_e32 v11, v12, v24
	v_mul_f32_e32 v11, 0xbfb8aa3b, v11
	v_exp_f32_e32 v11, v11
	v_add_f32_e32 v10, v16, v28
	v_mul_f32_e32 v10, 0xbfb8aa3b, v10
	v_exp_f32_e32 v10, v10
	v_add_f32_e32 v11, 1.0, v11
	v_rcp_f32_e32 v12, v11
	v_add_f32_e32 v11, v17, v29
	v_mul_f32_e32 v11, 0xbfb8aa3b, v11
	v_exp_f32_e32 v11, v11
	v_add_f32_e32 v10, 1.0, v10
	v_rcp_f32_e32 v10, v10
	v_lshlrev_b32_e32 v16, 16, v31
	v_add_f32_e32 v11, 1.0, v11
	v_rcp_f32_e32 v11, v11
	v_and_b32_e32 v17, 0xffff0000, v31
	v_lshlrev_b32_e32 v26, 16, v35
	v_and_b32_e32 v27, 0xffff0000, v35
	v_mul_f32_e32 v24, 0xbfb8aa3b, v26
	v_pk_mul_f32 v[10:11], v[10:11], v[16:17]
	v_mul_f32_e32 v16, 0xbfb8aa3b, v27
	v_exp_f32_e32 v24, v24
	v_exp_f32_e32 v16, v16
	v_add_f32_e32 v24, 1.0, v24
	v_add_f32_e32 v16, 1.0, v16
	v_rcp_f32_e32 v28, v24
	v_rcp_f32_e32 v29, v16
	v_lshlrev_b32_e32 v24, 16, v37
	v_pk_mul_f32 v[16:17], v[28:29], v[26:27]
	s_nop 0
	v_pk_mul_f32 v[16:17], v[10:11], v[16:17]
	v_add_f32_e32 v10, v13, v25
	v_mul_f32_e32 v10, 0xbfb8aa3b, v10
	v_exp_f32_e32 v10, v10
	v_and_b32_e32 v11, 0xffff0000, v33
	v_and_b32_e32 v25, 0xffff0000, v37
	v_mul_f32_e32 v26, 0xbfb8aa3b, v24
	v_add_f32_e32 v10, 1.0, v10
	v_rcp_f32_e32 v13, v10
	v_lshlrev_b32_e32 v10, 16, v33
	v_exp_f32_e32 v26, v26
	v_pk_mul_f32 v[10:11], v[12:13], v[10:11]
	v_mul_f32_e32 v12, 0xbfb8aa3b, v25
	v_exp_f32_e32 v12, v12
	v_add_f32_e32 v26, 1.0, v26
	v_rcp_f32_e32 v26, v26
	v_add_f32_e32 v12, 1.0, v12
	v_rcp_f32_e32 v27, v12
	s_nop 0
	v_pk_mul_f32 v[12:13], v[26:27], v[24:25]
	s_nop 0
	v_pk_mul_f32 v[24:25], v[10:11], v[12:13]
	v_cvt_pk_bf16_f32 v10, v14, v15
	v_lshlrev_b64 v[14:15], 12, v[38:39]
	v_lshl_add_u64 v[14:15], s[36:37], 0, v[14:15]
	v_cvt_pk_bf16_f32 v11, v16, v17
	v_cvt_pk_bf16_f32 v12, v22, v23
	v_cvt_pk_bf16_f32 v13, v24, v25
	v_lshl_add_u64 v[26:27], v[14:15], 0, v[150:151]
	global_store_dwordx4 v[26:27], v[10:13], off offset:2048
	global_load_dwordx4 v[10:13], v[148:149], off offset:528
	s_nop 0
	global_load_dwordx4 v[14:17], v[148:149], off offset:512
	global_load_dwordx4 v[22:25], v[20:21], off offset:256
	s_waitcnt vmcnt(0)
	v_add_f32_e32 v2, v2, v10
	global_load_dwordx4 v[18:21], v[18:19], off
	v_add_f32_e32 v6, v6, v14
	v_add_f32_e32 v7, v7, v15
	v_mul_f32_e32 v6, 0xbfb8aa3b, v6
	v_mul_f32_e32 v7, 0xbfb8aa3b, v7
	v_exp_f32_e32 v6, v6
	v_exp_f32_e32 v7, v7
	v_add_f32_e32 v3, v3, v11
	v_mul_f32_e32 v2, 0xbfb8aa3b, v2
	v_mul_f32_e32 v3, 0xbfb8aa3b, v3
	v_exp_f32_e32 v2, v2
	v_exp_f32_e32 v3, v3
	v_add_f32_e32 v6, 1.0, v6
	v_add_f32_e32 v7, 1.0, v7
	v_rcp_f32_e32 v6, v6
	v_rcp_f32_e32 v7, v7
	v_add_f32_e32 v2, 1.0, v2
	v_add_f32_e32 v3, 1.0, v3
	v_rcp_f32_e32 v2, v2
	v_rcp_f32_e32 v3, v3
	v_lshlrev_b32_e32 v14, 16, v22
	v_and_b32_e32 v15, 0xffff0000, v22
	v_pk_mul_f32 v[6:7], v[6:7], v[14:15]
	v_and_b32_e32 v11, 0xffff0000, v24
	s_waitcnt vmcnt(0)
	v_lshlrev_b32_e32 v28, 16, v18
	v_mul_f32_e32 v10, 0xbfb8aa3b, v28
	v_exp_f32_e32 v10, v10
	v_and_b32_e32 v29, 0xffff0000, v18
	v_add_f32_e32 v10, 1.0, v10
	v_rcp_f32_e32 v30, v10
	v_mul_f32_e32 v10, 0xbfb8aa3b, v29
	v_exp_f32_e32 v10, v10
	s_nop 0
	v_add_f32_e32 v10, 1.0, v10
	v_rcp_f32_e32 v31, v10
	v_lshlrev_b32_e32 v10, 16, v24
	v_pk_mul_f32 v[2:3], v[2:3], v[10:11]
	v_pk_mul_f32 v[14:15], v[30:31], v[28:29]
	s_nop 0
	v_pk_mul_f32 v[6:7], v[6:7], v[14:15]
	v_lshlrev_b32_e32 v14, 16, v20
	v_and_b32_e32 v15, 0xffff0000, v20
	v_mul_f32_e32 v18, 0xbfb8aa3b, v14
	v_mul_f32_e32 v10, 0xbfb8aa3b, v15
	v_exp_f32_e32 v18, v18
	v_exp_f32_e32 v10, v10
	v_add_f32_e32 v18, 1.0, v18
	v_add_f32_e32 v10, 1.0, v10
	v_rcp_f32_e32 v28, v18
	v_rcp_f32_e32 v29, v10
	s_nop 0
	v_pk_mul_f32 v[10:11], v[28:29], v[14:15]
	s_nop 0
	v_pk_mul_f32 v[10:11], v[2:3], v[10:11]
	v_add_f32_e32 v3, v4, v12
	v_mul_f32_e32 v3, 0xbfb8aa3b, v3
	v_exp_f32_e32 v3, v3
	v_add_f32_e32 v2, v8, v16
	v_mul_f32_e32 v2, 0xbfb8aa3b, v2
	v_exp_f32_e32 v2, v2
	v_add_f32_e32 v3, 1.0, v3
	v_rcp_f32_e32 v4, v3
	v_add_f32_e32 v3, v9, v17
	v_mul_f32_e32 v3, 0xbfb8aa3b, v3
	v_exp_f32_e32 v3, v3
	v_add_f32_e32 v2, 1.0, v2
	v_rcp_f32_e32 v2, v2
	v_lshlrev_b32_e32 v8, 16, v23
	v_add_f32_e32 v3, 1.0, v3
	v_rcp_f32_e32 v3, v3
	v_and_b32_e32 v9, 0xffff0000, v23
	v_lshlrev_b32_e32 v14, 16, v19
	v_and_b32_e32 v15, 0xffff0000, v19
	v_mul_f32_e32 v12, 0xbfb8aa3b, v14
	v_pk_mul_f32 v[2:3], v[2:3], v[8:9]
	v_mul_f32_e32 v8, 0xbfb8aa3b, v15
	v_exp_f32_e32 v12, v12
	v_exp_f32_e32 v8, v8
	v_add_f32_e32 v12, 1.0, v12
	v_add_f32_e32 v8, 1.0, v8
	v_rcp_f32_e32 v16, v12
	v_rcp_f32_e32 v17, v8
	v_lshlrev_b32_e32 v12, 16, v21
	v_pk_mul_f32 v[8:9], v[16:17], v[14:15]
	s_nop 0
	v_pk_mul_f32 v[8:9], v[2:3], v[8:9]
	v_add_f32_e32 v2, v5, v13
	v_mul_f32_e32 v2, 0xbfb8aa3b, v2
	v_exp_f32_e32 v2, v2
	v_and_b32_e32 v3, 0xffff0000, v25
	v_and_b32_e32 v13, 0xffff0000, v21
	v_mul_f32_e32 v14, 0xbfb8aa3b, v12
	v_add_f32_e32 v2, 1.0, v2
	v_rcp_f32_e32 v5, v2
	v_lshlrev_b32_e32 v2, 16, v25
	v_exp_f32_e32 v14, v14
	v_pk_mul_f32 v[2:3], v[4:5], v[2:3]
	v_mul_f32_e32 v4, 0xbfb8aa3b, v13
	v_exp_f32_e32 v4, v4
	v_add_f32_e32 v14, 1.0, v14
	v_rcp_f32_e32 v14, v14
	v_add_f32_e32 v4, 1.0, v4
	v_rcp_f32_e32 v15, v4
	s_nop 0
	v_pk_mul_f32 v[4:5], v[14:15], v[12:13]
	s_nop 0
	v_pk_mul_f32 v[12:13], v[2:3], v[4:5]
	v_cvt_pk_bf16_f32 v2, v6, v7
	v_cvt_pk_bf16_f32 v3, v8, v9
	v_cvt_pk_bf16_f32 v4, v10, v11
	v_cvt_pk_bf16_f32 v5, v12, v13
	global_store_dwordx4 v[26:27], v[2:5], off offset:2304
	s_cbranch_vccz .LBB0_970
	v_readlane_b32 s4, v254, 12
	s_waitcnt vmcnt(0)
	v_readlane_b32 s5, v254, 13
	s_andn2_b64 vcc, exec, s[4:5]
	s_cbranch_vccnz .LBB0_981
	s_barrier

.LBB0_1044:
	s_add_u32 s2, s68, 0xfff80080
	s_addc_u32 s17, s69, -1
	s_add_i32 s26, 0, 0x10000
	v_add_u32_e32 v156, s26, v141
	ds_read_b128 v[144:147], v156
	ds_read_b128 v[148:151], v156 offset:1024
	ds_read_b128 v[152:155], v156 offset:2048
	ds_read_b128 v[156:159], v156 offset:3072
	s_cmp_eq_u32 s44, 28
	s_cselect_b32 s73, s55, s17
	s_cselect_b32 s72, s24, s2
	s_cselect_b32 s71, s25, s92
	s_cselect_b32 s70, s43, s83
	v_lshl_add_u64 v[164:165], s[68:69], 0, v[136:137]
	s_add_i32 m0, s58, 0xc000
	ds_read_b128 v[160:163], v143
	ds_read_b128 v[188:191], v143 offset:1024
	ds_read_b128 v[192:195], v143 offset:2048
	ds_read_b128 v[196:199], v143 offset:3072
	ds_read_b128 v[200:203], v143 offset:4096
	ds_read_b128 v[216:219], v143 offset:5120
	ds_read_b128 v[220:223], v143 offset:6144
	ds_read_b128 v[224:227], v143 offset:7168
	global_load_lds_dwordx4 v[164:165], off
	v_lshl_add_u64 v[164:165], s[68:69], 0, v[138:139]
	s_add_i32 m0, s58, 0xe000
	s_nop 0
	global_load_lds_dwordx4 v[164:165], off
	s_waitcnt lgkmcnt(8)
	s_barrier
	s_waitcnt lgkmcnt(0)
	s_waitcnt lgkmcnt(0)
	v_mfma_f32_16x16x32_bf16 v[126:129], v[144:147], v[160:163], v[126:129]
	v_mfma_f32_16x16x32_bf16 v[122:125], v[152:155], v[160:163], v[122:125]
	v_mfma_f32_16x16x32_bf16 v[118:121], v[144:147], v[192:195], v[118:121]
	v_mfma_f32_16x16x32_bf16 v[114:117], v[152:155], v[192:195], v[114:117]
	v_mfma_f32_16x16x32_bf16 v[102:105], v[144:147], v[200:203], v[102:105]
	v_mfma_f32_16x16x32_bf16 v[98:101], v[152:155], v[200:203], v[98:101]
	v_mfma_f32_16x16x32_bf16 v[86:89], v[144:147], v[220:223], v[86:89]
	v_mfma_f32_16x16x32_bf16 v[82:85], v[152:155], v[220:223], v[82:85]
	v_mfma_f32_16x16x32_bf16 v[126:129], v[148:151], v[188:191], v[126:129]
	v_mfma_f32_16x16x32_bf16 v[122:125], v[156:159], v[188:191], v[122:125]
	v_mfma_f32_16x16x32_bf16 v[118:121], v[148:151], v[196:199], v[118:121]
	v_mfma_f32_16x16x32_bf16 v[114:117], v[156:159], v[196:199], v[114:117]
	v_mfma_f32_16x16x32_bf16 v[102:105], v[148:151], v[216:219], v[102:105]
	v_mfma_f32_16x16x32_bf16 v[98:101], v[156:159], v[216:219], v[98:101]
	v_mfma_f32_16x16x32_bf16 v[86:89], v[148:151], v[224:227], v[86:89]
	v_mfma_f32_16x16x32_bf16 v[82:85], v[156:159], v[224:227], v[82:85]
	s_barrier
	s_add_i32 s2, 0, 0x14000
	v_add_u32_e32 v164, s2, v141
	s_add_i32 s17, s26, s3
	ds_read_b128 v[228:231], v164
	ds_read_b128 v[232:235], v164 offset:1024
	ds_read_b128 v[236:239], v164 offset:2048
	ds_read_b128 v[240:243], v164 offset:3072
	v_lshl_add_u64 v[164:165], s[70:71], 0, v[0:1]
	s_mov_b32 m0, s17
	v_lshl_add_u64 v[204:205], s[70:71], 0, v[130:131]
	global_load_lds_dwordx4 v[164:165], off
	s_add_i32 m0, s17, 0x2000
	s_nop 0
	global_load_lds_dwordx4 v[204:205], off
	s_barrier
	s_waitcnt lgkmcnt(0)
	s_waitcnt lgkmcnt(0)
	v_mfma_f32_16x16x32_bf16 v[110:113], v[228:231], v[160:163], v[110:113]
	v_mfma_f32_16x16x32_bf16 v[106:109], v[236:239], v[160:163], v[106:109]
	v_mfma_f32_16x16x32_bf16 v[94:97], v[228:231], v[192:195], v[94:97]
	v_mfma_f32_16x16x32_bf16 v[90:93], v[236:239], v[192:195], v[90:93]
	v_mfma_f32_16x16x32_bf16 v[78:81], v[228:231], v[200:203], v[78:81]
	v_mfma_f32_16x16x32_bf16 v[74:77], v[236:239], v[200:203], v[74:77]
	v_mfma_f32_16x16x32_bf16 v[70:73], v[228:231], v[220:223], v[70:73]
	v_mfma_f32_16x16x32_bf16 v[66:69], v[236:239], v[220:223], v[66:69]
	v_mfma_f32_16x16x32_bf16 v[110:113], v[232:235], v[188:191], v[110:113]
	v_mfma_f32_16x16x32_bf16 v[106:109], v[240:243], v[188:191], v[106:109]
	v_mfma_f32_16x16x32_bf16 v[94:97], v[232:235], v[196:199], v[94:97]
	v_mfma_f32_16x16x32_bf16 v[90:93], v[240:243], v[196:199], v[90:93]
	v_mfma_f32_16x16x32_bf16 v[78:81], v[232:235], v[216:219], v[78:81]
	v_mfma_f32_16x16x32_bf16 v[74:77], v[240:243], v[216:219], v[74:77]
	v_mfma_f32_16x16x32_bf16 v[70:73], v[232:235], v[224:227], v[70:73]
	v_mfma_f32_16x16x32_bf16 v[66:69], v[240:243], v[224:227], v[66:69]
	s_mov_b32 m0, s58
	v_lshl_add_u64 v[244:245], s[72:73], 0, v[134:135]
	s_barrier
	ds_read_b128 v[160:163], v143 offset:16384
	ds_read_b128 v[188:191], v143 offset:17408
	ds_read_b128 v[192:195], v143 offset:18432
	ds_read_b128 v[196:199], v143 offset:19456
	ds_read_b128 v[200:203], v143 offset:20480
	ds_read_b128 v[216:219], v143 offset:21504
	ds_read_b128 v[220:223], v143 offset:22528
	ds_read_b128 v[224:227], v143 offset:23552
	global_load_lds_dwordx4 v[244:245], off
	v_lshl_add_u64 v[246:247], s[72:73], 0, v[132:133]
	s_mov_b32 m0, s74
	s_nop 0
	global_load_lds_dwordx4 v[246:247], off
	s_barrier
	s_waitcnt lgkmcnt(0)
	s_waitcnt lgkmcnt(0)
	v_mfma_f32_16x16x32_bf16 v[62:65], v[144:147], v[160:163], v[62:65]
	v_mfma_f32_16x16x32_bf16 v[58:61], v[152:155], v[160:163], v[58:61]
	v_mfma_f32_16x16x32_bf16 v[54:57], v[144:147], v[192:195], v[54:57]
	v_mfma_f32_16x16x32_bf16 v[50:53], v[152:155], v[192:195], v[50:53]
	v_mfma_f32_16x16x32_bf16 v[38:41], v[144:147], v[200:203], v[38:41]
	v_mfma_f32_16x16x32_bf16 v[34:37], v[152:155], v[200:203], v[34:37]
	v_mfma_f32_16x16x32_bf16 v[22:25], v[144:147], v[220:223], v[22:25]
	v_mfma_f32_16x16x32_bf16 v[18:21], v[152:155], v[220:223], v[18:21]
	v_mfma_f32_16x16x32_bf16 v[62:65], v[148:151], v[188:191], v[62:65]
	v_mfma_f32_16x16x32_bf16 v[58:61], v[156:159], v[188:191], v[58:61]
	v_mfma_f32_16x16x32_bf16 v[54:57], v[148:151], v[196:199], v[54:57]
	v_mfma_f32_16x16x32_bf16 v[50:53], v[156:159], v[196:199], v[50:53]
	v_mfma_f32_16x16x32_bf16 v[38:41], v[148:151], v[216:219], v[38:41]
	v_mfma_f32_16x16x32_bf16 v[34:37], v[156:159], v[216:219], v[34:37]
	v_mfma_f32_16x16x32_bf16 v[22:25], v[148:151], v[224:227], v[22:25]
	v_mfma_f32_16x16x32_bf16 v[18:21], v[156:159], v[224:227], v[18:21]
	s_barrier
	s_add_u32 s26, s70, 0x80000
	s_addc_u32 s27, s71, 0
	s_add_i32 s2, s2, s3
	v_lshl_add_u64 v[144:145], s[26:27], 0, v[0:1]
	s_mov_b32 m0, s2
	s_nop 0
	global_load_lds_dwordx4 v[144:145], off
	v_lshl_add_u64 v[144:145], s[26:27], 0, v[130:131]
	s_add_i32 m0, s2, 0x2000
	s_nop 0
	global_load_lds_dwordx4 v[144:145], off
	s_waitcnt vmcnt(6)
	s_barrier
	v_mfma_f32_16x16x32_bf16 v[46:49], v[228:231], v[160:163], v[46:49]
	v_mfma_f32_16x16x32_bf16 v[42:45], v[236:239], v[160:163], v[42:45]
	v_mfma_f32_16x16x32_bf16 v[30:33], v[228:231], v[192:195], v[30:33]
	v_mfma_f32_16x16x32_bf16 v[26:29], v[236:239], v[192:195], v[26:29]
	v_mfma_f32_16x16x32_bf16 v[14:17], v[228:231], v[200:203], v[14:17]
	v_mfma_f32_16x16x32_bf16 v[10:13], v[236:239], v[200:203], v[10:13]
	v_mfma_f32_16x16x32_bf16 v[6:9], v[228:231], v[220:223], v[6:9]
	v_mfma_f32_16x16x32_bf16 v[2:5], v[236:239], v[220:223], v[2:5]
	v_mfma_f32_16x16x32_bf16 v[46:49], v[232:235], v[188:191], v[46:49]
	v_mfma_f32_16x16x32_bf16 v[42:45], v[240:243], v[188:191], v[42:45]
	v_mfma_f32_16x16x32_bf16 v[30:33], v[232:235], v[196:199], v[30:33]
	v_mfma_f32_16x16x32_bf16 v[26:29], v[240:243], v[196:199], v[26:29]
	v_mfma_f32_16x16x32_bf16 v[14:17], v[232:235], v[216:219], v[14:17]
	v_mfma_f32_16x16x32_bf16 v[10:13], v[240:243], v[216:219], v[10:13]
	v_mfma_f32_16x16x32_bf16 v[6:9], v[232:235], v[224:227], v[6:9]
	v_mfma_f32_16x16x32_bf16 v[2:5], v[240:243], v[224:227], v[2:5]
	s_add_i32 s2, 0, 0x18000
	v_add_u32_e32 v156, s2, v141
	s_barrier
	ds_read_b128 v[144:147], v156
	ds_read_b128 v[148:151], v156 offset:1024
	ds_read_b128 v[152:155], v156 offset:2048
	ds_read_b128 v[156:159], v156 offset:3072
	s_add_u32 s26, s72, 0x80000
	s_addc_u32 s27, s73, 0
	s_mov_b32 m0, s75
	v_lshl_add_u64 v[228:229], s[26:27], 0, v[134:135]
	ds_read_b128 v[160:163], v143 offset:32768
	ds_read_b128 v[188:191], v143 offset:33792
	ds_read_b128 v[192:195], v143 offset:34816
	ds_read_b128 v[196:199], v143 offset:35840
	ds_read_b128 v[200:203], v143 offset:36864
	ds_read_b128 v[216:219], v143 offset:37888
	ds_read_b128 v[220:223], v143 offset:38912
	ds_read_b128 v[224:227], v143 offset:39936
	global_load_lds_dwordx4 v[228:229], off
	v_lshl_add_u64 v[228:229], s[26:27], 0, v[132:133]
	s_mov_b32 m0, s79
	s_nop 0
	global_load_lds_dwordx4 v[228:229], off
	s_waitcnt lgkmcnt(8)
	s_barrier
	s_waitcnt lgkmcnt(0)
	s_waitcnt lgkmcnt(0)
	v_mfma_f32_16x16x32_bf16 v[126:129], v[144:147], v[160:163], v[126:129]
	v_mfma_f32_16x16x32_bf16 v[122:125], v[152:155], v[160:163], v[122:125]
	v_mfma_f32_16x16x32_bf16 v[118:121], v[144:147], v[192:195], v[118:121]
	v_mfma_f32_16x16x32_bf16 v[114:117], v[152:155], v[192:195], v[114:117]
	v_mfma_f32_16x16x32_bf16 v[102:105], v[144:147], v[200:203], v[102:105]
	v_mfma_f32_16x16x32_bf16 v[98:101], v[152:155], v[200:203], v[98:101]
	v_mfma_f32_16x16x32_bf16 v[86:89], v[144:147], v[220:223], v[86:89]
	v_mfma_f32_16x16x32_bf16 v[82:85], v[152:155], v[220:223], v[82:85]
	v_mfma_f32_16x16x32_bf16 v[126:129], v[148:151], v[188:191], v[126:129]
	v_mfma_f32_16x16x32_bf16 v[122:125], v[156:159], v[188:191], v[122:125]
	v_mfma_f32_16x16x32_bf16 v[118:121], v[148:151], v[196:199], v[118:121]
	v_mfma_f32_16x16x32_bf16 v[114:117], v[156:159], v[196:199], v[114:117]
	v_mfma_f32_16x16x32_bf16 v[102:105], v[148:151], v[216:219], v[102:105]
	v_mfma_f32_16x16x32_bf16 v[98:101], v[156:159], v[216:219], v[98:101]
	v_mfma_f32_16x16x32_bf16 v[86:89], v[148:151], v[224:227], v[86:89]
	v_mfma_f32_16x16x32_bf16 v[82:85], v[156:159], v[224:227], v[82:85]
	s_barrier
	s_add_i32 s17, 0, 0x1c000
	s_add_i32 s2, s2, s3
	v_add_u32_e32 v206, s17, v141
	v_lshl_add_u64 v[164:165], v[164:165], 0, s[28:29]
	s_mov_b32 m0, s2
	ds_read_b128 v[228:231], v206
	ds_read_b128 v[232:235], v206 offset:1024
	ds_read_b128 v[236:239], v206 offset:2048
	ds_read_b128 v[240:243], v206 offset:3072
	global_load_lds_dwordx4 v[164:165], off
	v_lshl_add_u64 v[164:165], v[204:205], 0, s[28:29]
	s_add_i32 m0, s2, 0x2000
	s_nop 0
	global_load_lds_dwordx4 v[164:165], off
	s_barrier
	s_waitcnt lgkmcnt(0)
	s_waitcnt lgkmcnt(0)
	v_mfma_f32_16x16x32_bf16 v[110:113], v[228:231], v[160:163], v[110:113]
	v_mfma_f32_16x16x32_bf16 v[106:109], v[236:239], v[160:163], v[106:109]
	v_mfma_f32_16x16x32_bf16 v[94:97], v[228:231], v[192:195], v[94:97]
	v_mfma_f32_16x16x32_bf16 v[90:93], v[236:239], v[192:195], v[90:93]
	v_mfma_f32_16x16x32_bf16 v[78:81], v[228:231], v[200:203], v[78:81]
	v_mfma_f32_16x16x32_bf16 v[74:77], v[236:239], v[200:203], v[74:77]
	v_mfma_f32_16x16x32_bf16 v[70:73], v[228:231], v[220:223], v[70:73]
	v_mfma_f32_16x16x32_bf16 v[66:69], v[236:239], v[220:223], v[66:69]
	v_mfma_f32_16x16x32_bf16 v[110:113], v[232:235], v[188:191], v[110:113]
	v_mfma_f32_16x16x32_bf16 v[106:109], v[240:243], v[188:191], v[106:109]
	v_mfma_f32_16x16x32_bf16 v[94:97], v[232:235], v[196:199], v[94:97]
	v_mfma_f32_16x16x32_bf16 v[90:93], v[240:243], v[196:199], v[90:93]
	v_mfma_f32_16x16x32_bf16 v[78:81], v[232:235], v[216:219], v[78:81]
	v_mfma_f32_16x16x32_bf16 v[74:77], v[240:243], v[216:219], v[74:77]
	v_mfma_f32_16x16x32_bf16 v[70:73], v[232:235], v[224:227], v[70:73]
	v_mfma_f32_16x16x32_bf16 v[66:69], v[240:243], v[224:227], v[66:69]
	s_mov_b32 m0, s80
	v_lshl_add_u64 v[164:165], v[244:245], 0, s[28:29]
	s_barrier
	ds_read_b128 v[160:163], v143 offset:49152
	ds_read_b128 v[188:191], v143 offset:50176
	ds_read_b128 v[192:195], v143 offset:51200
	ds_read_b128 v[196:199], v143 offset:52224
	ds_read_b128 v[200:203], v143 offset:53248
	ds_read_b128 v[216:219], v143 offset:54272
	ds_read_b128 v[220:223], v143 offset:55296
	ds_read_b128 v[224:227], v143 offset:56320
	global_load_lds_dwordx4 v[164:165], off
	v_lshl_add_u64 v[164:165], v[246:247], 0, s[28:29]
	s_mov_b32 m0, s81
	s_nop 0
	global_load_lds_dwordx4 v[164:165], off
	s_barrier
	s_waitcnt lgkmcnt(0)
	s_waitcnt lgkmcnt(0)
	v_mfma_f32_16x16x32_bf16 v[62:65], v[144:147], v[160:163], v[62:65]
	v_mfma_f32_16x16x32_bf16 v[58:61], v[152:155], v[160:163], v[58:61]
	v_mfma_f32_16x16x32_bf16 v[54:57], v[144:147], v[192:195], v[54:57]
	v_mfma_f32_16x16x32_bf16 v[50:53], v[152:155], v[192:195], v[50:53]
	v_mfma_f32_16x16x32_bf16 v[38:41], v[144:147], v[200:203], v[38:41]
	v_mfma_f32_16x16x32_bf16 v[34:37], v[152:155], v[200:203], v[34:37]
	v_mfma_f32_16x16x32_bf16 v[22:25], v[144:147], v[220:223], v[22:25]
	v_mfma_f32_16x16x32_bf16 v[18:21], v[152:155], v[220:223], v[18:21]
	v_mfma_f32_16x16x32_bf16 v[62:65], v[148:151], v[188:191], v[62:65]
	v_mfma_f32_16x16x32_bf16 v[58:61], v[156:159], v[188:191], v[58:61]
	v_mfma_f32_16x16x32_bf16 v[54:57], v[148:151], v[196:199], v[54:57]
	v_mfma_f32_16x16x32_bf16 v[50:53], v[156:159], v[196:199], v[50:53]
	v_mfma_f32_16x16x32_bf16 v[38:41], v[148:151], v[216:219], v[38:41]
	v_mfma_f32_16x16x32_bf16 v[34:37], v[156:159], v[216:219], v[34:37]
	v_mfma_f32_16x16x32_bf16 v[22:25], v[148:151], v[224:227], v[22:25]
	v_mfma_f32_16x16x32_bf16 v[18:21], v[156:159], v[224:227], v[18:21]
	s_barrier
	s_add_u32 s26, s70, 0x80080
	s_addc_u32 s27, s71, 0
	s_add_i32 s2, s17, s3
	v_lshl_add_u64 v[144:145], s[26:27], 0, v[0:1]
	s_mov_b32 m0, s2
	s_nop 0
	global_load_lds_dwordx4 v[144:145], off
	v_lshl_add_u64 v[144:145], s[26:27], 0, v[130:131]
	s_add_i32 m0, s2, 0x2000
	s_nop 0
	global_load_lds_dwordx4 v[144:145], off
	s_waitcnt vmcnt(6)
	s_barrier
	v_mfma_f32_16x16x32_bf16 v[46:49], v[228:231], v[160:163], v[46:49]
	v_mfma_f32_16x16x32_bf16 v[42:45], v[236:239], v[160:163], v[42:45]
	v_mfma_f32_16x16x32_bf16 v[30:33], v[228:231], v[192:195], v[30:33]
	v_mfma_f32_16x16x32_bf16 v[26:29], v[236:239], v[192:195], v[26:29]
	v_mfma_f32_16x16x32_bf16 v[14:17], v[228:231], v[200:203], v[14:17]
	v_mfma_f32_16x16x32_bf16 v[10:13], v[236:239], v[200:203], v[10:13]
	v_mfma_f32_16x16x32_bf16 v[6:9], v[228:231], v[220:223], v[6:9]
	v_mfma_f32_16x16x32_bf16 v[2:5], v[236:239], v[220:223], v[2:5]
	v_mfma_f32_16x16x32_bf16 v[46:49], v[232:235], v[188:191], v[46:49]
	v_mfma_f32_16x16x32_bf16 v[42:45], v[240:243], v[188:191], v[42:45]
	v_mfma_f32_16x16x32_bf16 v[30:33], v[232:235], v[196:199], v[30:33]
	v_mfma_f32_16x16x32_bf16 v[26:29], v[240:243], v[196:199], v[26:29]
	v_mfma_f32_16x16x32_bf16 v[14:17], v[232:235], v[216:219], v[14:17]
	v_mfma_f32_16x16x32_bf16 v[10:13], v[240:243], v[216:219], v[10:13]
	v_mfma_f32_16x16x32_bf16 v[6:9], v[232:235], v[224:227], v[6:9]
	v_mfma_f32_16x16x32_bf16 v[2:5], v[240:243], v[224:227], v[2:5]
	s_add_i32 s44, s44, 2
	s_add_u32 s68, s68, 0x100
	s_addc_u32 s69, s69, 0
	s_add_u32 s83, s83, 0x100
	s_addc_u32 s92, s92, 0
	s_cmp_gt_u32 s44, 29
	s_barrier
	s_cbranch_scc0 .LBB0_1044
	v_lshl_add_u32 v144, s47, 8, v140
	v_lshl_or_b32 v146, s46, 8, v142
	v_ashrrev_i32_e32 v145, 31, v144
	v_cvt_pk_bf16_f32 v126, v126, v127
	v_cvt_pk_bf16_f32 v127, v128, v129
	v_cvt_pk_bf16_f32 v128, v122, v123
	v_lshlrev_b64 v[122:123], 12, v[144:145]
	v_ashrrev_i32_e32 v147, 31, v146
	v_cvt_pk_bf16_f32 v129, v124, v125
	v_lshl_add_u64 v[122:123], s[22:23], 0, v[122:123]
	v_lshlrev_b64 v[124:125], 1, v[146:147]
	v_lshl_add_u64 v[122:123], v[122:123], 0, v[124:125]
	v_cvt_pk_bf16_f32 v110, v110, v111
	v_cvt_pk_bf16_f32 v111, v112, v113
	v_cvt_pk_bf16_f32 v112, v106, v107
	v_cvt_pk_bf16_f32 v113, v108, v109
	global_store_dwordx4 v[122:123], v[110:113], off offset:256
	v_cvt_pk_bf16_f32 v94, v94, v95
	v_cvt_pk_bf16_f32 v95, v96, v97
	v_or_b32_e32 v110, 16, v144
	v_ashrrev_i32_e32 v111, 31, v110
	v_lshlrev_b64 v[110:111], 12, v[110:111]
	v_lshl_add_u64 v[110:111], s[22:23], 0, v[110:111]
	v_lshl_add_u64 v[110:111], v[110:111], 0, v[124:125]
	v_cvt_pk_bf16_f32 v96, v90, v91
	v_cvt_pk_bf16_f32 v97, v92, v93
	global_store_dwordx4 v[110:111], v[94:97], off offset:256
	s_mov_b32 s2, 0x80000
	v_cvt_pk_bf16_f32 v62, v62, v63
	v_or_b32_e32 v94, 32, v144
	v_ashrrev_i32_e32 v95, 31, v94
	v_cvt_pk_bf16_f32 v63, v64, v65
	v_cvt_pk_bf16_f32 v65, v60, v61
	s_mov_b64 s[4:5], 0x80000
	v_add_co_u32_e32 v60, vcc, s2, v122
	v_lshlrev_b64 v[94:95], 12, v[94:95]
	v_cvt_pk_bf16_f32 v64, v58, v59
	v_lshl_add_u64 v[58:59], v[122:123], 0, s[4:5]
	v_addc_co_u32_e32 v61, vcc, 0, v123, vcc
	v_cvt_pk_bf16_f32 v46, v46, v47
	v_cvt_pk_bf16_f32 v47, v48, v49
	v_cvt_pk_bf16_f32 v48, v42, v43
	v_cvt_pk_bf16_f32 v49, v44, v45
	s_mov_b32 s2, 0x90000
	v_lshl_add_u64 v[94:95], s[22:23], 0, v[94:95]
	global_store_dwordx4 v[58:59], v[46:49], off offset:256
	s_mov_b64 s[4:5], 0x90000
	v_lshl_add_u64 v[94:95], v[94:95], 0, v[124:125]
	v_add_co_u32_e32 v48, vcc, s2, v122
	v_cvt_pk_bf16_f32 v78, v78, v79
	v_cvt_pk_bf16_f32 v79, v80, v81
	v_cvt_pk_bf16_f32 v80, v74, v75
	v_cvt_pk_bf16_f32 v81, v76, v77
	v_lshl_add_u64 v[46:47], v[122:123], 0, s[4:5]
	v_addc_co_u32_e32 v49, vcc, 0, v123, vcc
	v_cvt_pk_bf16_f32 v30, v30, v31
	v_cvt_pk_bf16_f32 v31, v32, v33
	v_cvt_pk_bf16_f32 v32, v26, v27
	v_cvt_pk_bf16_f32 v33, v28, v29
	s_mov_b32 s2, 0xa0000
	global_store_dwordx4 v[94:95], v[78:81], off offset:256
	global_store_dwordx4 v[46:47], v[30:33], off offset:256
	s_mov_b64 s[4:5], 0xa0000
	v_or_b32_e32 v78, 48, v144
	v_add_co_u32_e32 v32, vcc, s2, v122
	v_ashrrev_i32_e32 v79, 31, v78
	v_lshl_add_u64 v[30:31], v[122:123], 0, s[4:5]
	v_addc_co_u32_e32 v33, vcc, 0, v123, vcc
	v_cvt_pk_bf16_f32 v14, v14, v15
	v_cvt_pk_bf16_f32 v15, v16, v17
	v_cvt_pk_bf16_f32 v16, v10, v11
	v_cvt_pk_bf16_f32 v17, v12, v13
	s_mov_b32 s2, 0xb0000
	v_lshlrev_b64 v[78:79], 12, v[78:79]
	global_store_dwordx4 v[30:31], v[14:17], off offset:256
	v_lshl_add_u64 v[78:79], s[22:23], 0, v[78:79]
	s_mov_b64 s[4:5], 0xb0000
	v_add_co_u32_e32 v16, vcc, s2, v122
	v_cvt_pk_bf16_f32 v106, v118, v119
	s_nop 0
	v_addc_co_u32_e32 v17, vcc, 0, v123, vcc
	v_cvt_pk_bf16_f32 v107, v120, v121
	v_cvt_pk_bf16_f32 v108, v114, v115
	v_cvt_pk_bf16_f32 v109, v116, v117
	v_cvt_pk_bf16_f32 v90, v102, v103
	v_cvt_pk_bf16_f32 v91, v104, v105
	v_cvt_pk_bf16_f32 v92, v98, v99
	v_cvt_pk_bf16_f32 v93, v100, v101
	v_cvt_pk_bf16_f32 v74, v86, v87
	v_cvt_pk_bf16_f32 v75, v88, v89
	v_cvt_pk_bf16_f32 v76, v82, v83
	v_cvt_pk_bf16_f32 v77, v84, v85
	v_lshl_add_u64 v[78:79], v[78:79], 0, v[124:125]
	v_cvt_pk_bf16_f32 v70, v70, v71
	v_cvt_pk_bf16_f32 v71, v72, v73
	v_cvt_pk_bf16_f32 v72, v66, v67
	v_cvt_pk_bf16_f32 v73, v68, v69
	v_cvt_pk_bf16_f32 v42, v54, v55
	v_cvt_pk_bf16_f32 v43, v56, v57
	v_cvt_pk_bf16_f32 v44, v50, v51
	v_cvt_pk_bf16_f32 v45, v52, v53
	v_cvt_pk_bf16_f32 v26, v38, v39
	v_cvt_pk_bf16_f32 v27, v40, v41
	v_cvt_pk_bf16_f32 v28, v34, v35
	v_cvt_pk_bf16_f32 v29, v36, v37
	v_cvt_pk_bf16_f32 v10, v22, v23
	v_cvt_pk_bf16_f32 v11, v24, v25
	v_cvt_pk_bf16_f32 v12, v18, v19
	v_cvt_pk_bf16_f32 v13, v20, v21
	v_lshl_add_u64 v[14:15], v[122:123], 0, s[4:5]
	v_cvt_pk_bf16_f32 v6, v6, v7
	v_cvt_pk_bf16_f32 v7, v8, v9
	v_cvt_pk_bf16_f32 v8, v2, v3
	v_cvt_pk_bf16_f32 v9, v4, v5
	s_and_b64 vcc, exec, s[0:1]
	s_mov_b32 s46, s42
	s_mov_b32 s47, s54
	s_mov_b64 s[70:71], s[64:65]
	s_mov_b64 s[68:69], s[62:63]
	global_store_dwordx4 v[122:123], v[126:129], off
	global_store_dwordx4 v[110:111], v[106:109], off
	global_store_dwordx4 v[94:95], v[90:93], off
	global_store_dwordx4 v[78:79], v[74:77], off
	global_store_dwordx4 v[78:79], v[70:73], off offset:256
	global_store_dwordx4 v[60:61], v[62:65], off
	global_store_dwordx4 v[48:49], v[42:45], off
	global_store_dwordx4 v[32:33], v[26:29], off
	global_store_dwordx4 v[16:17], v[10:13], off
	global_store_dwordx4 v[14:15], v[6:9], off offset:256
	s_cbranch_vccz .LBB0_1041
	v_readlane_b32 s0, v254, 12
	s_waitcnt vmcnt(0)
	v_readlane_b32 s1, v254, 13
	v_readlane_b32 s84, v251, 38
	s_andn2_b64 vcc, exec, s[0:1]
	v_readlane_b32 s85, v251, 39
	v_readlane_b32 s86, v251, 40
	v_readlane_b32 s87, v251, 41
	s_cbranch_vccnz .LBB0_1048
	s_barrier
